# GEMM K-loops: the genuinely redundant s_waitcnt lgkmcnt(0) right after each pre-MFMA barrier (a duplicate of the wait just before the barrier) removed, 32 sites
# speedup vs baseline: 1.0114x; 1.0114x over previous
; #define PG8_STAGE(bufoff, gbase, voff) do { _Pragma("unroll") for (int _i = 0; _i < 2; ++_i) \
;         __builtin_amdgcn_global_load_lds((const unsigned*)((const char*)(gbase) + (voff)[_i]), (PG8_LAS unsigned*)(lds + (bufoff) + ldsw + _i * 8192), 16, 0, 0); } while (0)
; #define PG8_LDA(dst, b, h) do { _Pragma("unroll") for (int m = 0; m < 4; ++m) _Pragma("unroll") for (int k = 0; k < 2; ++k) dst[m][k] = *(const PG8_LAS bf16x8*)(lds + PG8_SA(b, h) + aoff + m * 2048 + k * 1024); } while (0)
; #define PG8_LDB(dst, b, h) do { _Pragma("unroll") for (int n = 0; n < 2; ++n) _Pragma("unroll") for (int k = 0; k < 2; ++k) dst[n][k] = *(const PG8_LAS bf16x8*)(lds + PG8_SB(b, h) + boff + n * 2048 + k * 1024); } while (0)
; #define PG8_MMA(ai, bj, At, Bt) do { __builtin_amdgcn_s_setprio(1); _Pragma("unroll") for (int m = 0; m < 4; ++m) _Pragma("unroll") for (int n = 0; n < 2; ++n) _Pragma("unroll") for (int k = 0; k < 2; ++k) \
;         acc[ai][bj][m][n] = __builtin_amdgcn_mfma_f32_16x16x32_bf16(Bt[n][k], At[m][k], acc[ai][bj][m][n], 0, 0, 0); __builtin_amdgcn_s_setprio(0); } while (0)
; #define PG8_WAIT_V(n) asm volatile("s_waitcnt vmcnt(" #n ")" ::: "memory")
; #define PG8_WAIT_L(n) asm volatile("s_waitcnt lgkmcnt(" #n ")" ::: "memory")
; #define PG8_BAR __builtin_amdgcn_s_barrier()
; #define PG8_SCHED __builtin_amdgcn_sched_barrier(0)
; template <class Epi, class Sched, bool ALIGN_EPI = false, bool SP2 = false>
; __device__ __forceinline__ void gemm_phase(PG8_LAS unsigned char* lds, const Gemm g, const Sched& S, const Epi& E, const int tid) {
;     ...
;             PG8_LDB(B0, 0, 0); PG8_LDB(B1, 0, 1); PG8_SCHED; PG8_LDA(At, 0, 0); PG8_STAGE(PG8_SA(1, 1), a1 + hstep, voffA);
;             PG8_WAIT_V(8); PG8_WAIT_L(0); PG8_BAR; PG8_MMA(0, 0, At, B0); PG8_MMA(0, 1, At, B1); PG8_BAR; PG8_SCHED;
;             PG8_LDA(At, 0, 1); PG8_STAGE(PG8_SB(0, 0), b2, voffB); PG8_STAGE(PG8_SB(0, 1), b2 + hstep, voffB); PG8_STAGE(PG8_SA(0, 0), a2, voffA);
;             PG8_WAIT_V(8); PG8_WAIT_L(0); PG8_BAR; PG8_MMA(1, 0, At, B0); PG8_MMA(1, 1, At, B1); PG8_BAR; PG8_SCHED;
.LBB0_137:
	s_add_u32 s16, s10, s14
	s_addc_u32 s17, s11, s15
	s_add_u32 s16, s16, 0x100
	s_addc_u32 s17, s17, 0
	s_add_u32 s52, s49, s14
	s_addc_u32 s53, s50, s15
	s_add_i32 s54, 0, 0x10000
	s_cmpk_eq_i32 s14, 0x1500
	s_cselect_b32 s19, s13, s17
	s_cselect_b32 s18, s12, s16
	v_add_u32_e32 v147, s54, v145
	s_cselect_b32 s17, s5, s53
	s_cselect_b32 s16, s4, s52
	s_add_i32 s55, 0, 0x14000
	ds_read_b128 v[148:151], v147
	ds_read_b128 v[152:155], v147 offset:1024
	ds_read_b128 v[160:163], v147 offset:2048
	ds_read_b128 v[164:167], v147 offset:3072
	v_add_u32_e32 v147, s55, v145
	ds_read_b128 v[168:171], v147
	ds_read_b128 v[172:175], v147 offset:1024
	ds_read_b128 v[176:179], v147 offset:2048
	ds_read_b128 v[180:183], v147 offset:3072
	v_lshl_add_u64 v[156:157], v[142:143], 0, s[14:15]
	s_add_i32 m0, s29, 0xc000
	ds_read_b128 v[184:187], v146
	ds_read_b128 v[188:191], v146 offset:1024
	ds_read_b128 v[192:195], v146 offset:2048
	ds_read_b128 v[196:199], v146 offset:3072
	ds_read_b128 v[200:203], v146 offset:4096
	ds_read_b128 v[206:209], v146 offset:5120
	ds_read_b128 v[214:217], v146 offset:6144
	ds_read_b128 v[218:221], v146 offset:7168
	global_load_lds_dwordx4 v[156:157], off
	v_lshl_add_u64 v[156:157], v[140:141], 0, s[14:15]
	s_add_i32 m0, s29, 0xe000
	s_nop 0
	global_load_lds_dwordx4 v[156:157], off
	s_waitcnt vmcnt(8)
	s_waitcnt lgkmcnt(0)
	s_barrier
	s_setprio 1
	v_mfma_f32_16x16x32_bf16 v[32:35], v[148:151], v[184:187], v[32:35]
	v_mfma_f32_16x16x32_bf16 v[36:39], v[160:163], v[184:187], v[36:39]
	v_mfma_f32_16x16x32_bf16 v[48:51], v[148:151], v[192:195], v[48:51]
	v_mfma_f32_16x16x32_bf16 v[52:55], v[160:163], v[192:195], v[52:55]
	v_mfma_f32_16x16x32_bf16 v[56:59], v[148:151], v[200:203], v[56:59]
	v_mfma_f32_16x16x32_bf16 v[60:63], v[160:163], v[200:203], v[60:63]
	v_mfma_f32_16x16x32_bf16 v[74:77], v[148:151], v[214:217], v[74:77]
	v_mfma_f32_16x16x32_bf16 v[78:81], v[160:163], v[214:217], v[78:81]
	v_mfma_f32_16x16x32_bf16 v[32:35], v[152:155], v[188:191], v[32:35]
	v_mfma_f32_16x16x32_bf16 v[36:39], v[164:167], v[188:191], v[36:39]
	v_mfma_f32_16x16x32_bf16 v[48:51], v[152:155], v[196:199], v[48:51]
	v_mfma_f32_16x16x32_bf16 v[52:55], v[164:167], v[196:199], v[52:55]
	v_mfma_f32_16x16x32_bf16 v[56:59], v[152:155], v[206:209], v[56:59]
	v_mfma_f32_16x16x32_bf16 v[60:63], v[164:167], v[206:209], v[60:63]
	v_mfma_f32_16x16x32_bf16 v[74:77], v[152:155], v[218:221], v[74:77]
	v_mfma_f32_16x16x32_bf16 v[78:81], v[164:167], v[218:221], v[78:81]
	s_setprio 0
	s_setprio 1
	v_mfma_f32_16x16x32_bf16 v[106:109], v[168:171], v[184:187], v[106:109]
	v_mfma_f32_16x16x32_bf16 v[110:113], v[176:179], v[184:187], v[110:113]
	v_mfma_f32_16x16x32_bf16 v[102:105], v[168:171], v[192:195], v[102:105]
	v_mfma_f32_16x16x32_bf16 v[98:101], v[176:179], v[192:195], v[98:101]
	v_mfma_f32_16x16x32_bf16 v[70:73], v[168:171], v[200:203], v[70:73]
	v_mfma_f32_16x16x32_bf16 v[66:69], v[176:179], v[200:203], v[66:69]
	v_mfma_f32_16x16x32_bf16 v[44:47], v[168:171], v[214:217], v[44:47]
	v_mfma_f32_16x16x32_bf16 v[40:43], v[176:179], v[214:217], v[40:43]
	v_mfma_f32_16x16x32_bf16 v[106:109], v[172:175], v[188:191], v[106:109]
	v_mfma_f32_16x16x32_bf16 v[110:113], v[180:183], v[188:191], v[110:113]
	v_mfma_f32_16x16x32_bf16 v[102:105], v[172:175], v[196:199], v[102:105]
	v_mfma_f32_16x16x32_bf16 v[98:101], v[180:183], v[196:199], v[98:101]
	v_mfma_f32_16x16x32_bf16 v[70:73], v[172:175], v[206:209], v[70:73]
	v_mfma_f32_16x16x32_bf16 v[66:69], v[180:183], v[206:209], v[66:69]
	v_mfma_f32_16x16x32_bf16 v[44:47], v[172:175], v[218:221], v[44:47]
	v_mfma_f32_16x16x32_bf16 v[40:43], v[180:183], v[218:221], v[40:43]
	s_setprio 0
	s_barrier
	s_add_i32 s52, s54, s28
	v_lshl_add_u64 v[156:157], s[16:17], 0, v[64:65]
	s_mov_b32 m0, s52
	ds_read_b128 v[184:187], v146 offset:16384
	ds_read_b128 v[188:191], v146 offset:17408
	ds_read_b128 v[192:195], v146 offset:18432
	ds_read_b128 v[196:199], v146 offset:19456
	ds_read_b128 v[200:203], v146 offset:20480
	ds_read_b128 v[206:209], v146 offset:21504
	ds_read_b128 v[214:217], v146 offset:22528
	ds_read_b128 v[218:221], v146 offset:23552
	global_load_lds_dwordx4 v[156:157], off
	s_add_i32 m0, s52, 0x2000
	s_add_u32 s52, s16, 0xb0000
	v_lshl_add_u64 v[210:211], s[16:17], 0, v[130:131]
	s_addc_u32 s53, s17, 0
	s_add_i32 s54, s55, s28
	global_load_lds_dwordx4 v[210:211], off
	v_lshl_add_u64 v[222:223], s[52:53], 0, v[64:65]
	s_mov_b32 m0, s54
	v_lshl_add_u64 v[224:225], s[18:19], 0, v[132:133]
	global_load_lds_dwordx4 v[222:223], off
	v_lshl_add_u64 v[222:223], s[52:53], 0, v[130:131]
	s_add_i32 m0, s54, 0x2000
	s_nop 0
	global_load_lds_dwordx4 v[222:223], off
	v_lshl_add_u64 v[222:223], s[18:19], 0, v[134:135]
	s_mov_b32 m0, s29
	s_nop 0
	global_load_lds_dwordx4 v[222:223], off
	s_mov_b32 m0, s30
	s_nop 0
	global_load_lds_dwordx4 v[224:225], off
	s_waitcnt vmcnt(8)
	s_waitcnt lgkmcnt(0)
	s_barrier
; #define PG8_STAGE(bufoff, gbase, voff) do { _Pragma("unroll") for (int _i = 0; _i < 2; ++_i) \
;         __builtin_amdgcn_global_load_lds((const unsigned*)((const char*)(gbase) + (voff)[_i]), (PG8_LAS unsigned*)(lds + (bufoff) + ldsw + _i * 8192), 16, 0, 0); } while (0)
; #define PG8_LDA(dst, b, h) do { _Pragma("unroll") for (int m = 0; m < 4; ++m) _Pragma("unroll") for (int k = 0; k < 2; ++k) dst[m][k] = *(const PG8_LAS bf16x8*)(lds + PG8_SA(b, h) + aoff + m * 2048 + k * 1024); } while (0)
; #define PG8_LDB(dst, b, h) do { _Pragma("unroll") for (int n = 0; n < 2; ++n) _Pragma("unroll") for (int k = 0; k < 2; ++k) dst[n][k] = *(const PG8_LAS bf16x8*)(lds + PG8_SB(b, h) + boff + n * 2048 + k * 1024); } while (0)
; #define PG8_MMA(ai, bj, At, Bt) do { __builtin_amdgcn_s_setprio(1); _Pragma("unroll") for (int m = 0; m < 4; ++m) _Pragma("unroll") for (int n = 0; n < 2; ++n) _Pragma("unroll") for (int k = 0; k < 2; ++k) \
;         acc[ai][bj][m][n] = __builtin_amdgcn_mfma_f32_16x16x32_bf16(Bt[n][k], At[m][k], acc[ai][bj][m][n], 0, 0, 0); __builtin_amdgcn_s_setprio(0); } while (0)
; #define PG8_WAIT_V(n) asm volatile("s_waitcnt vmcnt(" #n ")" ::: "memory")
; #define PG8_WAIT_L(n) asm volatile("s_waitcnt lgkmcnt(" #n ")" ::: "memory")
; #define PG8_BAR __builtin_amdgcn_s_barrier()
; #define PG8_SCHED __builtin_amdgcn_sched_barrier(0)
; template <class Epi, class Sched, bool ALIGN_EPI = false, bool SP2 = false>
; __device__ __forceinline__ void gemm_phase(PG8_LAS unsigned char* lds, const Gemm g, const Sched& S, const Epi& E, const int tid) {
;     ...
;             PG8_WAIT_V(8); PG8_WAIT_L(0); PG8_BAR; PG8_MMA(1, 0, At, B0); PG8_MMA(1, 1, At, B1); PG8_BAR; PG8_SCHED;
;             PG8_LDB(B0, 1, 0); PG8_LDB(B1, 1, 1); PG8_SCHED; PG8_LDA(At, 1, 0); PG8_STAGE(PG8_SA(0, 1), a2 + hstep, voffA);
;             PG8_WAIT_V(8); PG8_WAIT_L(0); PG8_BAR; PG8_MMA(0, 0, At, B0); PG8_MMA(0, 1, At, B1); PG8_BAR; PG8_SCHED;
	s_setprio 1
	v_mfma_f32_16x16x32_bf16 v[82:85], v[148:151], v[184:187], v[82:85]
	v_mfma_f32_16x16x32_bf16 v[86:89], v[160:163], v[184:187], v[86:89]
	v_mfma_f32_16x16x32_bf16 v[90:93], v[148:151], v[192:195], v[90:93]
	v_mfma_f32_16x16x32_bf16 v[94:97], v[160:163], v[192:195], v[94:97]
	v_mfma_f32_16x16x32_bf16 v[114:117], v[148:151], v[200:203], v[114:117]
	v_mfma_f32_16x16x32_bf16 v[118:121], v[160:163], v[200:203], v[118:121]
	v_mfma_f32_16x16x32_bf16 v[122:125], v[148:151], v[214:217], v[122:125]
	v_mfma_f32_16x16x32_bf16 v[126:129], v[160:163], v[214:217], v[126:129]
	v_mfma_f32_16x16x32_bf16 v[82:85], v[152:155], v[188:191], v[82:85]
	v_mfma_f32_16x16x32_bf16 v[86:89], v[164:167], v[188:191], v[86:89]
	v_mfma_f32_16x16x32_bf16 v[90:93], v[152:155], v[196:199], v[90:93]
	v_mfma_f32_16x16x32_bf16 v[94:97], v[164:167], v[196:199], v[94:97]
	v_mfma_f32_16x16x32_bf16 v[114:117], v[152:155], v[206:209], v[114:117]
	v_mfma_f32_16x16x32_bf16 v[118:121], v[164:167], v[206:209], v[118:121]
	v_mfma_f32_16x16x32_bf16 v[122:125], v[152:155], v[218:221], v[122:125]
	v_mfma_f32_16x16x32_bf16 v[126:129], v[164:167], v[218:221], v[126:129]
	s_setprio 0
	s_setprio 1
	v_mfma_f32_16x16x32_bf16 v[28:31], v[168:171], v[184:187], v[28:31]
	v_mfma_f32_16x16x32_bf16 v[24:27], v[176:179], v[184:187], v[24:27]
	v_mfma_f32_16x16x32_bf16 v[20:23], v[168:171], v[192:195], v[20:23]
	v_mfma_f32_16x16x32_bf16 v[16:19], v[176:179], v[192:195], v[16:19]
	v_mfma_f32_16x16x32_bf16 v[12:15], v[168:171], v[200:203], v[12:15]
	v_mfma_f32_16x16x32_bf16 v[8:11], v[176:179], v[200:203], v[8:11]
	v_mfma_f32_16x16x32_bf16 v[4:7], v[168:171], v[214:217], v[4:7]
	v_mfma_f32_16x16x32_bf16 v[0:3], v[176:179], v[214:217], v[0:3]
	v_mfma_f32_16x16x32_bf16 v[28:31], v[172:175], v[188:191], v[28:31]
	v_mfma_f32_16x16x32_bf16 v[24:27], v[180:183], v[188:191], v[24:27]
	v_mfma_f32_16x16x32_bf16 v[20:23], v[172:175], v[196:199], v[20:23]
	v_mfma_f32_16x16x32_bf16 v[16:19], v[180:183], v[196:199], v[16:19]
	v_mfma_f32_16x16x32_bf16 v[12:15], v[172:175], v[206:209], v[12:15]
	v_mfma_f32_16x16x32_bf16 v[8:11], v[180:183], v[206:209], v[8:11]
	v_mfma_f32_16x16x32_bf16 v[4:7], v[172:175], v[218:221], v[4:7]
	v_mfma_f32_16x16x32_bf16 v[0:3], v[180:183], v[218:221], v[0:3]
	s_setprio 0
	s_barrier
	s_add_i32 s52, 0, 0x18000
	v_add_u32_e32 v147, s52, v145
	s_add_i32 s53, 0, 0x1c000
	ds_read_b128 v[148:151], v147
	ds_read_b128 v[152:155], v147 offset:1024
	ds_read_b128 v[160:163], v147 offset:2048
	ds_read_b128 v[164:167], v147 offset:3072
	v_add_u32_e32 v147, s53, v145
	ds_read_b128 v[168:171], v147
	ds_read_b128 v[172:175], v147 offset:1024
	ds_read_b128 v[176:179], v147 offset:2048
	ds_read_b128 v[180:183], v147 offset:3072
	s_add_u32 s18, s18, 0xb0000
	s_addc_u32 s19, s19, 0
	s_mov_b32 m0, s31
	v_lshl_add_u64 v[226:227], s[18:19], 0, v[134:135]
	ds_read_b128 v[184:187], v146 offset:32768
	ds_read_b128 v[188:191], v146 offset:33792
	ds_read_b128 v[192:195], v146 offset:34816
	ds_read_b128 v[196:199], v146 offset:35840
	ds_read_b128 v[200:203], v146 offset:36864
	ds_read_b128 v[206:209], v146 offset:37888
	ds_read_b128 v[214:217], v146 offset:38912
	ds_read_b128 v[218:221], v146 offset:39936
	global_load_lds_dwordx4 v[226:227], off
	v_lshl_add_u64 v[226:227], s[18:19], 0, v[132:133]
	s_mov_b32 m0, s34
	s_nop 0
	global_load_lds_dwordx4 v[226:227], off
	s_waitcnt vmcnt(8)
	s_waitcnt lgkmcnt(0)
	s_barrier
	s_setprio 1
	v_mfma_f32_16x16x32_bf16 v[32:35], v[148:151], v[184:187], v[32:35]
	v_mfma_f32_16x16x32_bf16 v[36:39], v[160:163], v[184:187], v[36:39]
	v_mfma_f32_16x16x32_bf16 v[48:51], v[148:151], v[192:195], v[48:51]
	v_mfma_f32_16x16x32_bf16 v[52:55], v[160:163], v[192:195], v[52:55]
	v_mfma_f32_16x16x32_bf16 v[56:59], v[148:151], v[200:203], v[56:59]
	v_mfma_f32_16x16x32_bf16 v[60:63], v[160:163], v[200:203], v[60:63]
	v_mfma_f32_16x16x32_bf16 v[74:77], v[148:151], v[214:217], v[74:77]
	v_mfma_f32_16x16x32_bf16 v[78:81], v[160:163], v[214:217], v[78:81]
	v_mfma_f32_16x16x32_bf16 v[32:35], v[152:155], v[188:191], v[32:35]
	v_mfma_f32_16x16x32_bf16 v[36:39], v[164:167], v[188:191], v[36:39]
	v_mfma_f32_16x16x32_bf16 v[48:51], v[152:155], v[196:199], v[48:51]
	v_mfma_f32_16x16x32_bf16 v[52:55], v[164:167], v[196:199], v[52:55]
	v_mfma_f32_16x16x32_bf16 v[56:59], v[152:155], v[206:209], v[56:59]
	v_mfma_f32_16x16x32_bf16 v[60:63], v[164:167], v[206:209], v[60:63]
	v_mfma_f32_16x16x32_bf16 v[74:77], v[152:155], v[218:221], v[74:77]
	v_mfma_f32_16x16x32_bf16 v[78:81], v[164:167], v[218:221], v[78:81]
	s_setprio 0
	s_setprio 1
	v_mfma_f32_16x16x32_bf16 v[106:109], v[168:171], v[184:187], v[106:109]
	v_mfma_f32_16x16x32_bf16 v[110:113], v[176:179], v[184:187], v[110:113]
	v_mfma_f32_16x16x32_bf16 v[102:105], v[168:171], v[192:195], v[102:105]
	v_mfma_f32_16x16x32_bf16 v[98:101], v[176:179], v[192:195], v[98:101]
	v_mfma_f32_16x16x32_bf16 v[70:73], v[168:171], v[200:203], v[70:73]
	v_mfma_f32_16x16x32_bf16 v[66:69], v[176:179], v[200:203], v[66:69]
	v_mfma_f32_16x16x32_bf16 v[44:47], v[168:171], v[214:217], v[44:47]
	v_mfma_f32_16x16x32_bf16 v[40:43], v[176:179], v[214:217], v[40:43]
	v_mfma_f32_16x16x32_bf16 v[106:109], v[172:175], v[188:191], v[106:109]
	v_mfma_f32_16x16x32_bf16 v[110:113], v[180:183], v[188:191], v[110:113]
	v_mfma_f32_16x16x32_bf16 v[102:105], v[172:175], v[196:199], v[102:105]
	v_mfma_f32_16x16x32_bf16 v[98:101], v[180:183], v[196:199], v[98:101]
	v_mfma_f32_16x16x32_bf16 v[70:73], v[172:175], v[206:209], v[70:73]
	v_mfma_f32_16x16x32_bf16 v[66:69], v[180:183], v[206:209], v[66:69]
	v_mfma_f32_16x16x32_bf16 v[44:47], v[172:175], v[218:221], v[44:47]
	v_mfma_f32_16x16x32_bf16 v[40:43], v[180:183], v[218:221], v[40:43]
	s_setprio 0
	s_barrier
; #define PG8_STAGE(bufoff, gbase, voff) do { _Pragma("unroll") for (int _i = 0; _i < 2; ++_i) \
;         __builtin_amdgcn_global_load_lds((const unsigned*)((const char*)(gbase) + (voff)[_i]), (PG8_LAS unsigned*)(lds + (bufoff) + ldsw + _i * 8192), 16, 0, 0); } while (0)
; #define PG8_LDA(dst, b, h) do { _Pragma("unroll") for (int m = 0; m < 4; ++m) _Pragma("unroll") for (int k = 0; k < 2; ++k) dst[m][k] = *(const PG8_LAS bf16x8*)(lds + PG8_SA(b, h) + aoff + m * 2048 + k * 1024); } while (0)
; #define PG8_MMA(ai, bj, At, Bt) do { __builtin_amdgcn_s_setprio(1); _Pragma("unroll") for (int m = 0; m < 4; ++m) _Pragma("unroll") for (int n = 0; n < 2; ++n) _Pragma("unroll") for (int k = 0; k < 2; ++k) \
;         acc[ai][bj][m][n] = __builtin_amdgcn_mfma_f32_16x16x32_bf16(Bt[n][k], At[m][k], acc[ai][bj][m][n], 0, 0, 0); __builtin_amdgcn_s_setprio(0); } while (0)
; #define PG8_WAIT_V(n) asm volatile("s_waitcnt vmcnt(" #n ")" ::: "memory")
; #define PG8_WAIT_L(n) asm volatile("s_waitcnt lgkmcnt(" #n ")" ::: "memory")
; #define PG8_BAR __builtin_amdgcn_s_barrier()
; #define PG8_SCHED __builtin_amdgcn_sched_barrier(0)
; template <class Epi, class Sched, bool ALIGN_EPI = false, bool SP2 = false>
; __device__ __forceinline__ void gemm_phase(PG8_LAS unsigned char* lds, const Gemm g, const Sched& S, const Epi& E, const int tid) {
;     ...
;             PG8_LDA(At, 1, 1); PG8_STAGE(PG8_SB(1, 0), b3, voffB); PG8_STAGE(PG8_SB(1, 1), b3 + hstep, voffB); PG8_STAGE(PG8_SA(1, 0), a3, voffA);
;             PG8_WAIT_V(8); PG8_WAIT_L(0); PG8_BAR; PG8_MMA(1, 0, At, B0); PG8_MMA(1, 1, At, B1); PG8_BAR; PG8_SCHED;
;     ...
; #pragma unroll
;         for (int a = 0; a < 2; ++a)
; #pragma unroll
;             for (int b = 0; b < 2; ++b)
; #pragma unroll
;                 for (int m = 0; m < 4; ++m)
; #pragma unroll
;                     for (int n = 0; n < 2; ++n) acc[a][b][m][n] = (f32x4){0.f, 0.f, 0.f, 0.f};
	s_add_i32 s18, s52, s28
	v_lshl_add_u64 v[156:157], v[156:157], 0, s[94:95]
	s_mov_b32 m0, s18
	ds_read_b128 v[184:187], v146 offset:49152
	ds_read_b128 v[188:191], v146 offset:50176
	ds_read_b128 v[192:195], v146 offset:51200
	ds_read_b128 v[196:199], v146 offset:52224
	ds_read_b128 v[200:203], v146 offset:53248
	ds_read_b128 v[206:209], v146 offset:54272
	ds_read_b128 v[214:217], v146 offset:55296
	ds_read_b128 v[218:221], v146 offset:56320
	global_load_lds_dwordx4 v[156:157], off
	s_add_i32 m0, s18, 0x2000
	s_add_u32 s16, s16, 0xb0080
	v_lshl_add_u64 v[156:157], v[210:211], 0, s[94:95]
	s_addc_u32 s17, s17, 0
	s_add_i32 s18, s53, s28
	global_load_lds_dwordx4 v[156:157], off
	v_lshl_add_u64 v[156:157], s[16:17], 0, v[64:65]
	s_mov_b32 m0, s18
	s_nop 0
	global_load_lds_dwordx4 v[156:157], off
	v_lshl_add_u64 v[156:157], s[16:17], 0, v[130:131]
	s_add_i32 m0, s18, 0x2000
	s_nop 0
	global_load_lds_dwordx4 v[156:157], off
	v_lshl_add_u64 v[156:157], v[222:223], 0, s[94:95]
	s_mov_b32 m0, s42
	s_nop 0
	global_load_lds_dwordx4 v[156:157], off
	v_lshl_add_u64 v[156:157], v[224:225], 0, s[94:95]
	s_mov_b32 m0, s44
	s_nop 0
	global_load_lds_dwordx4 v[156:157], off
	s_waitcnt vmcnt(8)
	s_waitcnt lgkmcnt(0)
	s_barrier
	s_setprio 1
	v_mfma_f32_16x16x32_bf16 v[82:85], v[148:151], v[184:187], v[82:85]
	v_mfma_f32_16x16x32_bf16 v[86:89], v[160:163], v[184:187], v[86:89]
	v_mfma_f32_16x16x32_bf16 v[90:93], v[148:151], v[192:195], v[90:93]
	v_mfma_f32_16x16x32_bf16 v[94:97], v[160:163], v[192:195], v[94:97]
	v_mfma_f32_16x16x32_bf16 v[114:117], v[148:151], v[200:203], v[114:117]
	v_mfma_f32_16x16x32_bf16 v[118:121], v[160:163], v[200:203], v[118:121]
	v_mfma_f32_16x16x32_bf16 v[122:125], v[148:151], v[214:217], v[122:125]
	v_mfma_f32_16x16x32_bf16 v[126:129], v[160:163], v[214:217], v[126:129]
	v_mfma_f32_16x16x32_bf16 v[82:85], v[152:155], v[188:191], v[82:85]
	v_mfma_f32_16x16x32_bf16 v[86:89], v[164:167], v[188:191], v[86:89]
	v_mfma_f32_16x16x32_bf16 v[90:93], v[152:155], v[196:199], v[90:93]
	v_mfma_f32_16x16x32_bf16 v[94:97], v[164:167], v[196:199], v[94:97]
	v_mfma_f32_16x16x32_bf16 v[114:117], v[152:155], v[206:209], v[114:117]
	v_mfma_f32_16x16x32_bf16 v[118:121], v[164:167], v[206:209], v[118:121]
	v_mfma_f32_16x16x32_bf16 v[122:125], v[152:155], v[218:221], v[122:125]
	v_mfma_f32_16x16x32_bf16 v[126:129], v[164:167], v[218:221], v[126:129]
	s_setprio 0
	s_setprio 1
	v_mfma_f32_16x16x32_bf16 v[28:31], v[168:171], v[184:187], v[28:31]
	v_mfma_f32_16x16x32_bf16 v[24:27], v[176:179], v[184:187], v[24:27]
	v_mfma_f32_16x16x32_bf16 v[20:23], v[168:171], v[192:195], v[20:23]
	v_mfma_f32_16x16x32_bf16 v[16:19], v[176:179], v[192:195], v[16:19]
	v_mfma_f32_16x16x32_bf16 v[12:15], v[168:171], v[200:203], v[12:15]
	v_mfma_f32_16x16x32_bf16 v[8:11], v[176:179], v[200:203], v[8:11]
	v_mfma_f32_16x16x32_bf16 v[4:7], v[168:171], v[214:217], v[4:7]
	v_mfma_f32_16x16x32_bf16 v[0:3], v[176:179], v[214:217], v[0:3]
	v_mfma_f32_16x16x32_bf16 v[28:31], v[172:175], v[188:191], v[28:31]
	v_mfma_f32_16x16x32_bf16 v[24:27], v[180:183], v[188:191], v[24:27]
	v_mfma_f32_16x16x32_bf16 v[20:23], v[172:175], v[196:199], v[20:23]
	v_mfma_f32_16x16x32_bf16 v[16:19], v[180:183], v[196:199], v[16:19]
	v_mfma_f32_16x16x32_bf16 v[12:15], v[172:175], v[206:209], v[12:15]
	v_mfma_f32_16x16x32_bf16 v[8:11], v[180:183], v[206:209], v[8:11]
	v_mfma_f32_16x16x32_bf16 v[4:7], v[172:175], v[218:221], v[4:7]
	v_mfma_f32_16x16x32_bf16 v[0:3], v[180:183], v[218:221], v[0:3]
	s_setprio 0
	s_barrier
	s_add_i32 s51, s51, 2
	s_add_u32 s14, s14, 0x100
	s_addc_u32 s15, s15, 0
	s_cmp_gt_u32 s51, 41
	s_cbranch_scc0 .LBB0_137
	s_add_u32 s14, s49, 0xffffff00
	s_addc_u32 s15, s50, -1
	s_and_b64 vcc, exec, s[2:3]
	s_cbranch_vccnz .LBB0_140
	v_mov_b32_e32 v0, 0
	s_mov_b32 s8, s46
	s_mov_b32 s22, s47
	s_mov_b64 s[10:11], s[12:13]
	s_mov_b32 s45, s48
	v_mov_b32_e32 v1, v0
	v_mov_b32_e32 v2, v0
	v_mov_b32_e32 v3, v0
	v_mov_b32_e32 v4, v0
	v_mov_b32_e32 v5, v0
	v_mov_b32_e32 v6, v0
	v_mov_b32_e32 v7, v0
	v_mov_b32_e32 v8, v0
	v_mov_b32_e32 v9, v0
	v_mov_b32_e32 v10, v0
	v_mov_b32_e32 v11, v0
	v_mov_b32_e32 v12, v0
	v_mov_b32_e32 v13, v0
	v_mov_b32_e32 v14, v0
	v_mov_b32_e32 v15, v0
	v_mov_b32_e32 v16, v0
	v_mov_b32_e32 v17, v0
	v_mov_b32_e32 v18, v0
	v_mov_b32_e32 v19, v0
	v_mov_b32_e32 v20, v0
	v_mov_b32_e32 v21, v0
	v_mov_b32_e32 v22, v0
	v_mov_b32_e32 v23, v0
	v_mov_b32_e32 v24, v0
	v_mov_b32_e32 v25, v0
	v_mov_b32_e32 v26, v0
	v_mov_b32_e32 v27, v0
	v_mov_b32_e32 v28, v0
	v_mov_b32_e32 v29, v0
	v_mov_b32_e32 v30, v0
	v_mov_b32_e32 v31, v0
	v_mov_b32_e32 v126, v0
	v_mov_b32_e32 v127, v0
	v_mov_b32_e32 v128, v0
	v_mov_b32_e32 v129, v0
	v_mov_b32_e32 v122, v0
	v_mov_b32_e32 v123, v0
	v_mov_b32_e32 v124, v0
	v_mov_b32_e32 v125, v0
	v_mov_b32_e32 v118, v0
	v_mov_b32_e32 v119, v0
	v_mov_b32_e32 v120, v0
	v_mov_b32_e32 v121, v0
	v_mov_b32_e32 v114, v0
	v_mov_b32_e32 v115, v0
	v_mov_b32_e32 v116, v0
	v_mov_b32_e32 v117, v0
	v_mov_b32_e32 v94, v0
	v_mov_b32_e32 v95, v0
	v_mov_b32_e32 v96, v0
	v_mov_b32_e32 v97, v0
	v_mov_b32_e32 v90, v0
	v_mov_b32_e32 v91, v0
	v_mov_b32_e32 v92, v0
	v_mov_b32_e32 v93, v0
	v_mov_b32_e32 v86, v0
	v_mov_b32_e32 v87, v0
	v_mov_b32_e32 v88, v0
	v_mov_b32_e32 v89, v0
	v_mov_b32_e32 v82, v0
	v_mov_b32_e32 v83, v0
	v_mov_b32_e32 v84, v0
	v_mov_b32_e32 v85, v0
	v_mov_b32_e32 v40, v0
	v_mov_b32_e32 v41, v0
	v_mov_b32_e32 v42, v0
	v_mov_b32_e32 v43, v0
	v_mov_b32_e32 v44, v0
	v_mov_b32_e32 v45, v0
	v_mov_b32_e32 v46, v0
	v_mov_b32_e32 v47, v0
	v_mov_b32_e32 v66, v0
	v_mov_b32_e32 v67, v0
	v_mov_b32_e32 v68, v0
	v_mov_b32_e32 v69, v0
	v_mov_b32_e32 v70, v0
	v_mov_b32_e32 v71, v0
	v_mov_b32_e32 v72, v0
	v_mov_b32_e32 v73, v0
	v_mov_b32_e32 v98, v0
	v_mov_b32_e32 v99, v0
	v_mov_b32_e32 v100, v0
	v_mov_b32_e32 v101, v0
	v_mov_b32_e32 v102, v0
	v_mov_b32_e32 v103, v0
	v_mov_b32_e32 v104, v0
	v_mov_b32_e32 v105, v0
	v_mov_b32_e32 v110, v0
	v_mov_b32_e32 v111, v0
	v_mov_b32_e32 v112, v0
	v_mov_b32_e32 v113, v0
	v_mov_b32_e32 v106, v0
	v_mov_b32_e32 v107, v0
	v_mov_b32_e32 v108, v0
	v_mov_b32_e32 v109, v0
	v_mov_b32_e32 v78, v0
	v_mov_b32_e32 v79, v0
	v_mov_b32_e32 v80, v0
	v_mov_b32_e32 v81, v0
	v_mov_b32_e32 v74, v0
	v_mov_b32_e32 v75, v0
	v_mov_b32_e32 v76, v0
	v_mov_b32_e32 v77, v0
	v_mov_b32_e32 v60, v0
	v_mov_b32_e32 v61, v0
	v_mov_b32_e32 v62, v0
	v_mov_b32_e32 v63, v0
	v_mov_b32_e32 v56, v0
	v_mov_b32_e32 v57, v0
	v_mov_b32_e32 v58, v0
	v_mov_b32_e32 v59, v0
	v_mov_b32_e32 v52, v0
	v_mov_b32_e32 v53, v0
	v_mov_b32_e32 v54, v0
	v_mov_b32_e32 v55, v0
	v_mov_b32_e32 v48, v0
	v_mov_b32_e32 v49, v0
	v_mov_b32_e32 v50, v0
	v_mov_b32_e32 v51, v0
	v_mov_b32_e32 v36, v0
	v_mov_b32_e32 v37, v0
	v_mov_b32_e32 v38, v0
	v_mov_b32_e32 v39, v0
	v_mov_b32_e32 v32, v0
	v_mov_b32_e32 v33, v0
	v_mov_b32_e32 v34, v0
	v_mov_b32_e32 v35, v0
	s_andn2_b64 vcc, exec, s[0:1]
	s_cbranch_vccnz .LBB0_141
	s_branch .LBB0_142

; #define PG8_STAGE(bufoff, gbase, voff) do { _Pragma("unroll") for (int _i = 0; _i < 2; ++_i) \
;         __builtin_amdgcn_global_load_lds((const unsigned*)((const char*)(gbase) + (voff)[_i]), (PG8_LAS unsigned*)(lds + (bufoff) + ldsw + _i * 8192), 16, 0, 0); } while (0)
; #define PG8_LDA(dst, b, h) do { _Pragma("unroll") for (int m = 0; m < 4; ++m) _Pragma("unroll") for (int k = 0; k < 2; ++k) dst[m][k] = *(const PG8_LAS bf16x8*)(lds + PG8_SA(b, h) + aoff + m * 2048 + k * 1024); } while (0)
; #define PG8_LDB(dst, b, h) do { _Pragma("unroll") for (int n = 0; n < 2; ++n) _Pragma("unroll") for (int k = 0; k < 2; ++k) dst[n][k] = *(const PG8_LAS bf16x8*)(lds + PG8_SB(b, h) + boff + n * 2048 + k * 1024); } while (0)
; #define PG8_MMA(ai, bj, At, Bt) do { __builtin_amdgcn_s_setprio(1); _Pragma("unroll") for (int m = 0; m < 4; ++m) _Pragma("unroll") for (int n = 0; n < 2; ++n) _Pragma("unroll") for (int k = 0; k < 2; ++k) \
;         acc[ai][bj][m][n] = __builtin_amdgcn_mfma_f32_16x16x32_bf16(Bt[n][k], At[m][k], acc[ai][bj][m][n], 0, 0, 0); __builtin_amdgcn_s_setprio(0); } while (0)
; #define PG8_WAIT_V(n) asm volatile("s_waitcnt vmcnt(" #n ")" ::: "memory")
; #define PG8_WAIT_L(n) asm volatile("s_waitcnt lgkmcnt(" #n ")" ::: "memory")
; #define PG8_BAR __builtin_amdgcn_s_barrier()
; #define PG8_SCHED __builtin_amdgcn_sched_barrier(0)
; template <class Epi, class Sched, bool ALIGN_EPI = false, bool SP2 = false>
; __device__ __forceinline__ void gemm_phase(PG8_LAS unsigned char* lds, const Gemm g, const Sched& S, const Epi& E, const int tid) {
;     ...
;             PG8_LDB(B0, 0, 0); PG8_LDB(B1, 0, 1); PG8_SCHED; PG8_LDA(At, 0, 0); PG8_STAGE(PG8_SA(1, 1), a1 + hstep, voffA);
;             PG8_WAIT_V(8); PG8_WAIT_L(0); PG8_BAR; PG8_MMA(0, 0, At, B0); PG8_MMA(0, 1, At, B1); PG8_BAR; PG8_SCHED;
;             PG8_LDA(At, 0, 1); PG8_STAGE(PG8_SB(0, 0), b2, voffB); PG8_STAGE(PG8_SB(0, 1), b2 + hstep, voffB); PG8_STAGE(PG8_SA(0, 0), a2, voffA);
.LBB0_254:
	s_add_u32 s18, s16, 0xfffc0080
	s_addc_u32 s19, s17, -1
	s_add_i32 s48, 0, 0x10000
	s_cmp_eq_u32 s47, 12
	s_cselect_b32 s21, s11, s19
	s_cselect_b32 s20, s42, s18
	v_add_u32_e32 v64, s48, v143
	s_cselect_b32 s19, s9, s46
	s_cselect_b32 s18, s44, s45
	s_add_i32 s50, 0, 0x14000
	ds_read_b128 v[146:149], v64
	ds_read_b128 v[150:153], v64 offset:1024
	ds_read_b128 v[154:157], v64 offset:2048
	ds_read_b128 v[158:161], v64 offset:3072
	v_add_u32_e32 v64, s50, v143
	ds_read_b128 v[162:165], v64
	ds_read_b128 v[166:169], v64 offset:1024
	ds_read_b128 v[170:173], v64 offset:2048
	ds_read_b128 v[174:177], v64 offset:3072
	v_lshl_add_u64 v[202:203], s[16:17], 0, v[140:141]
	s_add_i32 m0, s25, 0xc000
	ds_read_b128 v[178:181], v145
	ds_read_b128 v[182:185], v145 offset:1024
	ds_read_b128 v[186:189], v145 offset:2048
	ds_read_b128 v[190:193], v145 offset:3072
	ds_read_b128 v[194:197], v145 offset:4096
	ds_read_b128 v[198:201], v145 offset:5120
	ds_read_b128 v[206:209], v145 offset:6144
	ds_read_b128 v[214:217], v145 offset:7168
	global_load_lds_dwordx4 v[202:203], off
	v_lshl_add_u64 v[202:203], s[16:17], 0, v[138:139]
	s_add_i32 m0, s25, 0xe000
	s_nop 0
	global_load_lds_dwordx4 v[202:203], off
	s_waitcnt vmcnt(8)
	s_waitcnt lgkmcnt(0)
	s_barrier
	s_setprio 1
	v_mfma_f32_16x16x32_bf16 v[126:129], v[146:149], v[178:181], v[126:129]
	v_mfma_f32_16x16x32_bf16 v[122:125], v[154:157], v[178:181], v[122:125]
	v_mfma_f32_16x16x32_bf16 v[110:113], v[146:149], v[186:189], v[110:113]
	v_mfma_f32_16x16x32_bf16 v[106:109], v[154:157], v[186:189], v[106:109]
	v_mfma_f32_16x16x32_bf16 v[94:97], v[146:149], v[194:197], v[94:97]
	v_mfma_f32_16x16x32_bf16 v[90:93], v[154:157], v[194:197], v[90:93]
	v_mfma_f32_16x16x32_bf16 v[78:81], v[146:149], v[206:209], v[78:81]
	v_mfma_f32_16x16x32_bf16 v[74:77], v[154:157], v[206:209], v[74:77]
	v_mfma_f32_16x16x32_bf16 v[126:129], v[150:153], v[182:185], v[126:129]
	v_mfma_f32_16x16x32_bf16 v[122:125], v[158:161], v[182:185], v[122:125]
	v_mfma_f32_16x16x32_bf16 v[110:113], v[150:153], v[190:193], v[110:113]
	v_mfma_f32_16x16x32_bf16 v[106:109], v[158:161], v[190:193], v[106:109]
	v_mfma_f32_16x16x32_bf16 v[94:97], v[150:153], v[198:201], v[94:97]
	v_mfma_f32_16x16x32_bf16 v[90:93], v[158:161], v[198:201], v[90:93]
	v_mfma_f32_16x16x32_bf16 v[78:81], v[150:153], v[214:217], v[78:81]
	v_mfma_f32_16x16x32_bf16 v[74:77], v[158:161], v[214:217], v[74:77]
	s_setprio 0
	s_setprio 1
	v_mfma_f32_16x16x32_bf16 v[118:121], v[162:165], v[178:181], v[118:121]
	v_mfma_f32_16x16x32_bf16 v[114:117], v[170:173], v[178:181], v[114:117]
	v_mfma_f32_16x16x32_bf16 v[102:105], v[162:165], v[186:189], v[102:105]
	v_mfma_f32_16x16x32_bf16 v[98:101], v[170:173], v[186:189], v[98:101]
	v_mfma_f32_16x16x32_bf16 v[86:89], v[162:165], v[194:197], v[86:89]
	v_mfma_f32_16x16x32_bf16 v[82:85], v[170:173], v[194:197], v[82:85]
	v_mfma_f32_16x16x32_bf16 v[70:73], v[162:165], v[206:209], v[70:73]
	v_mfma_f32_16x16x32_bf16 v[66:69], v[170:173], v[206:209], v[66:69]
	v_mfma_f32_16x16x32_bf16 v[118:121], v[166:169], v[182:185], v[118:121]
	v_mfma_f32_16x16x32_bf16 v[114:117], v[174:177], v[182:185], v[114:117]
	v_mfma_f32_16x16x32_bf16 v[102:105], v[166:169], v[190:193], v[102:105]
	v_mfma_f32_16x16x32_bf16 v[98:101], v[174:177], v[190:193], v[98:101]
	v_mfma_f32_16x16x32_bf16 v[86:89], v[166:169], v[198:201], v[86:89]
	v_mfma_f32_16x16x32_bf16 v[82:85], v[174:177], v[198:201], v[82:85]
	v_mfma_f32_16x16x32_bf16 v[70:73], v[166:169], v[214:217], v[70:73]
	v_mfma_f32_16x16x32_bf16 v[66:69], v[174:177], v[214:217], v[66:69]
	s_setprio 0
	s_barrier
	s_add_i32 s48, s48, s24
	v_lshl_add_u64 v[202:203], s[18:19], 0, v[134:135]
	s_mov_b32 m0, s48
	ds_read_b128 v[178:181], v145 offset:16384
	ds_read_b128 v[182:185], v145 offset:17408
	ds_read_b128 v[186:189], v145 offset:18432
	ds_read_b128 v[190:193], v145 offset:19456
	ds_read_b128 v[194:197], v145 offset:20480
	ds_read_b128 v[198:201], v145 offset:21504
	ds_read_b128 v[206:209], v145 offset:22528
	ds_read_b128 v[214:217], v145 offset:23552
	global_load_lds_dwordx4 v[202:203], off
	s_add_i32 m0, s48, 0x2000
	s_add_u32 s48, s18, 0x40000
	v_lshl_add_u64 v[210:211], s[18:19], 0, v[130:131]
	s_addc_u32 s49, s19, 0
	s_add_i32 s50, s50, s24
	global_load_lds_dwordx4 v[210:211], off
	v_lshl_add_u64 v[218:219], s[48:49], 0, v[134:135]
	s_mov_b32 m0, s50
	v_lshl_add_u64 v[220:221], s[20:21], 0, v[132:133]
	global_load_lds_dwordx4 v[218:219], off
	v_lshl_add_u64 v[218:219], s[48:49], 0, v[130:131]
	s_add_i32 m0, s50, 0x2000
	s_nop 0
	global_load_lds_dwordx4 v[218:219], off
	v_lshl_add_u64 v[218:219], s[20:21], 0, v[136:137]
	s_mov_b32 m0, s25
	s_nop 0
	global_load_lds_dwordx4 v[218:219], off
	s_mov_b32 m0, s26
	s_nop 0
	global_load_lds_dwordx4 v[220:221], off
	s_waitcnt vmcnt(8)
	s_waitcnt lgkmcnt(0)
	s_barrier
; #define PG8_STAGE(bufoff, gbase, voff) do { _Pragma("unroll") for (int _i = 0; _i < 2; ++_i) \
;         __builtin_amdgcn_global_load_lds((const unsigned*)((const char*)(gbase) + (voff)[_i]), (PG8_LAS unsigned*)(lds + (bufoff) + ldsw + _i * 8192), 16, 0, 0); } while (0)
; #define PG8_LDA(dst, b, h) do { _Pragma("unroll") for (int m = 0; m < 4; ++m) _Pragma("unroll") for (int k = 0; k < 2; ++k) dst[m][k] = *(const PG8_LAS bf16x8*)(lds + PG8_SA(b, h) + aoff + m * 2048 + k * 1024); } while (0)
; #define PG8_LDB(dst, b, h) do { _Pragma("unroll") for (int n = 0; n < 2; ++n) _Pragma("unroll") for (int k = 0; k < 2; ++k) dst[n][k] = *(const PG8_LAS bf16x8*)(lds + PG8_SB(b, h) + boff + n * 2048 + k * 1024); } while (0)
; #define PG8_MMA(ai, bj, At, Bt) do { __builtin_amdgcn_s_setprio(1); _Pragma("unroll") for (int m = 0; m < 4; ++m) _Pragma("unroll") for (int n = 0; n < 2; ++n) _Pragma("unroll") for (int k = 0; k < 2; ++k) \
;         acc[ai][bj][m][n] = __builtin_amdgcn_mfma_f32_16x16x32_bf16(Bt[n][k], At[m][k], acc[ai][bj][m][n], 0, 0, 0); __builtin_amdgcn_s_setprio(0); } while (0)
; #define PG8_WAIT_V(n) asm volatile("s_waitcnt vmcnt(" #n ")" ::: "memory")
; #define PG8_WAIT_L(n) asm volatile("s_waitcnt lgkmcnt(" #n ")" ::: "memory")
; #define PG8_BAR __builtin_amdgcn_s_barrier()
; #define PG8_SCHED __builtin_amdgcn_sched_barrier(0)
; template <class Epi, class Sched, bool ALIGN_EPI = false, bool SP2 = false>
; __device__ __forceinline__ void gemm_phase(PG8_LAS unsigned char* lds, const Gemm g, const Sched& S, const Epi& E, const int tid) {
;     ...
;             PG8_WAIT_V(8); PG8_WAIT_L(0); PG8_BAR; PG8_MMA(1, 0, At, B0); PG8_MMA(1, 1, At, B1); PG8_BAR; PG8_SCHED;
;             PG8_LDB(B0, 1, 0); PG8_LDB(B1, 1, 1); PG8_SCHED; PG8_LDA(At, 1, 0); PG8_STAGE(PG8_SA(0, 1), a2 + hstep, voffA);
;             PG8_WAIT_V(8); PG8_WAIT_L(0); PG8_BAR; PG8_MMA(0, 0, At, B0); PG8_MMA(0, 1, At, B1); PG8_BAR; PG8_SCHED;
	s_setprio 1
	v_mfma_f32_16x16x32_bf16 v[60:63], v[146:149], v[178:181], v[60:63]
	v_mfma_f32_16x16x32_bf16 v[56:59], v[154:157], v[178:181], v[56:59]
	v_mfma_f32_16x16x32_bf16 v[44:47], v[146:149], v[186:189], v[44:47]
	v_mfma_f32_16x16x32_bf16 v[40:43], v[154:157], v[186:189], v[40:43]
	v_mfma_f32_16x16x32_bf16 v[28:31], v[146:149], v[194:197], v[28:31]
	v_mfma_f32_16x16x32_bf16 v[24:27], v[154:157], v[194:197], v[24:27]
	v_mfma_f32_16x16x32_bf16 v[12:15], v[146:149], v[206:209], v[12:15]
	v_mfma_f32_16x16x32_bf16 v[8:11], v[154:157], v[206:209], v[8:11]
	v_mfma_f32_16x16x32_bf16 v[60:63], v[150:153], v[182:185], v[60:63]
	v_mfma_f32_16x16x32_bf16 v[56:59], v[158:161], v[182:185], v[56:59]
	v_mfma_f32_16x16x32_bf16 v[44:47], v[150:153], v[190:193], v[44:47]
	v_mfma_f32_16x16x32_bf16 v[40:43], v[158:161], v[190:193], v[40:43]
	v_mfma_f32_16x16x32_bf16 v[28:31], v[150:153], v[198:201], v[28:31]
	v_mfma_f32_16x16x32_bf16 v[24:27], v[158:161], v[198:201], v[24:27]
	v_mfma_f32_16x16x32_bf16 v[12:15], v[150:153], v[214:217], v[12:15]
	v_mfma_f32_16x16x32_bf16 v[8:11], v[158:161], v[214:217], v[8:11]
	s_setprio 0
	s_setprio 1
	v_mfma_f32_16x16x32_bf16 v[52:55], v[162:165], v[178:181], v[52:55]
	v_mfma_f32_16x16x32_bf16 v[48:51], v[170:173], v[178:181], v[48:51]
	v_mfma_f32_16x16x32_bf16 v[36:39], v[162:165], v[186:189], v[36:39]
	v_mfma_f32_16x16x32_bf16 v[32:35], v[170:173], v[186:189], v[32:35]
	v_mfma_f32_16x16x32_bf16 v[20:23], v[162:165], v[194:197], v[20:23]
	v_mfma_f32_16x16x32_bf16 v[16:19], v[170:173], v[194:197], v[16:19]
	v_mfma_f32_16x16x32_bf16 v[4:7], v[162:165], v[206:209], v[4:7]
	v_mfma_f32_16x16x32_bf16 v[0:3], v[170:173], v[206:209], v[0:3]
	v_mfma_f32_16x16x32_bf16 v[52:55], v[166:169], v[182:185], v[52:55]
	v_mfma_f32_16x16x32_bf16 v[48:51], v[174:177], v[182:185], v[48:51]
	v_mfma_f32_16x16x32_bf16 v[36:39], v[166:169], v[190:193], v[36:39]
	v_mfma_f32_16x16x32_bf16 v[32:35], v[174:177], v[190:193], v[32:35]
	v_mfma_f32_16x16x32_bf16 v[20:23], v[166:169], v[198:201], v[20:23]
	v_mfma_f32_16x16x32_bf16 v[16:19], v[174:177], v[198:201], v[16:19]
	v_mfma_f32_16x16x32_bf16 v[4:7], v[166:169], v[214:217], v[4:7]
	v_mfma_f32_16x16x32_bf16 v[0:3], v[174:177], v[214:217], v[0:3]
	s_setprio 0
	s_barrier
	s_add_i32 s48, 0, 0x18000
	v_add_u32_e32 v64, s48, v143
	s_add_i32 s49, 0, 0x1c000
	ds_read_b128 v[146:149], v64
	ds_read_b128 v[150:153], v64 offset:1024
	ds_read_b128 v[154:157], v64 offset:2048
	ds_read_b128 v[158:161], v64 offset:3072
	v_add_u32_e32 v64, s49, v143
	ds_read_b128 v[162:165], v64
	ds_read_b128 v[166:169], v64 offset:1024
	ds_read_b128 v[170:173], v64 offset:2048
	ds_read_b128 v[174:177], v64 offset:3072
	s_add_u32 s20, s20, 0x40000
	s_addc_u32 s21, s21, 0
	s_mov_b32 m0, s27
	v_lshl_add_u64 v[222:223], s[20:21], 0, v[136:137]
	ds_read_b128 v[178:181], v145 offset:32768
	ds_read_b128 v[182:185], v145 offset:33792
	ds_read_b128 v[186:189], v145 offset:34816
	ds_read_b128 v[190:193], v145 offset:35840
	ds_read_b128 v[194:197], v145 offset:36864
	ds_read_b128 v[198:201], v145 offset:37888
	ds_read_b128 v[206:209], v145 offset:38912
	ds_read_b128 v[214:217], v145 offset:39936
	global_load_lds_dwordx4 v[222:223], off
	v_lshl_add_u64 v[222:223], s[20:21], 0, v[132:133]
	s_mov_b32 m0, s28
	s_nop 0
	global_load_lds_dwordx4 v[222:223], off
	s_waitcnt vmcnt(8)
	s_waitcnt lgkmcnt(0)
	s_barrier
	s_setprio 1
	v_mfma_f32_16x16x32_bf16 v[126:129], v[146:149], v[178:181], v[126:129]
	v_mfma_f32_16x16x32_bf16 v[122:125], v[154:157], v[178:181], v[122:125]
	v_mfma_f32_16x16x32_bf16 v[110:113], v[146:149], v[186:189], v[110:113]
	v_mfma_f32_16x16x32_bf16 v[106:109], v[154:157], v[186:189], v[106:109]
	v_mfma_f32_16x16x32_bf16 v[94:97], v[146:149], v[194:197], v[94:97]
	v_mfma_f32_16x16x32_bf16 v[90:93], v[154:157], v[194:197], v[90:93]
	v_mfma_f32_16x16x32_bf16 v[78:81], v[146:149], v[206:209], v[78:81]
	v_mfma_f32_16x16x32_bf16 v[74:77], v[154:157], v[206:209], v[74:77]
	v_mfma_f32_16x16x32_bf16 v[126:129], v[150:153], v[182:185], v[126:129]
	v_mfma_f32_16x16x32_bf16 v[122:125], v[158:161], v[182:185], v[122:125]
	v_mfma_f32_16x16x32_bf16 v[110:113], v[150:153], v[190:193], v[110:113]
	v_mfma_f32_16x16x32_bf16 v[106:109], v[158:161], v[190:193], v[106:109]
	v_mfma_f32_16x16x32_bf16 v[94:97], v[150:153], v[198:201], v[94:97]
	v_mfma_f32_16x16x32_bf16 v[90:93], v[158:161], v[198:201], v[90:93]
	v_mfma_f32_16x16x32_bf16 v[78:81], v[150:153], v[214:217], v[78:81]
	v_mfma_f32_16x16x32_bf16 v[74:77], v[158:161], v[214:217], v[74:77]
	s_setprio 0
	s_setprio 1
	v_mfma_f32_16x16x32_bf16 v[118:121], v[162:165], v[178:181], v[118:121]
	v_mfma_f32_16x16x32_bf16 v[114:117], v[170:173], v[178:181], v[114:117]
	v_mfma_f32_16x16x32_bf16 v[102:105], v[162:165], v[186:189], v[102:105]
	v_mfma_f32_16x16x32_bf16 v[98:101], v[170:173], v[186:189], v[98:101]
	v_mfma_f32_16x16x32_bf16 v[86:89], v[162:165], v[194:197], v[86:89]
	v_mfma_f32_16x16x32_bf16 v[82:85], v[170:173], v[194:197], v[82:85]
	v_mfma_f32_16x16x32_bf16 v[70:73], v[162:165], v[206:209], v[70:73]
	v_mfma_f32_16x16x32_bf16 v[66:69], v[170:173], v[206:209], v[66:69]
	v_mfma_f32_16x16x32_bf16 v[118:121], v[166:169], v[182:185], v[118:121]
	v_mfma_f32_16x16x32_bf16 v[114:117], v[174:177], v[182:185], v[114:117]
	v_mfma_f32_16x16x32_bf16 v[102:105], v[166:169], v[190:193], v[102:105]
	v_mfma_f32_16x16x32_bf16 v[98:101], v[174:177], v[190:193], v[98:101]
	v_mfma_f32_16x16x32_bf16 v[86:89], v[166:169], v[198:201], v[86:89]
	v_mfma_f32_16x16x32_bf16 v[82:85], v[174:177], v[198:201], v[82:85]
	v_mfma_f32_16x16x32_bf16 v[70:73], v[166:169], v[214:217], v[70:73]
	v_mfma_f32_16x16x32_bf16 v[66:69], v[174:177], v[214:217], v[66:69]
	s_setprio 0
	s_barrier
; #define PG8_STAGE(bufoff, gbase, voff) do { _Pragma("unroll") for (int _i = 0; _i < 2; ++_i) \
;         __builtin_amdgcn_global_load_lds((const unsigned*)((const char*)(gbase) + (voff)[_i]), (PG8_LAS unsigned*)(lds + (bufoff) + ldsw + _i * 8192), 16, 0, 0); } while (0)
; #define PG8_LDA(dst, b, h) do { _Pragma("unroll") for (int m = 0; m < 4; ++m) _Pragma("unroll") for (int k = 0; k < 2; ++k) dst[m][k] = *(const PG8_LAS bf16x8*)(lds + PG8_SA(b, h) + aoff + m * 2048 + k * 1024); } while (0)
; #define PG8_MMA(ai, bj, At, Bt) do { __builtin_amdgcn_s_setprio(1); _Pragma("unroll") for (int m = 0; m < 4; ++m) _Pragma("unroll") for (int n = 0; n < 2; ++n) _Pragma("unroll") for (int k = 0; k < 2; ++k) \
;         acc[ai][bj][m][n] = __builtin_amdgcn_mfma_f32_16x16x32_bf16(Bt[n][k], At[m][k], acc[ai][bj][m][n], 0, 0, 0); __builtin_amdgcn_s_setprio(0); } while (0)
; #define PG8_WAIT_V(n) asm volatile("s_waitcnt vmcnt(" #n ")" ::: "memory")
; #define PG8_WAIT_L(n) asm volatile("s_waitcnt lgkmcnt(" #n ")" ::: "memory")
; #define PG8_BAR __builtin_amdgcn_s_barrier()
; #define PG8_SCHED __builtin_amdgcn_sched_barrier(0)
; template <class Epi, class Sched, bool ALIGN_EPI = false, bool SP2 = false>
; __device__ __forceinline__ void gemm_phase(PG8_LAS unsigned char* lds, const Gemm g, const Sched& S, const Epi& E, const int tid) {
;     ...
;             PG8_LDA(At, 1, 1); PG8_STAGE(PG8_SB(1, 0), b3, voffB); PG8_STAGE(PG8_SB(1, 1), b3 + hstep, voffB); PG8_STAGE(PG8_SA(1, 0), a3, voffA);
;             PG8_WAIT_V(8); PG8_WAIT_L(0); PG8_BAR; PG8_MMA(1, 0, At, B0); PG8_MMA(1, 1, At, B1); PG8_BAR; PG8_SCHED;
;     ...
;         if constexpr (ALIGN_EPI) { if (wr == 0) PG8_BAR; }
	s_add_i32 s20, s48, s24
	v_lshl_add_u64 v[202:203], v[202:203], 0, s[94:95]
	s_mov_b32 m0, s20
	ds_read_b128 v[178:181], v145 offset:49152
	ds_read_b128 v[182:185], v145 offset:50176
	ds_read_b128 v[186:189], v145 offset:51200
	ds_read_b128 v[190:193], v145 offset:52224
	ds_read_b128 v[194:197], v145 offset:53248
	ds_read_b128 v[198:201], v145 offset:54272
	ds_read_b128 v[206:209], v145 offset:55296
	ds_read_b128 v[214:217], v145 offset:56320
	global_load_lds_dwordx4 v[202:203], off
	s_add_i32 m0, s20, 0x2000
	s_add_u32 s18, s18, 0x40080
	v_lshl_add_u64 v[202:203], v[210:211], 0, s[94:95]
	s_addc_u32 s19, s19, 0
	s_add_i32 s20, s49, s24
	global_load_lds_dwordx4 v[202:203], off
	v_lshl_add_u64 v[202:203], s[18:19], 0, v[134:135]
	s_mov_b32 m0, s20
	s_nop 0
	global_load_lds_dwordx4 v[202:203], off
	v_lshl_add_u64 v[202:203], s[18:19], 0, v[130:131]
	s_add_i32 m0, s20, 0x2000
	s_nop 0
	global_load_lds_dwordx4 v[202:203], off
	v_lshl_add_u64 v[202:203], v[218:219], 0, s[94:95]
	s_mov_b32 m0, s29
	s_nop 0
	global_load_lds_dwordx4 v[202:203], off
	v_lshl_add_u64 v[202:203], v[220:221], 0, s[94:95]
	s_mov_b32 m0, s30
	s_nop 0
	global_load_lds_dwordx4 v[202:203], off
	s_waitcnt vmcnt(8)
	s_waitcnt lgkmcnt(0)
	s_barrier
	s_setprio 1
	v_mfma_f32_16x16x32_bf16 v[60:63], v[146:149], v[178:181], v[60:63]
	v_mfma_f32_16x16x32_bf16 v[56:59], v[154:157], v[178:181], v[56:59]
	v_mfma_f32_16x16x32_bf16 v[44:47], v[146:149], v[186:189], v[44:47]
	v_mfma_f32_16x16x32_bf16 v[40:43], v[154:157], v[186:189], v[40:43]
	v_mfma_f32_16x16x32_bf16 v[28:31], v[146:149], v[194:197], v[28:31]
	v_mfma_f32_16x16x32_bf16 v[24:27], v[154:157], v[194:197], v[24:27]
	v_mfma_f32_16x16x32_bf16 v[12:15], v[146:149], v[206:209], v[12:15]
	v_mfma_f32_16x16x32_bf16 v[8:11], v[154:157], v[206:209], v[8:11]
	v_mfma_f32_16x16x32_bf16 v[60:63], v[150:153], v[182:185], v[60:63]
	v_mfma_f32_16x16x32_bf16 v[56:59], v[158:161], v[182:185], v[56:59]
	v_mfma_f32_16x16x32_bf16 v[44:47], v[150:153], v[190:193], v[44:47]
	v_mfma_f32_16x16x32_bf16 v[40:43], v[158:161], v[190:193], v[40:43]
	v_mfma_f32_16x16x32_bf16 v[28:31], v[150:153], v[198:201], v[28:31]
	v_mfma_f32_16x16x32_bf16 v[24:27], v[158:161], v[198:201], v[24:27]
	v_mfma_f32_16x16x32_bf16 v[12:15], v[150:153], v[214:217], v[12:15]
	v_mfma_f32_16x16x32_bf16 v[8:11], v[158:161], v[214:217], v[8:11]
	s_setprio 0
	s_setprio 1
	v_mfma_f32_16x16x32_bf16 v[52:55], v[162:165], v[178:181], v[52:55]
	v_mfma_f32_16x16x32_bf16 v[48:51], v[170:173], v[178:181], v[48:51]
	v_mfma_f32_16x16x32_bf16 v[36:39], v[162:165], v[186:189], v[36:39]
	v_mfma_f32_16x16x32_bf16 v[32:35], v[170:173], v[186:189], v[32:35]
	v_mfma_f32_16x16x32_bf16 v[20:23], v[162:165], v[194:197], v[20:23]
	v_mfma_f32_16x16x32_bf16 v[16:19], v[170:173], v[194:197], v[16:19]
	v_mfma_f32_16x16x32_bf16 v[4:7], v[162:165], v[206:209], v[4:7]
	v_mfma_f32_16x16x32_bf16 v[0:3], v[170:173], v[206:209], v[0:3]
	v_mfma_f32_16x16x32_bf16 v[52:55], v[166:169], v[182:185], v[52:55]
	v_mfma_f32_16x16x32_bf16 v[48:51], v[174:177], v[182:185], v[48:51]
	v_mfma_f32_16x16x32_bf16 v[36:39], v[166:169], v[190:193], v[36:39]
	v_mfma_f32_16x16x32_bf16 v[32:35], v[174:177], v[190:193], v[32:35]
	v_mfma_f32_16x16x32_bf16 v[20:23], v[166:169], v[198:201], v[20:23]
	v_mfma_f32_16x16x32_bf16 v[16:19], v[174:177], v[198:201], v[16:19]
	v_mfma_f32_16x16x32_bf16 v[4:7], v[166:169], v[214:217], v[4:7]
	v_mfma_f32_16x16x32_bf16 v[0:3], v[174:177], v[214:217], v[0:3]
	s_setprio 0
	s_barrier
	s_add_i32 s47, s47, 2
	s_add_u32 s45, s45, 0x100
	s_addc_u32 s46, s46, 0
	s_add_u32 s16, s16, 0x100
	s_addc_u32 s17, s17, 0
	s_cmp_gt_u32 s47, 13
	s_cbranch_scc0 .LBB0_254
	s_and_b64 vcc, exec, s[4:5]
	s_cbranch_vccz .LBB0_257
	s_barrier

; #define PG8_STAGE(bufoff, gbase, voff) do { _Pragma("unroll") for (int _i = 0; _i < 2; ++_i) \
;         __builtin_amdgcn_global_load_lds((const unsigned*)((const char*)(gbase) + (voff)[_i]), (PG8_LAS unsigned*)(lds + (bufoff) + ldsw + _i * 8192), 16, 0, 0); } while (0)
; #define PG8_LDA(dst, b, h) do { _Pragma("unroll") for (int m = 0; m < 4; ++m) _Pragma("unroll") for (int k = 0; k < 2; ++k) dst[m][k] = *(const PG8_LAS bf16x8*)(lds + PG8_SA(b, h) + aoff + m * 2048 + k * 1024); } while (0)
; #define PG8_LDB(dst, b, h) do { _Pragma("unroll") for (int n = 0; n < 2; ++n) _Pragma("unroll") for (int k = 0; k < 2; ++k) dst[n][k] = *(const PG8_LAS bf16x8*)(lds + PG8_SB(b, h) + boff + n * 2048 + k * 1024); } while (0)
; #define PG8_MMA(ai, bj, At, Bt) do { __builtin_amdgcn_s_setprio(1); _Pragma("unroll") for (int m = 0; m < 4; ++m) _Pragma("unroll") for (int n = 0; n < 2; ++n) _Pragma("unroll") for (int k = 0; k < 2; ++k) \
;         acc[ai][bj][m][n] = __builtin_amdgcn_mfma_f32_16x16x32_bf16(Bt[n][k], At[m][k], acc[ai][bj][m][n], 0, 0, 0); __builtin_amdgcn_s_setprio(0); } while (0)
; #define PG8_WAIT_V(n) asm volatile("s_waitcnt vmcnt(" #n ")" ::: "memory")
; #define PG8_WAIT_L(n) asm volatile("s_waitcnt lgkmcnt(" #n ")" ::: "memory")
; template <class Epi, class Sched, bool ALIGN_EPI = false, bool SP2 = false>
; __device__ __forceinline__ void gemm_phase(PG8_LAS unsigned char* lds, const Gemm g, const Sched& S, const Epi& E, const int tid) {
;     ...
;             const bool last = (t == nt - 2);
;             const char* a1 = cA + (size_t)(t + 1) * kstep;
;             const char* a2 = last ? nA : cA + (size_t)(t + 2) * kstep; const char* b2 = last ? nB : cB + (size_t)(t + 2) * kstep;
;             const char* a3 = a2 + kstep; const char* b3 = b2 + kstep;
;             if (last && has_next) S.a_ready(nxt);
;             if constexpr (SP2) {
;             PG8_LDB(B0, 0, 0); PG8_LDB(B1, 0, 1); PG8_SCHED; PG8_LDA(At, 0, 0); PG8_STAGE(PG8_SA(1, 1), a1 + hstep, voffA);
;             PG8_WAIT_V(8); PG8_WAIT_L(0); PG8_BAR; PG8_MMA(0, 0, At, B0); PG8_MMA(0, 1, At, B1); PG8_BAR; PG8_SCHED;
;             PG8_LDA(At, 0, 1); PG8_STAGE(PG8_SB(0, 0), b2, voffB); PG8_STAGE(PG8_SB(0, 1), b2 + hstep, voffB); PG8_STAGE(PG8_SA(0, 0), a2, voffA);
;             PG8_WAIT_V(8); PG8_WAIT_L(0); PG8_BAR; PG8_MMA(1, 0, At, B0); PG8_MMA(1, 1, At, B1); PG8_BAR; PG8_SCHED;
.LBB0_286:
	s_add_u32 s20, s8, s18
	s_addc_u32 s21, s9, s19
	s_add_u32 s20, s20, 0x100
	s_addc_u32 s21, s21, 0
	s_add_u32 s54, s49, s18
	s_addc_u32 s55, s50, s19
	s_add_i32 s56, 0, 0x10000
	s_cmpk_eq_i32 s18, 0x700
	s_cselect_b32 s23, s13, s21
	s_cselect_b32 s22, s51, s20
	s_cselect_b32 s21, s11, s55
	s_cselect_b32 s20, s52, s54
	s_add_i32 s57, 0, 0x14000
	v_add_u32_e32 v86, s56, v72
	v_add_u32_e32 v110, s57, v72
	ds_read_b128 v[74:77], v86
	ds_read_b128 v[78:81], v86 offset:1024
	ds_read_b128 v[82:85], v86 offset:2048
	ds_read_b128 v[86:89], v86 offset:3072
	ds_read_b128 v[90:93], v110
	ds_read_b128 v[94:97], v110 offset:1024
	ds_read_b128 v[106:109], v110 offset:2048
	ds_read_b128 v[110:113], v110 offset:3072
	v_lshl_add_u64 v[202:203], v[70:71], 0, s[18:19]
	s_add_i32 m0, s31, 0xc000
	ds_read_b128 v[114:117], v73
	ds_read_b128 v[118:121], v73 offset:1024
	ds_read_b128 v[122:125], v73 offset:2048
	ds_read_b128 v[126:129], v73 offset:3072
	ds_read_b128 v[194:197], v73 offset:4096
	ds_read_b128 v[198:201], v73 offset:5120
	ds_read_b128 v[206:209], v73 offset:6144
	ds_read_b128 v[214:217], v73 offset:7168
	global_load_lds_dwordx4 v[202:203], off
	v_lshl_add_u64 v[202:203], v[68:69], 0, s[18:19]
	s_add_i32 m0, s31, 0xe000
	s_nop 0
	global_load_lds_dwordx4 v[202:203], off
	s_waitcnt vmcnt(8)
	s_waitcnt lgkmcnt(0)
	s_barrier
	s_setprio 1
	v_mfma_f32_16x16x32_bf16 v[190:193], v[74:77], v[114:117], v[190:193]
	v_mfma_f32_16x16x32_bf16 v[186:189], v[82:85], v[114:117], v[186:189]
	v_mfma_f32_16x16x32_bf16 v[182:185], v[74:77], v[122:125], v[182:185]
	v_mfma_f32_16x16x32_bf16 v[178:181], v[82:85], v[122:125], v[178:181]
	v_mfma_f32_16x16x32_bf16 v[174:177], v[74:77], v[194:197], v[174:177]
	v_mfma_f32_16x16x32_bf16 v[170:173], v[82:85], v[194:197], v[170:173]
	v_mfma_f32_16x16x32_bf16 v[166:169], v[74:77], v[206:209], v[166:169]
	v_mfma_f32_16x16x32_bf16 v[162:165], v[82:85], v[206:209], v[162:165]
	v_mfma_f32_16x16x32_bf16 v[190:193], v[78:81], v[118:121], v[190:193]
	v_mfma_f32_16x16x32_bf16 v[186:189], v[86:89], v[118:121], v[186:189]
	v_mfma_f32_16x16x32_bf16 v[182:185], v[78:81], v[126:129], v[182:185]
	v_mfma_f32_16x16x32_bf16 v[178:181], v[86:89], v[126:129], v[178:181]
	v_mfma_f32_16x16x32_bf16 v[174:177], v[78:81], v[198:201], v[174:177]
	v_mfma_f32_16x16x32_bf16 v[170:173], v[86:89], v[198:201], v[170:173]
	v_mfma_f32_16x16x32_bf16 v[166:169], v[78:81], v[214:217], v[166:169]
	v_mfma_f32_16x16x32_bf16 v[162:165], v[86:89], v[214:217], v[162:165]
	s_setprio 0
	s_setprio 1
	v_mfma_f32_16x16x32_bf16 v[102:105], v[90:93], v[114:117], v[102:105]
	v_mfma_f32_16x16x32_bf16 v[98:101], v[106:109], v[114:117], v[98:101]
	v_mfma_f32_16x16x32_bf16 v[56:59], v[90:93], v[122:125], v[56:59]
	v_mfma_f32_16x16x32_bf16 v[48:51], v[106:109], v[122:125], v[48:51]
	v_mfma_f32_16x16x32_bf16 v[44:47], v[90:93], v[194:197], v[44:47]
	v_mfma_f32_16x16x32_bf16 v[40:43], v[106:109], v[194:197], v[40:43]
	v_mfma_f32_16x16x32_bf16 v[36:39], v[90:93], v[206:209], v[36:39]
	v_mfma_f32_16x16x32_bf16 v[32:35], v[106:109], v[206:209], v[32:35]
	v_mfma_f32_16x16x32_bf16 v[102:105], v[94:97], v[118:121], v[102:105]
	v_mfma_f32_16x16x32_bf16 v[98:101], v[110:113], v[118:121], v[98:101]
	v_mfma_f32_16x16x32_bf16 v[56:59], v[94:97], v[126:129], v[56:59]
	v_mfma_f32_16x16x32_bf16 v[48:51], v[110:113], v[126:129], v[48:51]
	v_mfma_f32_16x16x32_bf16 v[44:47], v[94:97], v[198:201], v[44:47]
	v_mfma_f32_16x16x32_bf16 v[40:43], v[110:113], v[198:201], v[40:43]
	v_mfma_f32_16x16x32_bf16 v[36:39], v[94:97], v[214:217], v[36:39]
	v_mfma_f32_16x16x32_bf16 v[32:35], v[110:113], v[214:217], v[32:35]
	s_setprio 0
	s_barrier
	s_add_i32 s54, s56, s30
	v_lshl_add_u64 v[202:203], s[20:21], 0, v[64:65]
	s_mov_b32 m0, s54
	ds_read_b128 v[114:117], v73 offset:16384
	ds_read_b128 v[118:121], v73 offset:17408
	ds_read_b128 v[122:125], v73 offset:18432
	ds_read_b128 v[126:129], v73 offset:19456
	ds_read_b128 v[194:197], v73 offset:20480
	ds_read_b128 v[198:201], v73 offset:21504
	ds_read_b128 v[206:209], v73 offset:22528
	ds_read_b128 v[214:217], v73 offset:23552
	global_load_lds_dwordx4 v[202:203], off
	s_add_i32 m0, s54, 0x2000
	s_add_u32 s54, s20, 0x40000
	v_lshl_add_u64 v[210:211], s[20:21], 0, v[52:53]
	s_addc_u32 s55, s21, 0
	s_add_i32 s56, s57, s30
	global_load_lds_dwordx4 v[210:211], off
	v_lshl_add_u64 v[218:219], s[54:55], 0, v[64:65]
	s_mov_b32 m0, s56
	v_lshl_add_u64 v[226:227], s[22:23], 0, v[60:61]
	global_load_lds_dwordx4 v[218:219], off
	v_lshl_add_u64 v[218:219], s[54:55], 0, v[52:53]
	s_add_i32 m0, s56, 0x2000
	v_lshl_add_u64 v[228:229], s[22:23], 0, v[54:55]
	global_load_lds_dwordx4 v[218:219], off
	s_mov_b32 m0, s31
	s_nop 0
	global_load_lds_dwordx4 v[226:227], off
	s_mov_b32 m0, s35
	s_nop 0
	global_load_lds_dwordx4 v[228:229], off
	s_waitcnt vmcnt(8)
	s_waitcnt lgkmcnt(0)
	s_barrier
; #define PG8_STAGE(bufoff, gbase, voff) do { _Pragma("unroll") for (int _i = 0; _i < 2; ++_i) \
;         __builtin_amdgcn_global_load_lds((const unsigned*)((const char*)(gbase) + (voff)[_i]), (PG8_LAS unsigned*)(lds + (bufoff) + ldsw + _i * 8192), 16, 0, 0); } while (0)
; #define PG8_LDA(dst, b, h) do { _Pragma("unroll") for (int m = 0; m < 4; ++m) _Pragma("unroll") for (int k = 0; k < 2; ++k) dst[m][k] = *(const PG8_LAS bf16x8*)(lds + PG8_SA(b, h) + aoff + m * 2048 + k * 1024); } while (0)
; #define PG8_LDB(dst, b, h) do { _Pragma("unroll") for (int n = 0; n < 2; ++n) _Pragma("unroll") for (int k = 0; k < 2; ++k) dst[n][k] = *(const PG8_LAS bf16x8*)(lds + PG8_SB(b, h) + boff + n * 2048 + k * 1024); } while (0)
; #define PG8_MMA(ai, bj, At, Bt) do { __builtin_amdgcn_s_setprio(1); _Pragma("unroll") for (int m = 0; m < 4; ++m) _Pragma("unroll") for (int n = 0; n < 2; ++n) _Pragma("unroll") for (int k = 0; k < 2; ++k) \
;         acc[ai][bj][m][n] = __builtin_amdgcn_mfma_f32_16x16x32_bf16(Bt[n][k], At[m][k], acc[ai][bj][m][n], 0, 0, 0); __builtin_amdgcn_s_setprio(0); } while (0)
; #define PG8_WAIT_V(n) asm volatile("s_waitcnt vmcnt(" #n ")" ::: "memory")
; #define PG8_WAIT_L(n) asm volatile("s_waitcnt lgkmcnt(" #n ")" ::: "memory")
; #define PG8_BAR __builtin_amdgcn_s_barrier()
; #define PG8_SCHED __builtin_amdgcn_sched_barrier(0)
; template <class Epi, class Sched, bool ALIGN_EPI = false, bool SP2 = false>
; __device__ __forceinline__ void gemm_phase(PG8_LAS unsigned char* lds, const Gemm g, const Sched& S, const Epi& E, const int tid) {
;     ...
;             PG8_WAIT_V(8); PG8_WAIT_L(0); PG8_BAR; PG8_MMA(1, 0, At, B0); PG8_MMA(1, 1, At, B1); PG8_BAR; PG8_SCHED;
;             PG8_LDB(B0, 1, 0); PG8_LDB(B1, 1, 1); PG8_SCHED; PG8_LDA(At, 1, 0); PG8_STAGE(PG8_SA(0, 1), a2 + hstep, voffA);
;             PG8_WAIT_V(8); PG8_WAIT_L(0); PG8_BAR; PG8_MMA(0, 0, At, B0); PG8_MMA(0, 1, At, B1); PG8_BAR; PG8_SCHED;
	s_setprio 1
	v_mfma_f32_16x16x32_bf16 v[158:161], v[74:77], v[114:117], v[158:161]
	v_mfma_f32_16x16x32_bf16 v[154:157], v[82:85], v[114:117], v[154:157]
	v_mfma_f32_16x16x32_bf16 v[150:153], v[74:77], v[122:125], v[150:153]
	v_mfma_f32_16x16x32_bf16 v[146:149], v[82:85], v[122:125], v[146:149]
	v_mfma_f32_16x16x32_bf16 v[142:145], v[74:77], v[194:197], v[142:145]
	v_mfma_f32_16x16x32_bf16 v[138:141], v[82:85], v[194:197], v[138:141]
	v_mfma_f32_16x16x32_bf16 v[74:77], v[74:77], v[206:209], v[134:137]
	v_mfma_f32_16x16x32_bf16 v[158:161], v[78:81], v[118:121], v[158:161]
	v_mfma_f32_16x16x32_bf16 v[154:157], v[86:89], v[118:121], v[154:157]
	v_mfma_f32_16x16x32_bf16 v[150:153], v[78:81], v[126:129], v[150:153]
	v_mfma_f32_16x16x32_bf16 v[146:149], v[86:89], v[126:129], v[146:149]
	v_mfma_f32_16x16x32_bf16 v[142:145], v[78:81], v[198:201], v[142:145]
	v_mfma_f32_16x16x32_bf16 v[138:141], v[86:89], v[198:201], v[138:141]
	v_mfma_f32_16x16x32_bf16 v[74:77], v[78:81], v[214:217], v[74:77]
	v_mfma_f32_16x16x32_bf16 v[78:81], v[82:85], v[206:209], v[130:133]
	v_mfma_f32_16x16x32_bf16 v[78:81], v[86:89], v[214:217], v[78:81]
	s_setprio 0
	s_setprio 1
	v_mfma_f32_16x16x32_bf16 v[28:31], v[90:93], v[114:117], v[28:31]
	v_mfma_f32_16x16x32_bf16 v[24:27], v[106:109], v[114:117], v[24:27]
	v_mfma_f32_16x16x32_bf16 v[20:23], v[90:93], v[122:125], v[20:23]
	v_mfma_f32_16x16x32_bf16 v[16:19], v[106:109], v[122:125], v[16:19]
	v_mfma_f32_16x16x32_bf16 v[12:15], v[90:93], v[194:197], v[12:15]
	v_mfma_f32_16x16x32_bf16 v[8:11], v[106:109], v[194:197], v[8:11]
	v_mfma_f32_16x16x32_bf16 v[4:7], v[90:93], v[206:209], v[4:7]
	v_mfma_f32_16x16x32_bf16 v[0:3], v[106:109], v[206:209], v[0:3]
	v_mfma_f32_16x16x32_bf16 v[28:31], v[94:97], v[118:121], v[28:31]
	v_mfma_f32_16x16x32_bf16 v[24:27], v[110:113], v[118:121], v[24:27]
	v_mfma_f32_16x16x32_bf16 v[20:23], v[94:97], v[126:129], v[20:23]
	v_mfma_f32_16x16x32_bf16 v[16:19], v[110:113], v[126:129], v[16:19]
	v_mfma_f32_16x16x32_bf16 v[12:15], v[94:97], v[198:201], v[12:15]
	v_mfma_f32_16x16x32_bf16 v[8:11], v[110:113], v[198:201], v[8:11]
	v_mfma_f32_16x16x32_bf16 v[4:7], v[94:97], v[214:217], v[4:7]
	v_mfma_f32_16x16x32_bf16 v[0:3], v[110:113], v[214:217], v[0:3]
	s_setprio 0
	s_barrier
	s_add_i32 s54, 0, 0x18000
	s_add_i32 s55, 0, 0x1c000
	v_add_u32_e32 v94, s54, v72
	v_add_u32_e32 v118, s55, v72
	ds_read_b128 v[82:85], v94
	ds_read_b128 v[86:89], v94 offset:1024
	ds_read_b128 v[90:93], v94 offset:2048
	ds_read_b128 v[94:97], v94 offset:3072
	ds_read_b128 v[106:109], v118
	ds_read_b128 v[110:113], v118 offset:1024
	ds_read_b128 v[114:117], v118 offset:2048
	ds_read_b128 v[118:121], v118 offset:3072
	s_add_u32 s22, s22, 0x40000
	s_addc_u32 s23, s23, 0
	s_mov_b32 m0, s42
	v_lshl_add_u64 v[218:219], s[22:23], 0, v[60:61]
	ds_read_b128 v[122:125], v73 offset:32768
	ds_read_b128 v[126:129], v73 offset:33792
	ds_read_b128 v[130:133], v73 offset:34816
	ds_read_b128 v[134:137], v73 offset:35840
	ds_read_b128 v[194:197], v73 offset:36864
	ds_read_b128 v[198:201], v73 offset:37888
	ds_read_b128 v[206:209], v73 offset:38912
	ds_read_b128 v[214:217], v73 offset:39936
	global_load_lds_dwordx4 v[218:219], off
	v_lshl_add_u64 v[218:219], s[22:23], 0, v[54:55]
	s_mov_b32 m0, s44
	s_nop 0
	global_load_lds_dwordx4 v[218:219], off
	s_waitcnt vmcnt(8)
	s_waitcnt lgkmcnt(0)
	s_barrier
	s_setprio 1
	v_mfma_f32_16x16x32_bf16 v[190:193], v[82:85], v[122:125], v[190:193]
	v_mfma_f32_16x16x32_bf16 v[186:189], v[90:93], v[122:125], v[186:189]
	v_mfma_f32_16x16x32_bf16 v[182:185], v[82:85], v[130:133], v[182:185]
	v_mfma_f32_16x16x32_bf16 v[178:181], v[90:93], v[130:133], v[178:181]
	v_mfma_f32_16x16x32_bf16 v[174:177], v[82:85], v[194:197], v[174:177]
	v_mfma_f32_16x16x32_bf16 v[170:173], v[90:93], v[194:197], v[170:173]
	v_mfma_f32_16x16x32_bf16 v[166:169], v[82:85], v[206:209], v[166:169]
	v_mfma_f32_16x16x32_bf16 v[162:165], v[90:93], v[206:209], v[162:165]
	v_mfma_f32_16x16x32_bf16 v[190:193], v[86:89], v[126:129], v[190:193]
	v_mfma_f32_16x16x32_bf16 v[186:189], v[94:97], v[126:129], v[186:189]
	v_mfma_f32_16x16x32_bf16 v[182:185], v[86:89], v[134:137], v[182:185]
	v_mfma_f32_16x16x32_bf16 v[178:181], v[94:97], v[134:137], v[178:181]
	v_mfma_f32_16x16x32_bf16 v[174:177], v[86:89], v[198:201], v[174:177]
	v_mfma_f32_16x16x32_bf16 v[170:173], v[94:97], v[198:201], v[170:173]
	v_mfma_f32_16x16x32_bf16 v[166:169], v[86:89], v[214:217], v[166:169]
	v_mfma_f32_16x16x32_bf16 v[162:165], v[94:97], v[214:217], v[162:165]
	s_setprio 0
	s_setprio 1
	v_mfma_f32_16x16x32_bf16 v[102:105], v[106:109], v[122:125], v[102:105]
	v_mfma_f32_16x16x32_bf16 v[98:101], v[114:117], v[122:125], v[98:101]
	v_mfma_f32_16x16x32_bf16 v[56:59], v[106:109], v[130:133], v[56:59]
	v_mfma_f32_16x16x32_bf16 v[48:51], v[114:117], v[130:133], v[48:51]
	v_mfma_f32_16x16x32_bf16 v[44:47], v[106:109], v[194:197], v[44:47]
	v_mfma_f32_16x16x32_bf16 v[40:43], v[114:117], v[194:197], v[40:43]
	v_mfma_f32_16x16x32_bf16 v[36:39], v[106:109], v[206:209], v[36:39]
	v_mfma_f32_16x16x32_bf16 v[32:35], v[114:117], v[206:209], v[32:35]
	v_mfma_f32_16x16x32_bf16 v[102:105], v[110:113], v[126:129], v[102:105]
	v_mfma_f32_16x16x32_bf16 v[98:101], v[118:121], v[126:129], v[98:101]
	v_mfma_f32_16x16x32_bf16 v[56:59], v[110:113], v[134:137], v[56:59]
	v_mfma_f32_16x16x32_bf16 v[48:51], v[118:121], v[134:137], v[48:51]
	v_mfma_f32_16x16x32_bf16 v[44:47], v[110:113], v[198:201], v[44:47]
	v_mfma_f32_16x16x32_bf16 v[40:43], v[118:121], v[198:201], v[40:43]
	v_mfma_f32_16x16x32_bf16 v[36:39], v[110:113], v[214:217], v[36:39]
	v_mfma_f32_16x16x32_bf16 v[32:35], v[118:121], v[214:217], v[32:35]
	s_setprio 0
	s_barrier
; #define PG8_STAGE(bufoff, gbase, voff) do { _Pragma("unroll") for (int _i = 0; _i < 2; ++_i) \
;         __builtin_amdgcn_global_load_lds((const unsigned*)((const char*)(gbase) + (voff)[_i]), (PG8_LAS unsigned*)(lds + (bufoff) + ldsw + _i * 8192), 16, 0, 0); } while (0)
; #define PG8_LDA(dst, b, h) do { _Pragma("unroll") for (int m = 0; m < 4; ++m) _Pragma("unroll") for (int k = 0; k < 2; ++k) dst[m][k] = *(const PG8_LAS bf16x8*)(lds + PG8_SA(b, h) + aoff + m * 2048 + k * 1024); } while (0)
; #define PG8_MMA(ai, bj, At, Bt) do { __builtin_amdgcn_s_setprio(1); _Pragma("unroll") for (int m = 0; m < 4; ++m) _Pragma("unroll") for (int n = 0; n < 2; ++n) _Pragma("unroll") for (int k = 0; k < 2; ++k) \
;         acc[ai][bj][m][n] = __builtin_amdgcn_mfma_f32_16x16x32_bf16(Bt[n][k], At[m][k], acc[ai][bj][m][n], 0, 0, 0); __builtin_amdgcn_s_setprio(0); } while (0)
; #define PG8_WAIT_V(n) asm volatile("s_waitcnt vmcnt(" #n ")" ::: "memory")
; #define PG8_WAIT_L(n) asm volatile("s_waitcnt lgkmcnt(" #n ")" ::: "memory")
; #define PG8_BAR __builtin_amdgcn_s_barrier()
; #define PG8_SCHED __builtin_amdgcn_sched_barrier(0)
; template <class Epi, class Sched, bool ALIGN_EPI = false, bool SP2 = false>
; __device__ __forceinline__ void gemm_phase(PG8_LAS unsigned char* lds, const Gemm g, const Sched& S, const Epi& E, const int tid) {
;     ...
;             PG8_LDA(At, 1, 1); PG8_STAGE(PG8_SB(1, 0), b3, voffB); PG8_STAGE(PG8_SB(1, 1), b3 + hstep, voffB); PG8_STAGE(PG8_SA(1, 0), a3, voffA);
;             PG8_WAIT_V(8); PG8_WAIT_L(0); PG8_BAR; PG8_MMA(1, 0, At, B0); PG8_MMA(1, 1, At, B1); PG8_BAR; PG8_SCHED;
;     ...
;         if (!has_next) break;
; #pragma unroll
;         for (int a = 0; a < 2; ++a)
; #pragma unroll
;             for (int b = 0; b < 2; ++b)
; #pragma unroll
;                 for (int m = 0; m < 4; ++m)
; #pragma unroll
;                     for (int n = 0; n < 2; ++n) acc[a][b][m][n] = (f32x4){0.f, 0.f, 0.f, 0.f};
;         cur = nxt; cA = nA; cB = nB; ++ui;
	s_add_i32 s22, s54, s30
	v_lshl_add_u64 v[130:131], v[202:203], 0, s[94:95]
	s_mov_b32 m0, s22
	ds_read_b128 v[122:125], v73 offset:49152
	ds_read_b128 v[126:129], v73 offset:50176
	ds_read_b128 v[194:197], v73 offset:51200
	ds_read_b128 v[198:201], v73 offset:52224
	ds_read_b128 v[206:209], v73 offset:53248
	ds_read_b128 v[214:217], v73 offset:54272
	ds_read_b128 v[218:221], v73 offset:55296
	ds_read_b128 v[222:225], v73 offset:56320
	global_load_lds_dwordx4 v[130:131], off
	s_add_i32 m0, s22, 0x2000
	s_add_u32 s20, s20, 0x40080
	v_lshl_add_u64 v[130:131], v[210:211], 0, s[94:95]
	s_addc_u32 s21, s21, 0
	s_add_i32 s22, s55, s30
	global_load_lds_dwordx4 v[130:131], off
	v_lshl_add_u64 v[130:131], s[20:21], 0, v[64:65]
	s_mov_b32 m0, s22
	s_nop 0
	global_load_lds_dwordx4 v[130:131], off
	v_lshl_add_u64 v[130:131], s[20:21], 0, v[52:53]
	s_add_i32 m0, s22, 0x2000
	s_nop 0
	global_load_lds_dwordx4 v[130:131], off
	v_lshl_add_u64 v[130:131], v[226:227], 0, s[94:95]
	s_mov_b32 m0, s45
	s_nop 0
	global_load_lds_dwordx4 v[130:131], off
	v_lshl_add_u64 v[130:131], v[228:229], 0, s[94:95]
	s_mov_b32 m0, s46
	s_nop 0
	global_load_lds_dwordx4 v[130:131], off
	s_waitcnt vmcnt(8)
	s_waitcnt lgkmcnt(0)
	s_barrier
	s_setprio 1
	v_mfma_f32_16x16x32_bf16 v[130:133], v[82:85], v[122:125], v[158:161]
	v_mfma_f32_16x16x32_bf16 v[158:161], v[86:89], v[126:129], v[130:133]
	v_mfma_f32_16x16x32_bf16 v[130:133], v[90:93], v[122:125], v[154:157]
	v_mfma_f32_16x16x32_bf16 v[154:157], v[94:97], v[126:129], v[130:133]
	v_mfma_f32_16x16x32_bf16 v[130:133], v[82:85], v[194:197], v[150:153]
	v_mfma_f32_16x16x32_bf16 v[150:153], v[86:89], v[198:201], v[130:133]
	v_mfma_f32_16x16x32_bf16 v[130:133], v[90:93], v[194:197], v[146:149]
	v_mfma_f32_16x16x32_bf16 v[146:149], v[94:97], v[198:201], v[130:133]
	v_mfma_f32_16x16x32_bf16 v[130:133], v[82:85], v[206:209], v[142:145]
	v_mfma_f32_16x16x32_bf16 v[74:77], v[82:85], v[218:221], v[74:77]
	v_mfma_f32_16x16x32_bf16 v[142:145], v[86:89], v[214:217], v[130:133]
	v_mfma_f32_16x16x32_bf16 v[130:133], v[90:93], v[206:209], v[138:141]
	v_mfma_f32_16x16x32_bf16 v[134:137], v[86:89], v[222:225], v[74:77]
	v_mfma_f32_16x16x32_bf16 v[74:77], v[90:93], v[218:221], v[78:81]
	v_mfma_f32_16x16x32_bf16 v[138:141], v[94:97], v[214:217], v[130:133]
	v_mfma_f32_16x16x32_bf16 v[130:133], v[94:97], v[222:225], v[74:77]
	s_setprio 0
	s_setprio 1
	v_mfma_f32_16x16x32_bf16 v[28:31], v[106:109], v[122:125], v[28:31]
	v_mfma_f32_16x16x32_bf16 v[24:27], v[114:117], v[122:125], v[24:27]
	v_mfma_f32_16x16x32_bf16 v[20:23], v[106:109], v[194:197], v[20:23]
	v_mfma_f32_16x16x32_bf16 v[16:19], v[114:117], v[194:197], v[16:19]
	v_mfma_f32_16x16x32_bf16 v[12:15], v[106:109], v[206:209], v[12:15]
	v_mfma_f32_16x16x32_bf16 v[8:11], v[114:117], v[206:209], v[8:11]
	v_mfma_f32_16x16x32_bf16 v[4:7], v[106:109], v[218:221], v[4:7]
	v_mfma_f32_16x16x32_bf16 v[0:3], v[114:117], v[218:221], v[0:3]
	v_mfma_f32_16x16x32_bf16 v[28:31], v[110:113], v[126:129], v[28:31]
	v_mfma_f32_16x16x32_bf16 v[24:27], v[118:121], v[126:129], v[24:27]
	v_mfma_f32_16x16x32_bf16 v[20:23], v[110:113], v[198:201], v[20:23]
	v_mfma_f32_16x16x32_bf16 v[16:19], v[118:121], v[198:201], v[16:19]
	v_mfma_f32_16x16x32_bf16 v[12:15], v[110:113], v[214:217], v[12:15]
	v_mfma_f32_16x16x32_bf16 v[8:11], v[118:121], v[214:217], v[8:11]
	v_mfma_f32_16x16x32_bf16 v[4:7], v[110:113], v[222:225], v[4:7]
	v_mfma_f32_16x16x32_bf16 v[0:3], v[118:121], v[222:225], v[0:3]
	s_setprio 0
	s_barrier
	s_add_i32 s53, s53, 2
	s_add_u32 s18, s18, 0x100
	s_addc_u32 s19, s19, 0
	s_cmp_gt_u32 s53, 13
	s_cbranch_scc0 .LBB0_286
	s_add_u32 s18, s49, 0xffffff00
	s_addc_u32 s19, s50, -1
	s_andn2_b64 vcc, exec, s[2:3]
	s_cbranch_vccnz .LBB0_289
	v_mov_b32_e32 v0, 0
	s_mov_b32 s4, s10
	s_mov_b32 s24, s12
	s_mov_b64 s[8:9], s[16:17]
	s_mov_b32 s47, s48
	v_mov_b32_e32 v1, v0
	v_mov_b32_e32 v2, v0
	v_mov_b32_e32 v3, v0
	v_mov_b32_e32 v4, v0
	v_mov_b32_e32 v5, v0
	v_mov_b32_e32 v6, v0
	v_mov_b32_e32 v7, v0
	v_mov_b32_e32 v8, v0
	v_mov_b32_e32 v9, v0
	v_mov_b32_e32 v10, v0
	v_mov_b32_e32 v11, v0
	v_mov_b32_e32 v12, v0
	v_mov_b32_e32 v13, v0
	v_mov_b32_e32 v14, v0
	v_mov_b32_e32 v15, v0
	v_mov_b32_e32 v16, v0
	v_mov_b32_e32 v17, v0
	v_mov_b32_e32 v18, v0
	v_mov_b32_e32 v19, v0
	v_mov_b32_e32 v20, v0
	v_mov_b32_e32 v21, v0
	v_mov_b32_e32 v22, v0
	v_mov_b32_e32 v23, v0
	v_mov_b32_e32 v24, v0
	v_mov_b32_e32 v25, v0
	v_mov_b32_e32 v26, v0
	v_mov_b32_e32 v27, v0
	v_mov_b32_e32 v28, v0
	v_mov_b32_e32 v29, v0
	v_mov_b32_e32 v30, v0
	v_mov_b32_e32 v31, v0
	v_mov_b32_e32 v130, v0
	v_mov_b32_e32 v131, v0
	v_mov_b32_e32 v132, v0
	v_mov_b32_e32 v133, v0
	v_mov_b32_e32 v134, v0
	v_mov_b32_e32 v135, v0
	v_mov_b32_e32 v136, v0
	v_mov_b32_e32 v137, v0
	v_mov_b32_e32 v138, v0
	v_mov_b32_e32 v139, v0
	v_mov_b32_e32 v140, v0
	v_mov_b32_e32 v141, v0
	v_mov_b32_e32 v142, v0
	v_mov_b32_e32 v143, v0
	v_mov_b32_e32 v144, v0
	v_mov_b32_e32 v145, v0
	v_mov_b32_e32 v146, v0
	v_mov_b32_e32 v147, v0
	v_mov_b32_e32 v148, v0
	v_mov_b32_e32 v149, v0
	v_mov_b32_e32 v150, v0
	v_mov_b32_e32 v151, v0
	v_mov_b32_e32 v152, v0
	v_mov_b32_e32 v153, v0
	v_mov_b32_e32 v154, v0
	v_mov_b32_e32 v155, v0
	v_mov_b32_e32 v156, v0
	v_mov_b32_e32 v157, v0
	v_mov_b32_e32 v158, v0
	v_mov_b32_e32 v159, v0
	v_mov_b32_e32 v160, v0
	v_mov_b32_e32 v161, v0
	v_mov_b32_e32 v32, v0
	v_mov_b32_e32 v33, v0
	v_mov_b32_e32 v34, v0
	v_mov_b32_e32 v35, v0
	v_mov_b32_e32 v36, v0
	v_mov_b32_e32 v37, v0
	v_mov_b32_e32 v38, v0
	v_mov_b32_e32 v39, v0
	v_mov_b32_e32 v40, v0
	v_mov_b32_e32 v41, v0
	v_mov_b32_e32 v42, v0
	v_mov_b32_e32 v43, v0
	v_mov_b32_e32 v44, v0
	v_mov_b32_e32 v45, v0
	v_mov_b32_e32 v46, v0
	v_mov_b32_e32 v47, v0
	v_mov_b32_e32 v48, v0
	v_mov_b32_e32 v49, v0
	v_mov_b32_e32 v50, v0
	v_mov_b32_e32 v51, v0
	v_mov_b32_e32 v56, v0
	v_mov_b32_e32 v57, v0
	v_mov_b32_e32 v58, v0
	v_mov_b32_e32 v59, v0
	v_mov_b32_e32 v98, v0
	v_mov_b32_e32 v99, v0
	v_mov_b32_e32 v100, v0
	v_mov_b32_e32 v101, v0
	v_mov_b32_e32 v102, v0
	v_mov_b32_e32 v103, v0
	v_mov_b32_e32 v104, v0
	v_mov_b32_e32 v105, v0
	v_mov_b32_e32 v162, v0
	v_mov_b32_e32 v163, v0
	v_mov_b32_e32 v164, v0
	v_mov_b32_e32 v165, v0
	v_mov_b32_e32 v166, v0
	v_mov_b32_e32 v167, v0
	v_mov_b32_e32 v168, v0
	v_mov_b32_e32 v169, v0
	v_mov_b32_e32 v170, v0
	v_mov_b32_e32 v171, v0
	v_mov_b32_e32 v172, v0
	v_mov_b32_e32 v173, v0
	v_mov_b32_e32 v174, v0
	v_mov_b32_e32 v175, v0
	v_mov_b32_e32 v176, v0
	v_mov_b32_e32 v177, v0
	v_mov_b32_e32 v178, v0
	v_mov_b32_e32 v179, v0
	v_mov_b32_e32 v180, v0
	v_mov_b32_e32 v181, v0
	v_mov_b32_e32 v182, v0
	v_mov_b32_e32 v183, v0
	v_mov_b32_e32 v184, v0
	v_mov_b32_e32 v185, v0
	v_mov_b32_e32 v186, v0
	v_mov_b32_e32 v187, v0
	v_mov_b32_e32 v188, v0
	v_mov_b32_e32 v189, v0
	v_mov_b32_e32 v190, v0
	v_mov_b32_e32 v191, v0
	v_mov_b32_e32 v192, v0
	v_mov_b32_e32 v193, v0
	s_andn2_b64 vcc, exec, s[0:1]
	s_cbranch_vccnz .LBB0_290
	s_branch .LBB0_291

; #define PG8_STAGE(bufoff, gbase, voff) do { _Pragma("unroll") for (int _i = 0; _i < 2; ++_i) \
;         __builtin_amdgcn_global_load_lds((const unsigned*)((const char*)(gbase) + (voff)[_i]), (PG8_LAS unsigned*)(lds + (bufoff) + ldsw + _i * 8192), 16, 0, 0); } while (0)
; #define PG8_LDA(dst, b, h) do { _Pragma("unroll") for (int m = 0; m < 4; ++m) _Pragma("unroll") for (int k = 0; k < 2; ++k) dst[m][k] = *(const PG8_LAS bf16x8*)(lds + PG8_SA(b, h) + aoff + m * 2048 + k * 1024); } while (0)
; #define PG8_LDB(dst, b, h) do { _Pragma("unroll") for (int n = 0; n < 2; ++n) _Pragma("unroll") for (int k = 0; k < 2; ++k) dst[n][k] = *(const PG8_LAS bf16x8*)(lds + PG8_SB(b, h) + boff + n * 2048 + k * 1024); } while (0)
; #define PG8_MMA(ai, bj, At, Bt) do { __builtin_amdgcn_s_setprio(1); _Pragma("unroll") for (int m = 0; m < 4; ++m) _Pragma("unroll") for (int n = 0; n < 2; ++n) _Pragma("unroll") for (int k = 0; k < 2; ++k) \
;         acc[ai][bj][m][n] = __builtin_amdgcn_mfma_f32_16x16x32_bf16(Bt[n][k], At[m][k], acc[ai][bj][m][n], 0, 0, 0); __builtin_amdgcn_s_setprio(0); } while (0)
; #define PG8_WAIT_V(n) asm volatile("s_waitcnt vmcnt(" #n ")" ::: "memory")
; #define PG8_WAIT_L(n) asm volatile("s_waitcnt lgkmcnt(" #n ")" ::: "memory")
; #define PG8_BAR __builtin_amdgcn_s_barrier()
; #define PG8_SCHED __builtin_amdgcn_sched_barrier(0)
; template <class Epi, class Sched, bool ALIGN_EPI = false, bool SP2 = false>
; __device__ __forceinline__ void gemm_phase(PG8_LAS unsigned char* lds, const Gemm g, const Sched& S, const Epi& E, const int tid) {
;     ...
;             PG8_LDB(B0, 0, 0); PG8_LDB(B1, 0, 1); PG8_SCHED; PG8_LDA(At, 0, 0); PG8_STAGE(PG8_SA(1, 1), a1 + hstep, voffA);
;             PG8_WAIT_V(8); PG8_WAIT_L(0); PG8_BAR; PG8_MMA(0, 0, At, B0); PG8_MMA(0, 1, At, B1); PG8_BAR; PG8_SCHED;
;             PG8_LDA(At, 0, 1); PG8_STAGE(PG8_SB(0, 0), b2, voffB); PG8_STAGE(PG8_SB(0, 1), b2 + hstep, voffB); PG8_STAGE(PG8_SA(0, 0), a2, voffA);
;             PG8_WAIT_V(8); PG8_WAIT_L(0); PG8_BAR; PG8_MMA(1, 0, At, B0); PG8_MMA(1, 1, At, B1); PG8_BAR; PG8_SCHED;
.LBB0_348:
	s_add_i32 s47, 0, 0x10000
	s_add_i32 s45, 0, 0x14000
	v_add_u32_e32 v8, s47, v141
	v_add_u32_e32 v9, s45, v141
	ds_read_b128 v[10:13], v8
	ds_read_b128 v[14:17], v8 offset:1024
	ds_read_b128 v[18:21], v8 offset:2048
	ds_read_b128 v[22:25], v8 offset:3072
	ds_read_b128 v[26:29], v9
	ds_read_b128 v[30:33], v9 offset:1024
	ds_read_b128 v[34:37], v9 offset:2048
	ds_read_b128 v[38:41], v9 offset:3072
	s_add_u32 s2, s14, 0x18080
	s_addc_u32 s3, s15, 0
	s_add_i32 s50, s23, 0xc000
	v_lshl_add_u64 v[62:63], s[2:3], 0, v[136:137]
	s_mov_b32 m0, s50
	ds_read_b128 v[0:3], v142
	ds_read_b128 v[4:7], v142 offset:1024
	ds_read_b128 v[42:45], v142 offset:2048
	ds_read_b128 v[46:49], v142 offset:3072
	ds_read_b128 v[50:53], v142 offset:4096
	ds_read_b128 v[54:57], v142 offset:5120
	ds_read_b128 v[58:61], v142 offset:6144
	ds_read_b128 v[66:69], v142 offset:7168
	global_load_lds_dwordx4 v[62:63], off
	v_lshl_add_u64 v[62:63], s[2:3], 0, v[132:133]
	s_add_i32 s2, s23, 0xe000
	s_mov_b32 m0, s2
	s_nop 0
	global_load_lds_dwordx4 v[62:63], off
	s_waitcnt vmcnt(8)
	s_waitcnt lgkmcnt(0)
	s_barrier
	s_setprio 1
	v_mfma_f32_16x16x32_bf16 v[70:73], v[10:13], v[0:3], 0
	v_mfma_f32_16x16x32_bf16 v[74:77], v[18:21], v[0:3], 0
	v_mfma_f32_16x16x32_bf16 v[78:81], v[10:13], v[42:45], 0
	v_mfma_f32_16x16x32_bf16 v[82:85], v[18:21], v[42:45], 0
	v_mfma_f32_16x16x32_bf16 v[86:89], v[10:13], v[50:53], 0
	v_mfma_f32_16x16x32_bf16 v[90:93], v[18:21], v[50:53], 0
	v_mfma_f32_16x16x32_bf16 v[94:97], v[10:13], v[58:61], 0
	v_mfma_f32_16x16x32_bf16 v[98:101], v[18:21], v[58:61], 0
	v_mfma_f32_16x16x32_bf16 v[70:73], v[14:17], v[4:7], v[70:73]
	v_mfma_f32_16x16x32_bf16 v[74:77], v[22:25], v[4:7], v[74:77]
	v_mfma_f32_16x16x32_bf16 v[78:81], v[14:17], v[46:49], v[78:81]
	v_mfma_f32_16x16x32_bf16 v[82:85], v[22:25], v[46:49], v[82:85]
	v_mfma_f32_16x16x32_bf16 v[86:89], v[14:17], v[54:57], v[86:89]
	v_mfma_f32_16x16x32_bf16 v[90:93], v[22:25], v[54:57], v[90:93]
	v_mfma_f32_16x16x32_bf16 v[94:97], v[14:17], v[66:69], v[94:97]
	v_mfma_f32_16x16x32_bf16 v[98:101], v[22:25], v[66:69], v[98:101]
	s_setprio 0
	s_setprio 1
	v_mfma_f32_16x16x32_bf16 v[102:105], v[26:29], v[0:3], 0
	v_mfma_f32_16x16x32_bf16 v[0:3], v[34:37], v[0:3], 0
	v_mfma_f32_16x16x32_bf16 v[106:109], v[38:41], v[4:7], v[0:3]
	v_mfma_f32_16x16x32_bf16 v[0:3], v[26:29], v[42:45], 0
	v_mfma_f32_16x16x32_bf16 v[110:113], v[30:33], v[46:49], v[0:3]
	v_mfma_f32_16x16x32_bf16 v[0:3], v[34:37], v[42:45], 0
	v_mfma_f32_16x16x32_bf16 v[42:45], v[38:41], v[46:49], v[0:3]
	v_mfma_f32_16x16x32_bf16 v[0:3], v[26:29], v[50:53], 0
	v_mfma_f32_16x16x32_bf16 v[46:49], v[30:33], v[54:57], v[0:3]
	v_mfma_f32_16x16x32_bf16 v[0:3], v[34:37], v[50:53], 0
	v_mfma_f32_16x16x32_bf16 v[50:53], v[38:41], v[54:57], v[0:3]
	v_mfma_f32_16x16x32_bf16 v[0:3], v[26:29], v[58:61], 0
	v_mfma_f32_16x16x32_bf16 v[54:57], v[30:33], v[66:69], v[0:3]
	v_mfma_f32_16x16x32_bf16 v[0:3], v[34:37], v[58:61], 0
	v_mfma_f32_16x16x32_bf16 v[102:105], v[30:33], v[4:7], v[102:105]
	v_mfma_f32_16x16x32_bf16 v[58:61], v[38:41], v[66:69], v[0:3]
	s_setprio 0
	s_barrier
	s_nop 3
	v_lshl_add_u64 v[0:1], s[16:17], 0, v[134:135]
	s_mov_b64 s[52:53], 0x100
	s_add_i32 s47, s47, s22
	v_lshl_add_u64 v[2:3], v[0:1], 0, s[52:53]
	s_mov_b32 m0, s47
	s_add_i32 s3, s47, 0x2000
	ds_read_b128 v[66:69], v142 offset:16384
	ds_read_b128 v[114:117], v142 offset:17408
	ds_read_b128 v[118:121], v142 offset:18432
	ds_read_b128 v[122:125], v142 offset:19456
	ds_read_b128 v[126:129], v142 offset:20480
	ds_read_b128 v[144:147], v142 offset:21504
	ds_read_b128 v[148:151], v142 offset:22528
	ds_read_b128 v[152:155], v142 offset:23552
	global_load_lds_dwordx4 v[2:3], off
	v_lshl_add_u64 v[2:3], s[16:17], 0, v[130:131]
	s_add_u32 s48, s16, 0x18100
	v_lshl_add_u64 v[4:5], v[2:3], 0, s[52:53]
	s_mov_b32 m0, s3
	s_addc_u32 s49, s17, 0
	s_add_i32 s45, s45, s22
	global_load_lds_dwordx4 v[4:5], off
	v_lshl_add_u64 v[4:5], s[48:49], 0, v[134:135]
	s_mov_b32 m0, s45
	s_add_i32 s46, s45, 0x2000
	global_load_lds_dwordx4 v[4:5], off
	v_lshl_add_u64 v[4:5], s[48:49], 0, v[130:131]
	s_mov_b32 m0, s46
	s_nop 0
	global_load_lds_dwordx4 v[4:5], off
	v_lshl_add_u64 v[4:5], s[14:15], 0, v[136:137]
	v_lshl_add_u64 v[6:7], v[4:5], 0, s[52:53]
	s_mov_b32 m0, s23
	s_nop 0
	global_load_lds_dwordx4 v[6:7], off
	v_lshl_add_u64 v[6:7], s[14:15], 0, v[132:133]
	v_lshl_add_u64 v[62:63], v[6:7], 0, s[52:53]
	s_mov_b32 m0, s24
	s_nop 0
	global_load_lds_dwordx4 v[62:63], off
	s_waitcnt vmcnt(8)
	s_waitcnt lgkmcnt(0)
	s_barrier
	s_setprio 1
	v_mfma_f32_16x16x32_bf16 v[156:159], v[10:13], v[66:69], 0
	v_mfma_f32_16x16x32_bf16 v[164:167], v[10:13], v[118:121], 0
	v_mfma_f32_16x16x32_bf16 v[172:175], v[10:13], v[126:129], 0
	v_mfma_f32_16x16x32_bf16 v[10:13], v[10:13], v[148:151], 0
	v_mfma_f32_16x16x32_bf16 v[156:159], v[14:17], v[114:117], v[156:159]
	v_mfma_f32_16x16x32_bf16 v[160:163], v[18:21], v[66:69], 0
	v_mfma_f32_16x16x32_bf16 v[164:167], v[14:17], v[122:125], v[164:167]
	v_mfma_f32_16x16x32_bf16 v[168:171], v[18:21], v[118:121], 0
	v_mfma_f32_16x16x32_bf16 v[172:175], v[14:17], v[144:147], v[172:175]
	v_mfma_f32_16x16x32_bf16 v[176:179], v[18:21], v[126:129], 0
	v_mfma_f32_16x16x32_bf16 v[12:15], v[14:17], v[152:155], v[10:13]
	v_mfma_f32_16x16x32_bf16 v[16:19], v[18:21], v[148:151], 0
	v_mfma_f32_16x16x32_bf16 v[16:19], v[22:25], v[152:155], v[16:19]
	v_mfma_f32_16x16x32_bf16 v[160:163], v[22:25], v[114:117], v[160:163]
	v_mfma_f32_16x16x32_bf16 v[168:171], v[22:25], v[122:125], v[168:171]
	v_mfma_f32_16x16x32_bf16 v[176:179], v[22:25], v[144:147], v[176:179]
	s_setprio 0
	s_setprio 1
	v_mfma_f32_16x16x32_bf16 v[20:23], v[26:29], v[66:69], 0
	v_mfma_f32_16x16x32_bf16 v[66:69], v[34:37], v[66:69], 0
	v_mfma_f32_16x16x32_bf16 v[20:23], v[30:33], v[114:117], v[20:23]
	v_mfma_f32_16x16x32_bf16 v[66:69], v[38:41], v[114:117], v[66:69]
	v_mfma_f32_16x16x32_bf16 v[114:117], v[26:29], v[118:121], 0
	v_mfma_f32_16x16x32_bf16 v[118:121], v[34:37], v[118:121], 0
	v_mfma_f32_16x16x32_bf16 v[114:117], v[30:33], v[122:125], v[114:117]
	v_mfma_f32_16x16x32_bf16 v[118:121], v[38:41], v[122:125], v[118:121]
	v_mfma_f32_16x16x32_bf16 v[122:125], v[26:29], v[126:129], 0
	v_mfma_f32_16x16x32_bf16 v[24:27], v[26:29], v[148:151], 0
	v_mfma_f32_16x16x32_bf16 v[122:125], v[30:33], v[144:147], v[122:125]
	v_mfma_f32_16x16x32_bf16 v[126:129], v[34:37], v[126:129], 0
	v_mfma_f32_16x16x32_bf16 v[24:27], v[30:33], v[152:155], v[24:27]
	v_mfma_f32_16x16x32_bf16 v[28:31], v[34:37], v[148:151], 0
	v_mfma_f32_16x16x32_bf16 v[126:129], v[38:41], v[144:147], v[126:129]
	v_mfma_f32_16x16x32_bf16 v[28:31], v[38:41], v[152:155], v[28:31]
	s_setprio 0
	s_barrier
; #define PG8_STAGE(bufoff, gbase, voff) do { _Pragma("unroll") for (int _i = 0; _i < 2; ++_i) \
;         __builtin_amdgcn_global_load_lds((const unsigned*)((const char*)(gbase) + (voff)[_i]), (PG8_LAS unsigned*)(lds + (bufoff) + ldsw + _i * 8192), 16, 0, 0); } while (0)
; #define PG8_LDA(dst, b, h) do { _Pragma("unroll") for (int m = 0; m < 4; ++m) _Pragma("unroll") for (int k = 0; k < 2; ++k) dst[m][k] = *(const PG8_LAS bf16x8*)(lds + PG8_SA(b, h) + aoff + m * 2048 + k * 1024); } while (0)
; #define PG8_LDB(dst, b, h) do { _Pragma("unroll") for (int n = 0; n < 2; ++n) _Pragma("unroll") for (int k = 0; k < 2; ++k) dst[n][k] = *(const PG8_LAS bf16x8*)(lds + PG8_SB(b, h) + boff + n * 2048 + k * 1024); } while (0)
; #define PG8_MMA(ai, bj, At, Bt) do { __builtin_amdgcn_s_setprio(1); _Pragma("unroll") for (int m = 0; m < 4; ++m) _Pragma("unroll") for (int n = 0; n < 2; ++n) _Pragma("unroll") for (int k = 0; k < 2; ++k) \
;         acc[ai][bj][m][n] = __builtin_amdgcn_mfma_f32_16x16x32_bf16(Bt[n][k], At[m][k], acc[ai][bj][m][n], 0, 0, 0); __builtin_amdgcn_s_setprio(0); } while (0)
; #define PG8_WAIT_V(n) asm volatile("s_waitcnt vmcnt(" #n ")" ::: "memory")
; #define PG8_WAIT_L(n) asm volatile("s_waitcnt lgkmcnt(" #n ")" ::: "memory")
; #define PG8_BAR __builtin_amdgcn_s_barrier()
; #define PG8_SCHED __builtin_amdgcn_sched_barrier(0)
; template <class Epi, class Sched, bool ALIGN_EPI = false, bool SP2 = false>
; __device__ __forceinline__ void gemm_phase(PG8_LAS unsigned char* lds, const Gemm g, const Sched& S, const Epi& E, const int tid) {
;     ...
;             PG8_LDB(B0, 1, 0); PG8_LDB(B1, 1, 1); PG8_SCHED; PG8_LDA(At, 1, 0); PG8_STAGE(PG8_SA(0, 1), a2 + hstep, voffA);
;             PG8_WAIT_V(8); PG8_WAIT_L(0); PG8_BAR; PG8_MMA(0, 0, At, B0); PG8_MMA(0, 1, At, B1); PG8_BAR; PG8_SCHED;
;             PG8_LDA(At, 1, 1); PG8_STAGE(PG8_SB(1, 0), b3, voffB); PG8_STAGE(PG8_SB(1, 1), b3 + hstep, voffB); PG8_STAGE(PG8_SA(1, 0), a3, voffA);
;             PG8_WAIT_V(8); PG8_WAIT_L(0); PG8_BAR; PG8_MMA(1, 0, At, B0); PG8_MMA(1, 1, At, B1); PG8_BAR; PG8_SCHED;
	s_add_i32 s52, 0, 0x18000
	s_add_i32 s51, 0, 0x1c000
	v_add_u32_e32 v10, s52, v141
	v_add_u32_e32 v11, s51, v141
	ds_read_b128 v[32:35], v10
	ds_read_b128 v[36:39], v10 offset:1024
	ds_read_b128 v[144:147], v10 offset:2048
	ds_read_b128 v[148:151], v10 offset:3072
	ds_read_b128 v[152:155], v11
	ds_read_b128 v[180:183], v11 offset:1024
	ds_read_b128 v[184:187], v11 offset:2048
	ds_read_b128 v[188:191], v11 offset:3072
	s_add_u32 s48, s14, 0x18100
	s_addc_u32 s49, s15, 0
	s_mov_b32 m0, s25
	v_lshl_add_u64 v[40:41], s[48:49], 0, v[136:137]
	ds_read_b128 v[192:195], v142 offset:32768
	ds_read_b128 v[196:199], v142 offset:33792
	ds_read_b128 v[214:217], v142 offset:34816
	ds_read_b128 v[218:221], v142 offset:35840
	ds_read_b128 v[222:225], v142 offset:36864
	ds_read_b128 v[226:229], v142 offset:37888
	ds_read_b128 v[248:251], v142 offset:38912
	ds_read_b128 v[206:209], v142 offset:39936
	global_load_lds_dwordx4 v[40:41], off
	v_lshl_add_u64 v[40:41], s[48:49], 0, v[132:133]
	s_mov_b32 m0, s26
	s_nop 0
	global_load_lds_dwordx4 v[40:41], off
	s_waitcnt vmcnt(8)
	s_waitcnt lgkmcnt(0)
	s_barrier
	s_setprio 1
	v_mfma_f32_16x16x32_bf16 v[70:73], v[32:35], v[192:195], v[70:73]
	v_mfma_f32_16x16x32_bf16 v[74:77], v[144:147], v[192:195], v[74:77]
	v_mfma_f32_16x16x32_bf16 v[78:81], v[32:35], v[214:217], v[78:81]
	v_mfma_f32_16x16x32_bf16 v[82:85], v[144:147], v[214:217], v[82:85]
	v_mfma_f32_16x16x32_bf16 v[86:89], v[32:35], v[222:225], v[86:89]
	v_mfma_f32_16x16x32_bf16 v[90:93], v[144:147], v[222:225], v[90:93]
	v_mfma_f32_16x16x32_bf16 v[94:97], v[32:35], v[248:251], v[94:97]
	v_mfma_f32_16x16x32_bf16 v[98:101], v[144:147], v[248:251], v[98:101]
	v_mfma_f32_16x16x32_bf16 v[70:73], v[36:39], v[196:199], v[70:73]
	v_mfma_f32_16x16x32_bf16 v[74:77], v[148:151], v[196:199], v[74:77]
	v_mfma_f32_16x16x32_bf16 v[78:81], v[36:39], v[218:221], v[78:81]
	v_mfma_f32_16x16x32_bf16 v[82:85], v[148:151], v[218:221], v[82:85]
	v_mfma_f32_16x16x32_bf16 v[86:89], v[36:39], v[226:229], v[86:89]
	v_mfma_f32_16x16x32_bf16 v[90:93], v[148:151], v[226:229], v[90:93]
	v_mfma_f32_16x16x32_bf16 v[94:97], v[36:39], v[206:209], v[94:97]
	v_mfma_f32_16x16x32_bf16 v[98:101], v[148:151], v[206:209], v[98:101]
	s_setprio 0
	s_setprio 1
	v_mfma_f32_16x16x32_bf16 v[102:105], v[152:155], v[192:195], v[102:105]
	v_mfma_f32_16x16x32_bf16 v[106:109], v[184:187], v[192:195], v[106:109]
	v_mfma_f32_16x16x32_bf16 v[110:113], v[152:155], v[214:217], v[110:113]
	v_mfma_f32_16x16x32_bf16 v[40:43], v[184:187], v[214:217], v[42:45]
	v_mfma_f32_16x16x32_bf16 v[44:47], v[152:155], v[222:225], v[46:49]
	v_mfma_f32_16x16x32_bf16 v[48:51], v[184:187], v[222:225], v[50:53]
	v_mfma_f32_16x16x32_bf16 v[52:55], v[152:155], v[248:251], v[54:57]
	v_mfma_f32_16x16x32_bf16 v[56:59], v[184:187], v[248:251], v[58:61]
	v_mfma_f32_16x16x32_bf16 v[102:105], v[180:183], v[196:199], v[102:105]
	v_mfma_f32_16x16x32_bf16 v[106:109], v[188:191], v[196:199], v[106:109]
	v_mfma_f32_16x16x32_bf16 v[110:113], v[180:183], v[218:221], v[110:113]
	v_mfma_f32_16x16x32_bf16 v[40:43], v[188:191], v[218:221], v[40:43]
	v_mfma_f32_16x16x32_bf16 v[44:47], v[180:183], v[226:229], v[44:47]
	v_mfma_f32_16x16x32_bf16 v[48:51], v[188:191], v[226:229], v[48:51]
	v_mfma_f32_16x16x32_bf16 v[52:55], v[180:183], v[206:209], v[52:55]
	v_mfma_f32_16x16x32_bf16 v[56:59], v[188:191], v[206:209], v[56:59]
	s_setprio 0
	s_barrier
	s_add_i32 s52, s52, s22
	s_mov_b64 s[56:57], 0x180
	s_add_i32 s48, s52, 0x2000
	v_lshl_add_u64 v[138:139], v[0:1], 0, s[56:57]
	s_mov_b32 m0, s52
	s_add_u32 s54, s16, 0x18180
	ds_read_b128 v[60:63], v142 offset:49152
	ds_read_b128 v[192:195], v142 offset:50176
	ds_read_b128 v[196:199], v142 offset:51200
	ds_read_b128 v[206:209], v142 offset:52224
	ds_read_b128 v[214:217], v142 offset:53248
	ds_read_b128 v[218:221], v142 offset:54272
	ds_read_b128 v[222:225], v142 offset:55296
	ds_read_b128 v[226:229], v142 offset:56320
	global_load_lds_dwordx4 v[138:139], off
	v_lshl_add_u64 v[138:139], v[2:3], 0, s[56:57]
	s_mov_b32 m0, s48
	s_addc_u32 s55, s17, 0
	s_add_i32 s49, s51, s22
	global_load_lds_dwordx4 v[138:139], off
	v_lshl_add_u64 v[138:139], s[54:55], 0, v[134:135]
	s_mov_b32 m0, s49
	s_add_i32 s51, s49, 0x2000
	global_load_lds_dwordx4 v[138:139], off
	v_lshl_add_u64 v[138:139], s[54:55], 0, v[130:131]
	s_mov_b32 m0, s51
	s_nop 0
	global_load_lds_dwordx4 v[138:139], off
	v_lshl_add_u64 v[138:139], v[4:5], 0, s[56:57]
	s_mov_b32 m0, s28
	s_nop 0
	global_load_lds_dwordx4 v[138:139], off
	v_lshl_add_u64 v[138:139], v[6:7], 0, s[56:57]
	s_mov_b32 m0, s29
	s_nop 0
	global_load_lds_dwordx4 v[138:139], off
	s_waitcnt vmcnt(8)
	s_waitcnt lgkmcnt(0)
	s_barrier
; #define PG8_STAGE(bufoff, gbase, voff) do { _Pragma("unroll") for (int _i = 0; _i < 2; ++_i) \
;         __builtin_amdgcn_global_load_lds((const unsigned*)((const char*)(gbase) + (voff)[_i]), (PG8_LAS unsigned*)(lds + (bufoff) + ldsw + _i * 8192), 16, 0, 0); } while (0)
; #define PG8_LDA(dst, b, h) do { _Pragma("unroll") for (int m = 0; m < 4; ++m) _Pragma("unroll") for (int k = 0; k < 2; ++k) dst[m][k] = *(const PG8_LAS bf16x8*)(lds + PG8_SA(b, h) + aoff + m * 2048 + k * 1024); } while (0)
; #define PG8_LDB(dst, b, h) do { _Pragma("unroll") for (int n = 0; n < 2; ++n) _Pragma("unroll") for (int k = 0; k < 2; ++k) dst[n][k] = *(const PG8_LAS bf16x8*)(lds + PG8_SB(b, h) + boff + n * 2048 + k * 1024); } while (0)
; #define PG8_MMA(ai, bj, At, Bt) do { __builtin_amdgcn_s_setprio(1); _Pragma("unroll") for (int m = 0; m < 4; ++m) _Pragma("unroll") for (int n = 0; n < 2; ++n) _Pragma("unroll") for (int k = 0; k < 2; ++k) \
;         acc[ai][bj][m][n] = __builtin_amdgcn_mfma_f32_16x16x32_bf16(Bt[n][k], At[m][k], acc[ai][bj][m][n], 0, 0, 0); __builtin_amdgcn_s_setprio(0); } while (0)
; #define PG8_WAIT_V(n) asm volatile("s_waitcnt vmcnt(" #n ")" ::: "memory")
; #define PG8_WAIT_L(n) asm volatile("s_waitcnt lgkmcnt(" #n ")" ::: "memory")
; #define PG8_BAR __builtin_amdgcn_s_barrier()
; #define PG8_SCHED __builtin_amdgcn_sched_barrier(0)
; template <class Epi, class Sched, bool ALIGN_EPI = false, bool SP2 = false>
; __device__ __forceinline__ void gemm_phase(PG8_LAS unsigned char* lds, const Gemm g, const Sched& S, const Epi& E, const int tid) {
;     ...
;             PG8_LDB(B0, 0, 0); PG8_LDB(B1, 0, 1); PG8_SCHED; PG8_LDA(At, 0, 0); PG8_STAGE(PG8_SA(1, 1), a1 + hstep, voffA);
;             PG8_WAIT_V(8); PG8_WAIT_L(0); PG8_BAR; PG8_MMA(0, 0, At, B0); PG8_MMA(0, 1, At, B1); PG8_BAR; PG8_SCHED;
;     ...
;             PG8_WAIT_V(8); PG8_WAIT_L(0); PG8_BAR; PG8_MMA(1, 0, At, B0); PG8_MMA(1, 1, At, B1); PG8_BAR; PG8_SCHED;
	s_setprio 1
	v_mfma_f32_16x16x32_bf16 v[12:15], v[32:35], v[222:225], v[12:15]
	v_mfma_f32_16x16x32_bf16 v[16:19], v[144:147], v[222:225], v[16:19]
	v_mfma_f32_16x16x32_bf16 v[156:159], v[32:35], v[60:63], v[156:159]
	v_mfma_f32_16x16x32_bf16 v[160:163], v[144:147], v[60:63], v[160:163]
	v_mfma_f32_16x16x32_bf16 v[164:167], v[32:35], v[196:199], v[164:167]
	v_mfma_f32_16x16x32_bf16 v[168:171], v[144:147], v[196:199], v[168:171]
	v_mfma_f32_16x16x32_bf16 v[172:175], v[32:35], v[214:217], v[172:175]
	v_mfma_f32_16x16x32_bf16 v[176:179], v[144:147], v[214:217], v[176:179]
	v_mfma_f32_16x16x32_bf16 v[12:15], v[36:39], v[226:229], v[12:15]
	v_mfma_f32_16x16x32_bf16 v[16:19], v[148:151], v[226:229], v[16:19]
	v_mfma_f32_16x16x32_bf16 v[156:159], v[36:39], v[192:195], v[156:159]
	v_mfma_f32_16x16x32_bf16 v[160:163], v[148:151], v[192:195], v[160:163]
	v_mfma_f32_16x16x32_bf16 v[164:167], v[36:39], v[206:209], v[164:167]
	v_mfma_f32_16x16x32_bf16 v[168:171], v[148:151], v[206:209], v[168:171]
	v_mfma_f32_16x16x32_bf16 v[172:175], v[36:39], v[218:221], v[172:175]
	v_mfma_f32_16x16x32_bf16 v[176:179], v[148:151], v[218:221], v[176:179]
	s_setprio 0
	s_setprio 1
	v_mfma_f32_16x16x32_bf16 v[20:23], v[152:155], v[60:63], v[20:23]
	v_mfma_f32_16x16x32_bf16 v[32:35], v[184:187], v[60:63], v[66:69]
	v_mfma_f32_16x16x32_bf16 v[36:39], v[152:155], v[196:199], v[114:117]
	v_mfma_f32_16x16x32_bf16 v[60:63], v[184:187], v[196:199], v[118:121]
	v_mfma_f32_16x16x32_bf16 v[66:69], v[152:155], v[214:217], v[122:125]
	v_mfma_f32_16x16x32_bf16 v[114:117], v[184:187], v[214:217], v[126:129]
	v_mfma_f32_16x16x32_bf16 v[24:27], v[152:155], v[222:225], v[24:27]
	v_mfma_f32_16x16x32_bf16 v[28:31], v[184:187], v[222:225], v[28:31]
	v_mfma_f32_16x16x32_bf16 v[20:23], v[180:183], v[192:195], v[20:23]
	v_mfma_f32_16x16x32_bf16 v[32:35], v[188:191], v[192:195], v[32:35]
	v_mfma_f32_16x16x32_bf16 v[36:39], v[180:183], v[206:209], v[36:39]
	v_mfma_f32_16x16x32_bf16 v[60:63], v[188:191], v[206:209], v[60:63]
	v_mfma_f32_16x16x32_bf16 v[66:69], v[180:183], v[218:221], v[66:69]
	v_mfma_f32_16x16x32_bf16 v[114:117], v[188:191], v[218:221], v[114:117]
	v_mfma_f32_16x16x32_bf16 v[24:27], v[180:183], v[226:229], v[24:27]
	v_mfma_f32_16x16x32_bf16 v[28:31], v[188:191], v[226:229], v[28:31]
	s_setprio 0
	s_barrier
	ds_read_b128 v[118:121], v8
	ds_read_b128 v[122:125], v8 offset:1024
	ds_read_b128 v[126:129], v8 offset:2048
	ds_read_b128 v[144:147], v8 offset:3072
	ds_read_b128 v[148:151], v9
	ds_read_b128 v[152:155], v9 offset:1024
	ds_read_b128 v[180:183], v9 offset:2048
	ds_read_b128 v[184:187], v9 offset:3072
	s_add_u32 s54, s14, 0x18180
	s_addc_u32 s55, s15, 0
	s_mov_b32 m0, s50
	v_lshl_add_u64 v[138:139], s[54:55], 0, v[136:137]
	ds_read_b128 v[188:191], v142
	ds_read_b128 v[192:195], v142 offset:1024
	ds_read_b128 v[196:199], v142 offset:2048
	ds_read_b128 v[206:209], v142 offset:3072
	ds_read_b128 v[214:217], v142 offset:4096
	ds_read_b128 v[218:221], v142 offset:5120
	ds_read_b128 v[222:225], v142 offset:6144
	ds_read_b128 v[226:229], v142 offset:7168
	global_load_lds_dwordx4 v[138:139], off
	v_lshl_add_u64 v[138:139], s[54:55], 0, v[132:133]
	s_mov_b32 m0, s2
	s_nop 0
	global_load_lds_dwordx4 v[138:139], off
	s_waitcnt vmcnt(8)
	s_waitcnt lgkmcnt(0)
	s_barrier
	s_setprio 1
	v_mfma_f32_16x16x32_bf16 v[70:73], v[118:121], v[188:191], v[70:73]
	v_mfma_f32_16x16x32_bf16 v[74:77], v[126:129], v[188:191], v[74:77]
	v_mfma_f32_16x16x32_bf16 v[78:81], v[118:121], v[196:199], v[78:81]
	v_mfma_f32_16x16x32_bf16 v[82:85], v[126:129], v[196:199], v[82:85]
	v_mfma_f32_16x16x32_bf16 v[86:89], v[118:121], v[214:217], v[86:89]
	v_mfma_f32_16x16x32_bf16 v[90:93], v[126:129], v[214:217], v[90:93]
	v_mfma_f32_16x16x32_bf16 v[94:97], v[118:121], v[222:225], v[94:97]
	v_mfma_f32_16x16x32_bf16 v[98:101], v[126:129], v[222:225], v[98:101]
	v_mfma_f32_16x16x32_bf16 v[70:73], v[122:125], v[192:195], v[70:73]
	v_mfma_f32_16x16x32_bf16 v[74:77], v[144:147], v[192:195], v[74:77]
	v_mfma_f32_16x16x32_bf16 v[78:81], v[122:125], v[206:209], v[78:81]
	v_mfma_f32_16x16x32_bf16 v[82:85], v[144:147], v[206:209], v[82:85]
	v_mfma_f32_16x16x32_bf16 v[86:89], v[122:125], v[218:221], v[86:89]
	v_mfma_f32_16x16x32_bf16 v[90:93], v[144:147], v[218:221], v[90:93]
	v_mfma_f32_16x16x32_bf16 v[94:97], v[122:125], v[226:229], v[94:97]
	v_mfma_f32_16x16x32_bf16 v[98:101], v[144:147], v[226:229], v[98:101]
	s_setprio 0
	s_setprio 1
	v_mfma_f32_16x16x32_bf16 v[102:105], v[148:151], v[188:191], v[102:105]
	v_mfma_f32_16x16x32_bf16 v[106:109], v[180:183], v[188:191], v[106:109]
	v_mfma_f32_16x16x32_bf16 v[110:113], v[148:151], v[196:199], v[110:113]
	v_mfma_f32_16x16x32_bf16 v[40:43], v[180:183], v[196:199], v[40:43]
	v_mfma_f32_16x16x32_bf16 v[44:47], v[148:151], v[214:217], v[44:47]
	v_mfma_f32_16x16x32_bf16 v[48:51], v[180:183], v[214:217], v[48:51]
	v_mfma_f32_16x16x32_bf16 v[52:55], v[148:151], v[222:225], v[52:55]
	v_mfma_f32_16x16x32_bf16 v[56:59], v[180:183], v[222:225], v[56:59]
	v_mfma_f32_16x16x32_bf16 v[102:105], v[152:155], v[192:195], v[102:105]
	v_mfma_f32_16x16x32_bf16 v[106:109], v[184:187], v[192:195], v[106:109]
	v_mfma_f32_16x16x32_bf16 v[110:113], v[152:155], v[206:209], v[110:113]
	v_mfma_f32_16x16x32_bf16 v[40:43], v[184:187], v[206:209], v[40:43]
	v_mfma_f32_16x16x32_bf16 v[44:47], v[152:155], v[218:221], v[44:47]
	v_mfma_f32_16x16x32_bf16 v[48:51], v[184:187], v[218:221], v[48:51]
	v_mfma_f32_16x16x32_bf16 v[52:55], v[152:155], v[226:229], v[52:55]
	v_mfma_f32_16x16x32_bf16 v[56:59], v[184:187], v[226:229], v[56:59]
	s_setprio 0
	s_barrier
; #define PG8_STAGE(bufoff, gbase, voff) do { _Pragma("unroll") for (int _i = 0; _i < 2; ++_i) \
;         __builtin_amdgcn_global_load_lds((const unsigned*)((const char*)(gbase) + (voff)[_i]), (PG8_LAS unsigned*)(lds + (bufoff) + ldsw + _i * 8192), 16, 0, 0); } while (0)
; #define PG8_LDA(dst, b, h) do { _Pragma("unroll") for (int m = 0; m < 4; ++m) _Pragma("unroll") for (int k = 0; k < 2; ++k) dst[m][k] = *(const PG8_LAS bf16x8*)(lds + PG8_SA(b, h) + aoff + m * 2048 + k * 1024); } while (0)
; #define PG8_LDB(dst, b, h) do { _Pragma("unroll") for (int n = 0; n < 2; ++n) _Pragma("unroll") for (int k = 0; k < 2; ++k) dst[n][k] = *(const PG8_LAS bf16x8*)(lds + PG8_SB(b, h) + boff + n * 2048 + k * 1024); } while (0)
; #define PG8_MMA(ai, bj, At, Bt) do { __builtin_amdgcn_s_setprio(1); _Pragma("unroll") for (int m = 0; m < 4; ++m) _Pragma("unroll") for (int n = 0; n < 2; ++n) _Pragma("unroll") for (int k = 0; k < 2; ++k) \
;         acc[ai][bj][m][n] = __builtin_amdgcn_mfma_f32_16x16x32_bf16(Bt[n][k], At[m][k], acc[ai][bj][m][n], 0, 0, 0); __builtin_amdgcn_s_setprio(0); } while (0)
; #define PG8_WAIT_V(n) asm volatile("s_waitcnt vmcnt(" #n ")" ::: "memory")
; #define PG8_WAIT_L(n) asm volatile("s_waitcnt lgkmcnt(" #n ")" ::: "memory")
; #define PG8_BAR __builtin_amdgcn_s_barrier()
; #define PG8_SCHED __builtin_amdgcn_sched_barrier(0)
; template <class Epi, class Sched, bool ALIGN_EPI = false, bool SP2 = false>
; __device__ __forceinline__ void gemm_phase(PG8_LAS unsigned char* lds, const Gemm g, const Sched& S, const Epi& E, const int tid) {
;     ...
;             PG8_LDA(At, 0, 1); PG8_STAGE(PG8_SB(0, 0), b2, voffB); PG8_STAGE(PG8_SB(0, 1), b2 + hstep, voffB); PG8_STAGE(PG8_SA(0, 0), a2, voffA);
;             PG8_WAIT_V(8); PG8_WAIT_L(0); PG8_BAR; PG8_MMA(1, 0, At, B0); PG8_MMA(1, 1, At, B1); PG8_BAR; PG8_SCHED;
;             PG8_LDB(B0, 1, 0); PG8_LDB(B1, 1, 1); PG8_SCHED; PG8_LDA(At, 1, 0); PG8_STAGE(PG8_SA(0, 1), a2 + hstep, voffA);
	s_mov_b64 s[56:57], 0x200
	s_mov_b32 m0, s47
	v_lshl_add_u64 v[138:139], v[0:1], 0, s[56:57]
	s_add_u32 s54, s16, 0x18200
	ds_read_b128 v[188:191], v142 offset:16384
	ds_read_b128 v[192:195], v142 offset:17408
	ds_read_b128 v[196:199], v142 offset:18432
	ds_read_b128 v[206:209], v142 offset:19456
	ds_read_b128 v[214:217], v142 offset:20480
	ds_read_b128 v[218:221], v142 offset:21504
	ds_read_b128 v[222:225], v142 offset:22528
	ds_read_b128 v[226:229], v142 offset:23552
	global_load_lds_dwordx4 v[138:139], off
	v_lshl_add_u64 v[138:139], v[2:3], 0, s[56:57]
	s_mov_b32 m0, s3
	s_addc_u32 s55, s17, 0
	global_load_lds_dwordx4 v[138:139], off
	v_lshl_add_u64 v[138:139], s[54:55], 0, v[134:135]
	s_mov_b32 m0, s45
	s_nop 0
	global_load_lds_dwordx4 v[138:139], off
	v_lshl_add_u64 v[138:139], s[54:55], 0, v[130:131]
	s_mov_b32 m0, s46
	s_nop 0
	global_load_lds_dwordx4 v[138:139], off
	v_lshl_add_u64 v[138:139], v[4:5], 0, s[56:57]
	s_mov_b32 m0, s23
	s_nop 0
	global_load_lds_dwordx4 v[138:139], off
	v_lshl_add_u64 v[138:139], v[6:7], 0, s[56:57]
	s_mov_b32 m0, s24
	s_nop 0
	global_load_lds_dwordx4 v[138:139], off
	s_waitcnt vmcnt(8)
	s_waitcnt lgkmcnt(0)
	s_barrier
	s_setprio 1
	v_mfma_f32_16x16x32_bf16 v[12:15], v[118:121], v[222:225], v[12:15]
	v_mfma_f32_16x16x32_bf16 v[16:19], v[126:129], v[222:225], v[16:19]
	v_mfma_f32_16x16x32_bf16 v[156:159], v[118:121], v[188:191], v[156:159]
	v_mfma_f32_16x16x32_bf16 v[160:163], v[126:129], v[188:191], v[160:163]
	v_mfma_f32_16x16x32_bf16 v[164:167], v[118:121], v[196:199], v[164:167]
	v_mfma_f32_16x16x32_bf16 v[168:171], v[126:129], v[196:199], v[168:171]
	v_mfma_f32_16x16x32_bf16 v[172:175], v[118:121], v[214:217], v[172:175]
	v_mfma_f32_16x16x32_bf16 v[176:179], v[126:129], v[214:217], v[176:179]
	v_mfma_f32_16x16x32_bf16 v[12:15], v[122:125], v[226:229], v[12:15]
	v_mfma_f32_16x16x32_bf16 v[16:19], v[144:147], v[226:229], v[16:19]
	v_mfma_f32_16x16x32_bf16 v[156:159], v[122:125], v[192:195], v[156:159]
	v_mfma_f32_16x16x32_bf16 v[160:163], v[144:147], v[192:195], v[160:163]
	v_mfma_f32_16x16x32_bf16 v[164:167], v[122:125], v[206:209], v[164:167]
	v_mfma_f32_16x16x32_bf16 v[168:171], v[144:147], v[206:209], v[168:171]
	v_mfma_f32_16x16x32_bf16 v[172:175], v[122:125], v[218:221], v[172:175]
	v_mfma_f32_16x16x32_bf16 v[176:179], v[144:147], v[218:221], v[176:179]
	s_setprio 0
	s_setprio 1
	v_mfma_f32_16x16x32_bf16 v[20:23], v[148:151], v[188:191], v[20:23]
	v_mfma_f32_16x16x32_bf16 v[32:35], v[180:183], v[188:191], v[32:35]
	v_mfma_f32_16x16x32_bf16 v[36:39], v[148:151], v[196:199], v[36:39]
	v_mfma_f32_16x16x32_bf16 v[60:63], v[180:183], v[196:199], v[60:63]
	v_mfma_f32_16x16x32_bf16 v[66:69], v[148:151], v[214:217], v[66:69]
	v_mfma_f32_16x16x32_bf16 v[114:117], v[180:183], v[214:217], v[114:117]
	v_mfma_f32_16x16x32_bf16 v[24:27], v[148:151], v[222:225], v[24:27]
	v_mfma_f32_16x16x32_bf16 v[28:31], v[180:183], v[222:225], v[28:31]
	v_mfma_f32_16x16x32_bf16 v[20:23], v[152:155], v[192:195], v[20:23]
	v_mfma_f32_16x16x32_bf16 v[32:35], v[184:187], v[192:195], v[32:35]
	v_mfma_f32_16x16x32_bf16 v[36:39], v[152:155], v[206:209], v[36:39]
	v_mfma_f32_16x16x32_bf16 v[60:63], v[184:187], v[206:209], v[60:63]
	v_mfma_f32_16x16x32_bf16 v[66:69], v[152:155], v[218:221], v[66:69]
	v_mfma_f32_16x16x32_bf16 v[114:117], v[184:187], v[218:221], v[114:117]
	v_mfma_f32_16x16x32_bf16 v[24:27], v[152:155], v[226:229], v[24:27]
	v_mfma_f32_16x16x32_bf16 v[28:31], v[184:187], v[226:229], v[28:31]
	s_setprio 0
	s_barrier
	ds_read_b128 v[118:121], v10
	ds_read_b128 v[122:125], v10 offset:1024
	ds_read_b128 v[126:129], v10 offset:2048
	ds_read_b128 v[144:147], v10 offset:3072
	ds_read_b128 v[148:151], v11
	ds_read_b128 v[152:155], v11 offset:1024
	ds_read_b128 v[180:183], v11 offset:2048
	ds_read_b128 v[184:187], v11 offset:3072
	s_add_u32 s54, s14, 0x18200
	s_addc_u32 s55, s15, 0
	s_mov_b32 m0, s25
	v_lshl_add_u64 v[138:139], s[54:55], 0, v[136:137]
	ds_read_b128 v[188:191], v142 offset:32768
	ds_read_b128 v[192:195], v142 offset:33792
	ds_read_b128 v[196:199], v142 offset:34816
	ds_read_b128 v[206:209], v142 offset:35840
	ds_read_b128 v[214:217], v142 offset:36864
	ds_read_b128 v[218:221], v142 offset:37888
	ds_read_b128 v[222:225], v142 offset:38912
	ds_read_b128 v[226:229], v142 offset:39936
	global_load_lds_dwordx4 v[138:139], off
	v_lshl_add_u64 v[138:139], s[54:55], 0, v[132:133]
	s_mov_b32 m0, s26
	s_nop 0
	global_load_lds_dwordx4 v[138:139], off
	s_waitcnt vmcnt(8)
	s_waitcnt lgkmcnt(0)
	s_barrier
; #define PG8_STAGE(bufoff, gbase, voff) do { _Pragma("unroll") for (int _i = 0; _i < 2; ++_i) \
;         __builtin_amdgcn_global_load_lds((const unsigned*)((const char*)(gbase) + (voff)[_i]), (PG8_LAS unsigned*)(lds + (bufoff) + ldsw + _i * 8192), 16, 0, 0); } while (0)
; #define PG8_LDA(dst, b, h) do { _Pragma("unroll") for (int m = 0; m < 4; ++m) _Pragma("unroll") for (int k = 0; k < 2; ++k) dst[m][k] = *(const PG8_LAS bf16x8*)(lds + PG8_SA(b, h) + aoff + m * 2048 + k * 1024); } while (0)
; #define PG8_MMA(ai, bj, At, Bt) do { __builtin_amdgcn_s_setprio(1); _Pragma("unroll") for (int m = 0; m < 4; ++m) _Pragma("unroll") for (int n = 0; n < 2; ++n) _Pragma("unroll") for (int k = 0; k < 2; ++k) \
;         acc[ai][bj][m][n] = __builtin_amdgcn_mfma_f32_16x16x32_bf16(Bt[n][k], At[m][k], acc[ai][bj][m][n], 0, 0, 0); __builtin_amdgcn_s_setprio(0); } while (0)
; #define PG8_WAIT_V(n) asm volatile("s_waitcnt vmcnt(" #n ")" ::: "memory")
; #define PG8_WAIT_L(n) asm volatile("s_waitcnt lgkmcnt(" #n ")" ::: "memory")
; #define PG8_BAR __builtin_amdgcn_s_barrier()
; #define PG8_SCHED __builtin_amdgcn_sched_barrier(0)
; template <class Epi, class Sched, bool ALIGN_EPI = false, bool SP2 = false>
; __device__ __forceinline__ void gemm_phase(PG8_LAS unsigned char* lds, const Gemm g, const Sched& S, const Epi& E, const int tid) {
;     ...
;             PG8_WAIT_V(8); PG8_WAIT_L(0); PG8_BAR; PG8_MMA(0, 0, At, B0); PG8_MMA(0, 1, At, B1); PG8_BAR; PG8_SCHED;
;             PG8_LDA(At, 1, 1); PG8_STAGE(PG8_SB(1, 0), b3, voffB); PG8_STAGE(PG8_SB(1, 1), b3 + hstep, voffB); PG8_STAGE(PG8_SA(1, 0), a3, voffA);
;             PG8_WAIT_V(8); PG8_WAIT_L(0); PG8_BAR; PG8_MMA(1, 0, At, B0); PG8_MMA(1, 1, At, B1); PG8_BAR; PG8_SCHED;
	s_setprio 1
	v_mfma_f32_16x16x32_bf16 v[70:73], v[118:121], v[188:191], v[70:73]
	v_mfma_f32_16x16x32_bf16 v[74:77], v[126:129], v[188:191], v[74:77]
	v_mfma_f32_16x16x32_bf16 v[78:81], v[118:121], v[196:199], v[78:81]
	v_mfma_f32_16x16x32_bf16 v[82:85], v[126:129], v[196:199], v[82:85]
	v_mfma_f32_16x16x32_bf16 v[86:89], v[118:121], v[214:217], v[86:89]
	v_mfma_f32_16x16x32_bf16 v[90:93], v[126:129], v[214:217], v[90:93]
	v_mfma_f32_16x16x32_bf16 v[94:97], v[118:121], v[222:225], v[94:97]
	v_mfma_f32_16x16x32_bf16 v[98:101], v[126:129], v[222:225], v[98:101]
	v_mfma_f32_16x16x32_bf16 v[70:73], v[122:125], v[192:195], v[70:73]
	v_mfma_f32_16x16x32_bf16 v[74:77], v[144:147], v[192:195], v[74:77]
	v_mfma_f32_16x16x32_bf16 v[78:81], v[122:125], v[206:209], v[78:81]
	v_mfma_f32_16x16x32_bf16 v[82:85], v[144:147], v[206:209], v[82:85]
	v_mfma_f32_16x16x32_bf16 v[86:89], v[122:125], v[218:221], v[86:89]
	v_mfma_f32_16x16x32_bf16 v[90:93], v[144:147], v[218:221], v[90:93]
	v_mfma_f32_16x16x32_bf16 v[94:97], v[122:125], v[226:229], v[94:97]
	v_mfma_f32_16x16x32_bf16 v[98:101], v[144:147], v[226:229], v[98:101]
	s_setprio 0
	s_setprio 1
	v_mfma_f32_16x16x32_bf16 v[102:105], v[148:151], v[188:191], v[102:105]
	v_mfma_f32_16x16x32_bf16 v[106:109], v[180:183], v[188:191], v[106:109]
	v_mfma_f32_16x16x32_bf16 v[110:113], v[148:151], v[196:199], v[110:113]
	v_mfma_f32_16x16x32_bf16 v[40:43], v[180:183], v[196:199], v[40:43]
	v_mfma_f32_16x16x32_bf16 v[44:47], v[148:151], v[214:217], v[44:47]
	v_mfma_f32_16x16x32_bf16 v[48:51], v[180:183], v[214:217], v[48:51]
	v_mfma_f32_16x16x32_bf16 v[52:55], v[148:151], v[222:225], v[52:55]
	v_mfma_f32_16x16x32_bf16 v[56:59], v[180:183], v[222:225], v[56:59]
	v_mfma_f32_16x16x32_bf16 v[102:105], v[152:155], v[192:195], v[102:105]
	v_mfma_f32_16x16x32_bf16 v[106:109], v[184:187], v[192:195], v[106:109]
	v_mfma_f32_16x16x32_bf16 v[110:113], v[152:155], v[206:209], v[110:113]
	v_mfma_f32_16x16x32_bf16 v[40:43], v[184:187], v[206:209], v[40:43]
	v_mfma_f32_16x16x32_bf16 v[44:47], v[152:155], v[218:221], v[44:47]
	v_mfma_f32_16x16x32_bf16 v[48:51], v[184:187], v[218:221], v[48:51]
	v_mfma_f32_16x16x32_bf16 v[52:55], v[152:155], v[226:229], v[52:55]
	v_mfma_f32_16x16x32_bf16 v[56:59], v[184:187], v[226:229], v[56:59]
	s_setprio 0
	s_barrier
	s_mov_b64 s[54:55], 0x280
	s_mov_b32 m0, s52
	v_lshl_add_u64 v[0:1], v[0:1], 0, s[54:55]
	s_add_u32 s16, s16, 0x18280
	ds_read_b128 v[188:191], v142 offset:49152
	ds_read_b128 v[192:195], v142 offset:50176
	ds_read_b128 v[196:199], v142 offset:51200
	ds_read_b128 v[206:209], v142 offset:52224
	ds_read_b128 v[214:217], v142 offset:53248
	ds_read_b128 v[218:221], v142 offset:54272
	ds_read_b128 v[222:225], v142 offset:55296
	ds_read_b128 v[226:229], v142 offset:56320
	global_load_lds_dwordx4 v[0:1], off
	v_lshl_add_u64 v[0:1], v[2:3], 0, s[54:55]
	s_mov_b32 m0, s48
	s_addc_u32 s17, s17, 0
	global_load_lds_dwordx4 v[0:1], off
	v_lshl_add_u64 v[0:1], s[16:17], 0, v[134:135]
	s_mov_b32 m0, s49
	s_nop 0
	global_load_lds_dwordx4 v[0:1], off
	v_lshl_add_u64 v[0:1], s[16:17], 0, v[130:131]
	s_mov_b32 m0, s51
	s_nop 0
	global_load_lds_dwordx4 v[0:1], off
	v_lshl_add_u64 v[0:1], v[4:5], 0, s[54:55]
	s_mov_b32 m0, s28
	s_nop 0
	global_load_lds_dwordx4 v[0:1], off
	v_lshl_add_u64 v[0:1], v[6:7], 0, s[54:55]
	s_mov_b32 m0, s29
	s_nop 0
	global_load_lds_dwordx4 v[0:1], off
	s_waitcnt vmcnt(8)
	s_waitcnt lgkmcnt(0)
	s_barrier
	s_setprio 1
	v_mfma_f32_16x16x32_bf16 v[0:3], v[118:121], v[188:191], v[156:159]
	v_mfma_f32_16x16x32_bf16 v[4:7], v[126:129], v[188:191], v[160:163]
	v_mfma_f32_16x16x32_bf16 v[12:15], v[118:121], v[222:225], v[12:15]
	v_mfma_f32_16x16x32_bf16 v[16:19], v[126:129], v[222:225], v[16:19]
	v_mfma_f32_16x16x32_bf16 v[0:3], v[122:125], v[192:195], v[0:3]
	v_mfma_f32_16x16x32_bf16 v[4:7], v[144:147], v[192:195], v[4:7]
	v_mfma_f32_16x16x32_bf16 v[156:159], v[118:121], v[196:199], v[164:167]
	v_mfma_f32_16x16x32_bf16 v[160:163], v[126:129], v[196:199], v[168:171]
	v_mfma_f32_16x16x32_bf16 v[164:167], v[118:121], v[214:217], v[172:175]
	v_mfma_f32_16x16x32_bf16 v[168:171], v[126:129], v[214:217], v[176:179]
	v_mfma_f32_16x16x32_bf16 v[12:15], v[122:125], v[226:229], v[12:15]
	v_mfma_f32_16x16x32_bf16 v[16:19], v[144:147], v[226:229], v[16:19]
	v_mfma_f32_16x16x32_bf16 v[156:159], v[122:125], v[206:209], v[156:159]
	v_mfma_f32_16x16x32_bf16 v[160:163], v[144:147], v[206:209], v[160:163]
	v_mfma_f32_16x16x32_bf16 v[164:167], v[122:125], v[218:221], v[164:167]
	v_mfma_f32_16x16x32_bf16 v[168:171], v[144:147], v[218:221], v[168:171]
	s_setprio 0
	s_setprio 1
	v_mfma_f32_16x16x32_bf16 v[20:23], v[148:151], v[188:191], v[20:23]
	v_mfma_f32_16x16x32_bf16 v[32:35], v[180:183], v[188:191], v[32:35]
	v_mfma_f32_16x16x32_bf16 v[36:39], v[148:151], v[196:199], v[36:39]
	v_mfma_f32_16x16x32_bf16 v[60:63], v[180:183], v[196:199], v[60:63]
	v_mfma_f32_16x16x32_bf16 v[66:69], v[148:151], v[214:217], v[66:69]
	v_mfma_f32_16x16x32_bf16 v[114:117], v[180:183], v[214:217], v[114:117]
	v_mfma_f32_16x16x32_bf16 v[24:27], v[148:151], v[222:225], v[24:27]
	v_mfma_f32_16x16x32_bf16 v[28:31], v[180:183], v[222:225], v[28:31]
	v_mfma_f32_16x16x32_bf16 v[20:23], v[152:155], v[192:195], v[20:23]
	v_mfma_f32_16x16x32_bf16 v[32:35], v[184:187], v[192:195], v[32:35]
	v_mfma_f32_16x16x32_bf16 v[36:39], v[152:155], v[206:209], v[36:39]
	v_mfma_f32_16x16x32_bf16 v[60:63], v[184:187], v[206:209], v[60:63]
	v_mfma_f32_16x16x32_bf16 v[66:69], v[152:155], v[218:221], v[66:69]
	v_mfma_f32_16x16x32_bf16 v[114:117], v[184:187], v[218:221], v[114:117]
	v_mfma_f32_16x16x32_bf16 v[24:27], v[152:155], v[226:229], v[24:27]
	v_mfma_f32_16x16x32_bf16 v[28:31], v[184:187], v[226:229], v[28:31]
	s_setprio 0
	s_barrier
; #define PG8_STAGE(bufoff, gbase, voff) do { _Pragma("unroll") for (int _i = 0; _i < 2; ++_i) \
;         __builtin_amdgcn_global_load_lds((const unsigned*)((const char*)(gbase) + (voff)[_i]), (PG8_LAS unsigned*)(lds + (bufoff) + ldsw + _i * 8192), 16, 0, 0); } while (0)
; #define PG8_LDA(dst, b, h) do { _Pragma("unroll") for (int m = 0; m < 4; ++m) _Pragma("unroll") for (int k = 0; k < 2; ++k) dst[m][k] = *(const PG8_LAS bf16x8*)(lds + PG8_SA(b, h) + aoff + m * 2048 + k * 1024); } while (0)
; #define PG8_LDB(dst, b, h) do { _Pragma("unroll") for (int n = 0; n < 2; ++n) _Pragma("unroll") for (int k = 0; k < 2; ++k) dst[n][k] = *(const PG8_LAS bf16x8*)(lds + PG8_SB(b, h) + boff + n * 2048 + k * 1024); } while (0)
; #define PG8_MMA(ai, bj, At, Bt) do { __builtin_amdgcn_s_setprio(1); _Pragma("unroll") for (int m = 0; m < 4; ++m) _Pragma("unroll") for (int n = 0; n < 2; ++n) _Pragma("unroll") for (int k = 0; k < 2; ++k) \
;         acc[ai][bj][m][n] = __builtin_amdgcn_mfma_f32_16x16x32_bf16(Bt[n][k], At[m][k], acc[ai][bj][m][n], 0, 0, 0); __builtin_amdgcn_s_setprio(0); } while (0)
; #define PG8_WAIT_V(n) asm volatile("s_waitcnt vmcnt(" #n ")" ::: "memory")
; #define PG8_WAIT_L(n) asm volatile("s_waitcnt lgkmcnt(" #n ")" ::: "memory")
; #define PG8_BAR __builtin_amdgcn_s_barrier()
; #define PG8_SCHED __builtin_amdgcn_sched_barrier(0)
; template <class Epi, class Sched, bool ALIGN_EPI = false, bool SP2 = false>
; __device__ __forceinline__ void gemm_phase(PG8_LAS unsigned char* lds, const Gemm g, const Sched& S, const Epi& E, const int tid) {
;     ...
;             PG8_LDB(B0, 0, 0); PG8_LDB(B1, 0, 1); PG8_SCHED; PG8_LDA(At, 0, 0); PG8_STAGE(PG8_SA(1, 1), a1 + hstep, voffA);
;             PG8_WAIT_V(8); PG8_WAIT_L(0); PG8_BAR; PG8_MMA(0, 0, At, B0); PG8_MMA(0, 1, At, B1); PG8_BAR; PG8_SCHED;
;             PG8_LDA(At, 0, 1); PG8_STAGE(PG8_SB(0, 0), b2, voffB); PG8_STAGE(PG8_SB(0, 1), b2 + hstep, voffB); PG8_STAGE(PG8_SA(0, 0), a2, voffA);
;             PG8_WAIT_V(8); PG8_WAIT_L(0); PG8_BAR; PG8_MMA(1, 0, At, B0); PG8_MMA(1, 1, At, B1); PG8_BAR; PG8_SCHED;
	ds_read_b128 v[118:121], v8
	ds_read_b128 v[122:125], v8 offset:1024
	ds_read_b128 v[126:129], v8 offset:2048
	ds_read_b128 v[144:147], v8 offset:3072
	ds_read_b128 v[148:151], v9
	ds_read_b128 v[152:155], v9 offset:1024
	ds_read_b128 v[172:175], v9 offset:2048
	ds_read_b128 v[176:179], v9 offset:3072
	s_add_u32 s14, s14, 0x18280
	s_addc_u32 s15, s15, 0
	s_mov_b32 m0, s50
	v_lshl_add_u64 v[8:9], s[14:15], 0, v[136:137]
	ds_read_b128 v[180:183], v142
	ds_read_b128 v[184:187], v142 offset:1024
	ds_read_b128 v[188:191], v142 offset:2048
	ds_read_b128 v[192:195], v142 offset:3072
	ds_read_b128 v[196:199], v142 offset:4096
	ds_read_b128 v[206:209], v142 offset:5120
	ds_read_b128 v[214:217], v142 offset:6144
	ds_read_b128 v[218:221], v142 offset:7168
	global_load_lds_dwordx4 v[8:9], off
	v_lshl_add_u64 v[8:9], s[14:15], 0, v[132:133]
	s_mov_b32 m0, s2
	s_nop 0
	global_load_lds_dwordx4 v[8:9], off
	s_waitcnt vmcnt(8)
	s_waitcnt lgkmcnt(0)
	s_barrier
	s_setprio 1
	v_mfma_f32_16x16x32_bf16 v[94:97], v[118:121], v[214:217], v[94:97]
	v_mfma_f32_16x16x32_bf16 v[70:73], v[118:121], v[180:183], v[70:73]
	v_mfma_f32_16x16x32_bf16 v[74:77], v[126:129], v[180:183], v[74:77]
	v_mfma_f32_16x16x32_bf16 v[78:81], v[118:121], v[188:191], v[78:81]
	v_mfma_f32_16x16x32_bf16 v[82:85], v[126:129], v[188:191], v[82:85]
	v_mfma_f32_16x16x32_bf16 v[86:89], v[118:121], v[196:199], v[86:89]
	v_mfma_f32_16x16x32_bf16 v[90:93], v[126:129], v[196:199], v[90:93]
	v_mfma_f32_16x16x32_bf16 v[222:225], v[122:125], v[218:221], v[94:97]
	v_mfma_f32_16x16x32_bf16 v[94:97], v[126:129], v[214:217], v[98:101]
	v_mfma_f32_16x16x32_bf16 v[70:73], v[122:125], v[184:187], v[70:73]
	v_mfma_f32_16x16x32_bf16 v[74:77], v[144:147], v[184:187], v[74:77]
	v_mfma_f32_16x16x32_bf16 v[78:81], v[122:125], v[192:195], v[78:81]
	v_mfma_f32_16x16x32_bf16 v[82:85], v[144:147], v[192:195], v[82:85]
	v_mfma_f32_16x16x32_bf16 v[86:89], v[122:125], v[206:209], v[86:89]
	v_mfma_f32_16x16x32_bf16 v[90:93], v[144:147], v[206:209], v[90:93]
	v_mfma_f32_16x16x32_bf16 v[98:101], v[144:147], v[218:221], v[94:97]
	s_setprio 0
	s_setprio 1
	v_mfma_f32_16x16x32_bf16 v[94:97], v[148:151], v[180:183], v[102:105]
	v_mfma_f32_16x16x32_bf16 v[102:105], v[152:155], v[184:187], v[94:97]
	v_mfma_f32_16x16x32_bf16 v[94:97], v[172:175], v[180:183], v[106:109]
	v_mfma_f32_16x16x32_bf16 v[40:43], v[172:175], v[188:191], v[40:43]
	v_mfma_f32_16x16x32_bf16 v[44:47], v[148:151], v[196:199], v[44:47]
	v_mfma_f32_16x16x32_bf16 v[48:51], v[172:175], v[196:199], v[48:51]
	v_mfma_f32_16x16x32_bf16 v[52:55], v[148:151], v[214:217], v[52:55]
	v_mfma_f32_16x16x32_bf16 v[56:59], v[172:175], v[214:217], v[56:59]
	v_mfma_f32_16x16x32_bf16 v[180:183], v[176:179], v[184:187], v[94:97]
	v_mfma_f32_16x16x32_bf16 v[94:97], v[148:151], v[188:191], v[110:113]
	v_mfma_f32_16x16x32_bf16 v[40:43], v[176:179], v[192:195], v[40:43]
	v_mfma_f32_16x16x32_bf16 v[44:47], v[152:155], v[206:209], v[44:47]
	v_mfma_f32_16x16x32_bf16 v[48:51], v[176:179], v[206:209], v[48:51]
	v_mfma_f32_16x16x32_bf16 v[52:55], v[152:155], v[218:221], v[52:55]
	v_mfma_f32_16x16x32_bf16 v[56:59], v[176:179], v[218:221], v[56:59]
	v_mfma_f32_16x16x32_bf16 v[184:187], v[152:155], v[192:195], v[94:97]
	s_setprio 0
	s_barrier
	s_mov_b32 m0, s47
	v_lshl_add_u64 v[138:139], s[12:13], 0, v[134:135]
	s_add_u32 s2, s12, 0x18000
	ds_read_b128 v[94:97], v142 offset:16384
	ds_read_b128 v[106:109], v142 offset:17408
	ds_read_b128 v[110:113], v142 offset:18432
	ds_read_b128 v[188:191], v142 offset:19456
	ds_read_b128 v[192:195], v142 offset:20480
	ds_read_b128 v[196:199], v142 offset:21504
	ds_read_b128 v[206:209], v142 offset:22528
	ds_read_b128 v[214:217], v142 offset:23552
	global_load_lds_dwordx4 v[138:139], off
	v_lshl_add_u64 v[252:253], s[12:13], 0, v[130:131]
	s_mov_b32 m0, s3
	s_addc_u32 s3, s13, 0
	global_load_lds_dwordx4 v[252:253], off
	v_lshl_add_u64 v[8:9], s[2:3], 0, v[134:135]
	s_mov_b32 m0, s45
	v_lshl_add_u64 v[246:247], s[10:11], 0, v[136:137]
	global_load_lds_dwordx4 v[8:9], off
	v_lshl_add_u64 v[8:9], s[2:3], 0, v[130:131]
	s_mov_b32 m0, s46
	v_lshl_add_u64 v[210:211], s[10:11], 0, v[132:133]
	global_load_lds_dwordx4 v[8:9], off
	s_mov_b32 m0, s23
	s_nop 0
	global_load_lds_dwordx4 v[246:247], off
	s_mov_b32 m0, s24
	s_nop 0
	global_load_lds_dwordx4 v[210:211], off
	s_waitcnt vmcnt(8)
	s_waitcnt lgkmcnt(0)
	s_barrier
	s_setprio 1
	v_mfma_f32_16x16x32_bf16 v[0:3], v[118:121], v[94:97], v[0:3]
	v_mfma_f32_16x16x32_bf16 v[4:7], v[126:129], v[94:97], v[4:7]
	v_mfma_f32_16x16x32_bf16 v[12:15], v[118:121], v[206:209], v[12:15]
	v_mfma_f32_16x16x32_bf16 v[16:19], v[126:129], v[206:209], v[16:19]
	v_mfma_f32_16x16x32_bf16 v[0:3], v[122:125], v[106:109], v[0:3]
	v_mfma_f32_16x16x32_bf16 v[4:7], v[144:147], v[106:109], v[4:7]
	v_mfma_f32_16x16x32_bf16 v[156:159], v[118:121], v[110:113], v[156:159]
	v_mfma_f32_16x16x32_bf16 v[160:163], v[126:129], v[110:113], v[160:163]
	v_mfma_f32_16x16x32_bf16 v[164:167], v[118:121], v[192:195], v[164:167]
	v_mfma_f32_16x16x32_bf16 v[168:171], v[126:129], v[192:195], v[168:171]
	v_mfma_f32_16x16x32_bf16 v[12:15], v[122:125], v[214:217], v[12:15]
	v_mfma_f32_16x16x32_bf16 v[16:19], v[144:147], v[214:217], v[16:19]
	v_mfma_f32_16x16x32_bf16 v[156:159], v[122:125], v[188:191], v[156:159]
	v_mfma_f32_16x16x32_bf16 v[160:163], v[144:147], v[188:191], v[160:163]
	v_mfma_f32_16x16x32_bf16 v[164:167], v[122:125], v[196:199], v[164:167]
	v_mfma_f32_16x16x32_bf16 v[168:171], v[144:147], v[196:199], v[168:171]
	s_setprio 0
	s_setprio 1
	v_mfma_f32_16x16x32_bf16 v[60:63], v[172:175], v[110:113], v[60:63]
	v_mfma_f32_16x16x32_bf16 v[20:23], v[148:151], v[94:97], v[20:23]
	v_mfma_f32_16x16x32_bf16 v[32:35], v[172:175], v[94:97], v[32:35]
	v_mfma_f32_16x16x32_bf16 v[36:39], v[148:151], v[110:113], v[36:39]
	v_mfma_f32_16x16x32_bf16 v[144:147], v[176:179], v[188:191], v[60:63]
	v_mfma_f32_16x16x32_bf16 v[60:63], v[148:151], v[192:195], v[66:69]
	v_mfma_f32_16x16x32_bf16 v[24:27], v[148:151], v[206:209], v[24:27]
	v_mfma_f32_16x16x32_bf16 v[20:23], v[152:155], v[106:109], v[20:23]
	v_mfma_f32_16x16x32_bf16 v[32:35], v[176:179], v[106:109], v[32:35]
	v_mfma_f32_16x16x32_bf16 v[36:39], v[152:155], v[188:191], v[36:39]
	v_mfma_f32_16x16x32_bf16 v[188:191], v[152:155], v[196:199], v[60:63]
	v_mfma_f32_16x16x32_bf16 v[60:63], v[172:175], v[192:195], v[114:117]
	v_mfma_f32_16x16x32_bf16 v[148:151], v[152:155], v[214:217], v[24:27]
	v_mfma_f32_16x16x32_bf16 v[24:27], v[172:175], v[206:209], v[28:31]
	v_mfma_f32_16x16x32_bf16 v[192:195], v[176:179], v[196:199], v[60:63]
	v_mfma_f32_16x16x32_bf16 v[152:155], v[176:179], v[214:217], v[24:27]
	s_setprio 0
	s_barrier
; #define PG8_STAGE(bufoff, gbase, voff) do { _Pragma("unroll") for (int _i = 0; _i < 2; ++_i) \
;         __builtin_amdgcn_global_load_lds((const unsigned*)((const char*)(gbase) + (voff)[_i]), (PG8_LAS unsigned*)(lds + (bufoff) + ldsw + _i * 8192), 16, 0, 0); } while (0)
; #define PG8_LDA(dst, b, h) do { _Pragma("unroll") for (int m = 0; m < 4; ++m) _Pragma("unroll") for (int k = 0; k < 2; ++k) dst[m][k] = *(const PG8_LAS bf16x8*)(lds + PG8_SA(b, h) + aoff + m * 2048 + k * 1024); } while (0)
; #define PG8_LDB(dst, b, h) do { _Pragma("unroll") for (int n = 0; n < 2; ++n) _Pragma("unroll") for (int k = 0; k < 2; ++k) dst[n][k] = *(const PG8_LAS bf16x8*)(lds + PG8_SB(b, h) + boff + n * 2048 + k * 1024); } while (0)
; #define PG8_MMA(ai, bj, At, Bt) do { __builtin_amdgcn_s_setprio(1); _Pragma("unroll") for (int m = 0; m < 4; ++m) _Pragma("unroll") for (int n = 0; n < 2; ++n) _Pragma("unroll") for (int k = 0; k < 2; ++k) \
;         acc[ai][bj][m][n] = __builtin_amdgcn_mfma_f32_16x16x32_bf16(Bt[n][k], At[m][k], acc[ai][bj][m][n], 0, 0, 0); __builtin_amdgcn_s_setprio(0); } while (0)
; #define PG8_WAIT_V(n) asm volatile("s_waitcnt vmcnt(" #n ")" ::: "memory")
; #define PG8_WAIT_L(n) asm volatile("s_waitcnt lgkmcnt(" #n ")" ::: "memory")
; #define PG8_BAR __builtin_amdgcn_s_barrier()
; #define PG8_SCHED __builtin_amdgcn_sched_barrier(0)
; template <class Epi, class Sched, bool ALIGN_EPI = false, bool SP2 = false>
; __device__ __forceinline__ void gemm_phase(PG8_LAS unsigned char* lds, const Gemm g, const Sched& S, const Epi& E, const int tid) {
;     ...
;             PG8_LDB(B0, 1, 0); PG8_LDB(B1, 1, 1); PG8_SCHED; PG8_LDA(At, 1, 0); PG8_STAGE(PG8_SA(0, 1), a2 + hstep, voffA);
;             PG8_WAIT_V(8); PG8_WAIT_L(0); PG8_BAR; PG8_MMA(0, 0, At, B0); PG8_MMA(0, 1, At, B1); PG8_BAR; PG8_SCHED;
;             PG8_LDA(At, 1, 1); PG8_STAGE(PG8_SB(1, 0), b3, voffB); PG8_STAGE(PG8_SB(1, 1), b3 + hstep, voffB); PG8_STAGE(PG8_SA(1, 0), a3, voffA);
;             PG8_WAIT_V(8); PG8_WAIT_L(0); PG8_BAR; PG8_MMA(1, 0, At, B0); PG8_MMA(1, 1, At, B1); PG8_BAR; PG8_SCHED;
;     ...
;         if constexpr (ALIGN_EPI) { if (wr == 0) PG8_BAR; }
	ds_read_b128 v[172:175], v10
	ds_read_b128 v[176:179], v10 offset:1024
	ds_read_b128 v[196:199], v10 offset:2048
	ds_read_b128 v[206:209], v10 offset:3072
	ds_read_b128 v[214:217], v11
	ds_read_b128 v[218:221], v11 offset:1024
	ds_read_b128 v[226:229], v11 offset:2048
	ds_read_b128 v[248:251], v11 offset:3072
	s_add_u32 s2, s10, 0x18000
	s_addc_u32 s3, s11, 0
	s_mov_b32 m0, s25
	v_lshl_add_u64 v[94:95], s[2:3], 0, v[136:137]
	ds_read_b128 v[8:11], v142 offset:32768
	ds_read_b128 v[24:27], v142 offset:33792
	ds_read_b128 v[28:31], v142 offset:34816
	ds_read_b128 v[60:63], v142 offset:35840
	ds_read_b128 v[66:69], v142 offset:36864
	ds_read_b128 v[234:237], v142 offset:37888
	ds_read_b128 v[238:241], v142 offset:38912
	ds_read_b128 v[230:233], v142 offset:39936
	global_load_lds_dwordx4 v[94:95], off
	v_lshl_add_u64 v[94:95], s[2:3], 0, v[132:133]
	s_mov_b32 m0, s26
	s_nop 0
	global_load_lds_dwordx4 v[94:95], off
	s_waitcnt vmcnt(8)
	s_waitcnt lgkmcnt(0)
	s_barrier
	s_setprio 1
	v_mfma_f32_16x16x32_bf16 v[70:73], v[172:175], v[8:11], v[70:73]
	v_mfma_f32_16x16x32_bf16 v[126:129], v[176:179], v[24:27], v[70:73]
	v_mfma_f32_16x16x32_bf16 v[70:73], v[196:199], v[8:11], v[74:77]
	v_mfma_f32_16x16x32_bf16 v[122:125], v[206:209], v[24:27], v[70:73]
	v_mfma_f32_16x16x32_bf16 v[70:73], v[172:175], v[28:31], v[78:81]
	v_mfma_f32_16x16x32_bf16 v[110:113], v[176:179], v[60:63], v[70:73]
	v_mfma_f32_16x16x32_bf16 v[70:73], v[196:199], v[28:31], v[82:85]
	v_mfma_f32_16x16x32_bf16 v[106:109], v[206:209], v[60:63], v[70:73]
	v_mfma_f32_16x16x32_bf16 v[70:73], v[172:175], v[66:69], v[86:89]
	v_mfma_f32_16x16x32_bf16 v[94:97], v[176:179], v[234:237], v[70:73]
	v_mfma_f32_16x16x32_bf16 v[70:73], v[196:199], v[66:69], v[90:93]
	v_mfma_f32_16x16x32_bf16 v[90:93], v[206:209], v[234:237], v[70:73]
	v_mfma_f32_16x16x32_bf16 v[70:73], v[172:175], v[238:241], v[222:225]
	v_mfma_f32_16x16x32_bf16 v[78:81], v[176:179], v[230:233], v[70:73]
	v_mfma_f32_16x16x32_bf16 v[70:73], v[196:199], v[238:241], v[98:101]
	v_mfma_f32_16x16x32_bf16 v[74:77], v[206:209], v[230:233], v[70:73]
	s_setprio 0
	s_setprio 1
	v_mfma_f32_16x16x32_bf16 v[70:73], v[214:217], v[8:11], v[102:105]
	v_mfma_f32_16x16x32_bf16 v[8:11], v[226:229], v[8:11], v[180:183]
	v_mfma_f32_16x16x32_bf16 v[118:121], v[248:251], v[24:27], v[8:11]
	v_mfma_f32_16x16x32_bf16 v[8:11], v[214:217], v[28:31], v[184:187]
	v_mfma_f32_16x16x32_bf16 v[98:101], v[218:221], v[60:63], v[8:11]
	v_mfma_f32_16x16x32_bf16 v[8:11], v[226:229], v[28:31], v[40:43]
	v_mfma_f32_16x16x32_bf16 v[102:105], v[248:251], v[60:63], v[8:11]
	v_mfma_f32_16x16x32_bf16 v[8:11], v[214:217], v[66:69], v[44:47]
	v_mfma_f32_16x16x32_bf16 v[82:85], v[218:221], v[234:237], v[8:11]
	v_mfma_f32_16x16x32_bf16 v[8:11], v[226:229], v[66:69], v[48:51]
	v_mfma_f32_16x16x32_bf16 v[86:89], v[248:251], v[234:237], v[8:11]
	v_mfma_f32_16x16x32_bf16 v[8:11], v[214:217], v[238:241], v[52:55]
	v_mfma_f32_16x16x32_bf16 v[66:69], v[218:221], v[230:233], v[8:11]
	v_mfma_f32_16x16x32_bf16 v[8:11], v[226:229], v[238:241], v[56:59]
	v_mfma_f32_16x16x32_bf16 v[114:117], v[218:221], v[24:27], v[70:73]
	v_mfma_f32_16x16x32_bf16 v[70:73], v[248:251], v[230:233], v[8:11]
	s_setprio 0
	s_barrier
	s_mov_b32 m0, s52
	s_nop 2
	v_lshl_add_u64 v[8:9], v[138:139], 0, s[94:95]
	s_add_u32 s2, s12, 0x18080
	ds_read_b128 v[52:55], v142 offset:49152
	ds_read_b128 v[180:183], v142 offset:50176
	ds_read_b128 v[184:187], v142 offset:51200
	ds_read_b128 v[222:225], v142 offset:52224
	ds_read_b128 v[230:233], v142 offset:53248
	ds_read_b128 v[234:237], v142 offset:54272
	ds_read_b128 v[238:241], v142 offset:55296
	ds_read_b128 v[200:203], v142 offset:56320
	global_load_lds_dwordx4 v[8:9], off
	v_lshl_add_u64 v[8:9], v[252:253], 0, s[94:95]
	s_mov_b32 m0, s48
	s_addc_u32 s3, s13, 0
	global_load_lds_dwordx4 v[8:9], off
	v_lshl_add_u64 v[8:9], s[2:3], 0, v[134:135]
	s_mov_b32 m0, s49
	s_nop 0
	global_load_lds_dwordx4 v[8:9], off
	v_lshl_add_u64 v[8:9], s[2:3], 0, v[130:131]
	s_mov_b32 m0, s51
	s_nop 0
	global_load_lds_dwordx4 v[8:9], off
	v_lshl_add_u64 v[8:9], v[246:247], 0, s[94:95]
	s_mov_b32 m0, s28
	s_nop 0
	global_load_lds_dwordx4 v[8:9], off
	v_lshl_add_u64 v[8:9], v[210:211], 0, s[94:95]
	s_mov_b32 m0, s29
	s_nop 0
	global_load_lds_dwordx4 v[8:9], off
	s_waitcnt vmcnt(8)
	s_waitcnt lgkmcnt(0)
	s_barrier
	s_setprio 1
	v_mfma_f32_16x16x32_bf16 v[0:3], v[172:175], v[52:55], v[0:3]
	v_mfma_f32_16x16x32_bf16 v[60:63], v[176:179], v[180:183], v[0:3]
	v_mfma_f32_16x16x32_bf16 v[0:3], v[196:199], v[52:55], v[4:7]
	v_mfma_f32_16x16x32_bf16 v[56:59], v[206:209], v[180:183], v[0:3]
	v_mfma_f32_16x16x32_bf16 v[0:3], v[172:175], v[184:187], v[156:159]
	v_mfma_f32_16x16x32_bf16 v[44:47], v[176:179], v[222:225], v[0:3]
	v_mfma_f32_16x16x32_bf16 v[0:3], v[196:199], v[184:187], v[160:163]
	v_mfma_f32_16x16x32_bf16 v[40:43], v[206:209], v[222:225], v[0:3]
	v_mfma_f32_16x16x32_bf16 v[0:3], v[172:175], v[230:233], v[164:167]
	v_mfma_f32_16x16x32_bf16 v[28:31], v[176:179], v[234:237], v[0:3]
	v_mfma_f32_16x16x32_bf16 v[0:3], v[196:199], v[230:233], v[168:171]
	v_mfma_f32_16x16x32_bf16 v[24:27], v[206:209], v[234:237], v[0:3]
	v_mfma_f32_16x16x32_bf16 v[0:3], v[172:175], v[238:241], v[12:15]
	v_mfma_f32_16x16x32_bf16 v[8:11], v[176:179], v[200:203], v[0:3]
	v_mfma_f32_16x16x32_bf16 v[0:3], v[196:199], v[238:241], v[16:19]
	v_mfma_f32_16x16x32_bf16 v[12:15], v[206:209], v[200:203], v[0:3]
	s_setprio 0
	s_setprio 1
	v_mfma_f32_16x16x32_bf16 v[0:3], v[214:217], v[52:55], v[20:23]
	v_mfma_f32_16x16x32_bf16 v[48:51], v[218:221], v[180:183], v[0:3]
	v_mfma_f32_16x16x32_bf16 v[0:3], v[226:229], v[52:55], v[32:35]
	v_mfma_f32_16x16x32_bf16 v[52:55], v[248:251], v[180:183], v[0:3]
	v_mfma_f32_16x16x32_bf16 v[0:3], v[214:217], v[184:187], v[36:39]
	v_mfma_f32_16x16x32_bf16 v[32:35], v[218:221], v[222:225], v[0:3]
	v_mfma_f32_16x16x32_bf16 v[0:3], v[226:229], v[184:187], v[144:147]
	v_mfma_f32_16x16x32_bf16 v[36:39], v[248:251], v[222:225], v[0:3]
	v_mfma_f32_16x16x32_bf16 v[0:3], v[214:217], v[230:233], v[188:191]
	v_mfma_f32_16x16x32_bf16 v[16:19], v[218:221], v[234:237], v[0:3]
	v_mfma_f32_16x16x32_bf16 v[0:3], v[226:229], v[230:233], v[192:195]
	v_mfma_f32_16x16x32_bf16 v[20:23], v[248:251], v[234:237], v[0:3]
	v_mfma_f32_16x16x32_bf16 v[0:3], v[214:217], v[238:241], v[148:151]
	v_mfma_f32_16x16x32_bf16 v[4:7], v[226:229], v[238:241], v[152:155]
	v_mfma_f32_16x16x32_bf16 v[0:3], v[218:221], v[200:203], v[0:3]
	v_mfma_f32_16x16x32_bf16 v[4:7], v[248:251], v[200:203], v[4:7]
	s_setprio 0
	s_barrier
	s_andn2_b64 vcc, exec, s[8:9]
	s_cbranch_vccnz .LBB0_350
	s_barrier

; #define PG8_STAGE(bufoff, gbase, voff) do { _Pragma("unroll") for (int _i = 0; _i < 2; ++_i) \
;         __builtin_amdgcn_global_load_lds((const unsigned*)((const char*)(gbase) + (voff)[_i]), (PG8_LAS unsigned*)(lds + (bufoff) + ldsw + _i * 8192), 16, 0, 0); } while (0)
; #define PG8_LDA(dst, b, h) do { _Pragma("unroll") for (int m = 0; m < 4; ++m) _Pragma("unroll") for (int k = 0; k < 2; ++k) dst[m][k] = *(const PG8_LAS bf16x8*)(lds + PG8_SA(b, h) + aoff + m * 2048 + k * 1024); } while (0)
; #define PG8_LDB(dst, b, h) do { _Pragma("unroll") for (int n = 0; n < 2; ++n) _Pragma("unroll") for (int k = 0; k < 2; ++k) dst[n][k] = *(const PG8_LAS bf16x8*)(lds + PG8_SB(b, h) + boff + n * 2048 + k * 1024); } while (0)
; #define PG8_MMA(ai, bj, At, Bt) do { __builtin_amdgcn_s_setprio(1); _Pragma("unroll") for (int m = 0; m < 4; ++m) _Pragma("unroll") for (int n = 0; n < 2; ++n) _Pragma("unroll") for (int k = 0; k < 2; ++k) \
;         acc[ai][bj][m][n] = __builtin_amdgcn_mfma_f32_16x16x32_bf16(Bt[n][k], At[m][k], acc[ai][bj][m][n], 0, 0, 0); __builtin_amdgcn_s_setprio(0); } while (0)
; #define PG8_WAIT_V(n) asm volatile("s_waitcnt vmcnt(" #n ")" ::: "memory")
; #define PG8_WAIT_L(n) asm volatile("s_waitcnt lgkmcnt(" #n ")" ::: "memory")
; template <class Epi, class Sched, bool ALIGN_EPI = false, bool SP2 = false>
; __device__ __forceinline__ void gemm_phase(PG8_LAS unsigned char* lds, const Gemm g, const Sched& S, const Epi& E, const int tid) {
;     ...
;             const bool last = (t == nt - 2);
;             const char* a1 = cA + (size_t)(t + 1) * kstep;
;             const char* a2 = last ? nA : cA + (size_t)(t + 2) * kstep; const char* b2 = last ? nB : cB + (size_t)(t + 2) * kstep;
;             const char* a3 = a2 + kstep; const char* b3 = b2 + kstep;
;             if (last && has_next) S.a_ready(nxt);
;             if constexpr (SP2) {
;             PG8_LDB(B0, 0, 0); PG8_LDB(B1, 0, 1); PG8_SCHED; PG8_LDA(At, 0, 0); PG8_STAGE(PG8_SA(1, 1), a1 + hstep, voffA);
;             PG8_WAIT_V(8); PG8_WAIT_L(0); PG8_BAR; PG8_MMA(0, 0, At, B0); PG8_MMA(0, 1, At, B1); PG8_BAR; PG8_SCHED;
;             PG8_LDA(At, 0, 1); PG8_STAGE(PG8_SB(0, 0), b2, voffB); PG8_STAGE(PG8_SB(0, 1), b2 + hstep, voffB); PG8_STAGE(PG8_SA(0, 0), a2, voffA);
;             PG8_WAIT_V(8); PG8_WAIT_L(0); PG8_BAR; PG8_MMA(1, 0, At, B0); PG8_MMA(1, 1, At, B1); PG8_BAR; PG8_SCHED;
.LBB0_511:
	s_add_u32 s6, s24, s4
	s_addc_u32 s7, s25, s5
	s_add_u32 s6, s6, 0x2c00100
	s_addc_u32 s7, s7, 0
	s_add_u32 s27, s22, s4
	s_addc_u32 s28, s23, s5
	s_add_i32 s29, 0, 0x10000
	s_cmpk_eq_i32 s4, 0x700
	s_cselect_b32 s9, s3, s7
	s_cselect_b32 s8, s2, s6
	v_add_u32_e32 v149, s29, v142
	s_cselect_b32 s7, s1, s28
	s_cselect_b32 s6, s0, s27
	s_add_i32 s27, 0, 0x14000
	ds_read_b128 v[144:147], v149
	ds_read_b128 v[150:153], v149 offset:1024
	ds_read_b128 v[154:157], v149 offset:2048
	ds_read_b128 v[158:161], v149 offset:3072
	v_add_u32_e32 v149, s27, v142
	ds_read_b128 v[162:165], v149
	ds_read_b128 v[166:169], v149 offset:1024
	ds_read_b128 v[170:173], v149 offset:2048
	ds_read_b128 v[174:177], v149 offset:3072
	v_lshl_add_u64 v[202:203], v[138:139], 0, s[4:5]
	s_add_i32 m0, s13, 0xc000
	ds_read_b128 v[178:181], v143
	ds_read_b128 v[182:185], v143 offset:1024
	ds_read_b128 v[186:189], v143 offset:2048
	ds_read_b128 v[190:193], v143 offset:3072
	ds_read_b128 v[194:197], v143 offset:4096
	ds_read_b128 v[198:201], v143 offset:5120
	ds_read_b128 v[214:217], v143 offset:6144
	ds_read_b128 v[218:221], v143 offset:7168
	global_load_lds_dwordx4 v[202:203], off
	v_lshl_add_u64 v[202:203], v[136:137], 0, s[4:5]
	s_add_i32 m0, s13, 0xe000
	s_nop 0
	global_load_lds_dwordx4 v[202:203], off
	s_waitcnt vmcnt(8)
	s_waitcnt lgkmcnt(0)
	s_barrier
	s_setprio 1
	v_mfma_f32_16x16x32_bf16 v[126:129], v[144:147], v[178:181], v[126:129]
	v_mfma_f32_16x16x32_bf16 v[122:125], v[154:157], v[178:181], v[122:125]
	v_mfma_f32_16x16x32_bf16 v[118:121], v[144:147], v[186:189], v[118:121]
	v_mfma_f32_16x16x32_bf16 v[114:117], v[154:157], v[186:189], v[114:117]
	v_mfma_f32_16x16x32_bf16 v[110:113], v[144:147], v[194:197], v[110:113]
	v_mfma_f32_16x16x32_bf16 v[106:109], v[154:157], v[194:197], v[106:109]
	v_mfma_f32_16x16x32_bf16 v[102:105], v[144:147], v[214:217], v[102:105]
	v_mfma_f32_16x16x32_bf16 v[98:101], v[154:157], v[214:217], v[98:101]
	v_mfma_f32_16x16x32_bf16 v[126:129], v[150:153], v[182:185], v[126:129]
	v_mfma_f32_16x16x32_bf16 v[122:125], v[158:161], v[182:185], v[122:125]
	v_mfma_f32_16x16x32_bf16 v[118:121], v[150:153], v[190:193], v[118:121]
	v_mfma_f32_16x16x32_bf16 v[114:117], v[158:161], v[190:193], v[114:117]
	v_mfma_f32_16x16x32_bf16 v[110:113], v[150:153], v[198:201], v[110:113]
	v_mfma_f32_16x16x32_bf16 v[106:109], v[158:161], v[198:201], v[106:109]
	v_mfma_f32_16x16x32_bf16 v[102:105], v[150:153], v[218:221], v[102:105]
	v_mfma_f32_16x16x32_bf16 v[98:101], v[158:161], v[218:221], v[98:101]
	s_setprio 0
	s_setprio 1
	v_mfma_f32_16x16x32_bf16 v[60:63], v[162:165], v[178:181], v[60:63]
	v_mfma_f32_16x16x32_bf16 v[56:59], v[170:173], v[178:181], v[56:59]
	v_mfma_f32_16x16x32_bf16 v[52:55], v[162:165], v[186:189], v[52:55]
	v_mfma_f32_16x16x32_bf16 v[48:51], v[170:173], v[186:189], v[48:51]
	v_mfma_f32_16x16x32_bf16 v[44:47], v[162:165], v[194:197], v[44:47]
	v_mfma_f32_16x16x32_bf16 v[40:43], v[170:173], v[194:197], v[40:43]
	v_mfma_f32_16x16x32_bf16 v[36:39], v[162:165], v[214:217], v[36:39]
	v_mfma_f32_16x16x32_bf16 v[32:35], v[170:173], v[214:217], v[32:35]
	v_mfma_f32_16x16x32_bf16 v[60:63], v[166:169], v[182:185], v[60:63]
	v_mfma_f32_16x16x32_bf16 v[56:59], v[174:177], v[182:185], v[56:59]
	v_mfma_f32_16x16x32_bf16 v[52:55], v[166:169], v[190:193], v[52:55]
	v_mfma_f32_16x16x32_bf16 v[48:51], v[174:177], v[190:193], v[48:51]
	v_mfma_f32_16x16x32_bf16 v[44:47], v[166:169], v[198:201], v[44:47]
	v_mfma_f32_16x16x32_bf16 v[40:43], v[174:177], v[198:201], v[40:43]
	v_mfma_f32_16x16x32_bf16 v[36:39], v[166:169], v[218:221], v[36:39]
	v_mfma_f32_16x16x32_bf16 v[32:35], v[174:177], v[218:221], v[32:35]
	s_setprio 0
	s_barrier
	s_add_i32 s28, s29, s12
	v_lshl_add_u64 v[202:203], s[6:7], 0, v[64:65]
	s_mov_b32 m0, s28
	ds_read_b128 v[178:181], v143 offset:16384
	ds_read_b128 v[182:185], v143 offset:17408
	ds_read_b128 v[186:189], v143 offset:18432
	ds_read_b128 v[190:193], v143 offset:19456
	ds_read_b128 v[194:197], v143 offset:20480
	ds_read_b128 v[198:201], v143 offset:21504
	ds_read_b128 v[214:217], v143 offset:22528
	ds_read_b128 v[218:221], v143 offset:23552
	global_load_lds_dwordx4 v[202:203], off
	s_add_i32 m0, s28, 0x2000
	s_add_u32 s28, s6, 0x40000
	v_lshl_add_u64 v[206:207], s[6:7], 0, v[134:135]
	s_addc_u32 s29, s7, 0
	s_add_i32 s27, s27, s12
	global_load_lds_dwordx4 v[206:207], off
	v_lshl_add_u64 v[208:209], s[28:29], 0, v[64:65]
	s_mov_b32 m0, s27
	v_lshl_add_u64 v[222:223], s[8:9], 0, v[132:133]
	global_load_lds_dwordx4 v[208:209], off
	v_lshl_add_u64 v[208:209], s[28:29], 0, v[134:135]
	s_add_i32 m0, s27, 0x2000
	s_nop 0
	global_load_lds_dwordx4 v[208:209], off
	v_lshl_add_u64 v[208:209], s[8:9], 0, v[130:131]
	s_mov_b32 m0, s13
	s_nop 0
	global_load_lds_dwordx4 v[208:209], off
	s_mov_b32 m0, s16
	s_nop 0
	global_load_lds_dwordx4 v[222:223], off
	s_waitcnt vmcnt(8)
	s_waitcnt lgkmcnt(0)
	s_barrier
; #define PG8_STAGE(bufoff, gbase, voff) do { _Pragma("unroll") for (int _i = 0; _i < 2; ++_i) \
;         __builtin_amdgcn_global_load_lds((const unsigned*)((const char*)(gbase) + (voff)[_i]), (PG8_LAS unsigned*)(lds + (bufoff) + ldsw + _i * 8192), 16, 0, 0); } while (0)
; #define PG8_LDA(dst, b, h) do { _Pragma("unroll") for (int m = 0; m < 4; ++m) _Pragma("unroll") for (int k = 0; k < 2; ++k) dst[m][k] = *(const PG8_LAS bf16x8*)(lds + PG8_SA(b, h) + aoff + m * 2048 + k * 1024); } while (0)
; #define PG8_LDB(dst, b, h) do { _Pragma("unroll") for (int n = 0; n < 2; ++n) _Pragma("unroll") for (int k = 0; k < 2; ++k) dst[n][k] = *(const PG8_LAS bf16x8*)(lds + PG8_SB(b, h) + boff + n * 2048 + k * 1024); } while (0)
; #define PG8_MMA(ai, bj, At, Bt) do { __builtin_amdgcn_s_setprio(1); _Pragma("unroll") for (int m = 0; m < 4; ++m) _Pragma("unroll") for (int n = 0; n < 2; ++n) _Pragma("unroll") for (int k = 0; k < 2; ++k) \
;         acc[ai][bj][m][n] = __builtin_amdgcn_mfma_f32_16x16x32_bf16(Bt[n][k], At[m][k], acc[ai][bj][m][n], 0, 0, 0); __builtin_amdgcn_s_setprio(0); } while (0)
; #define PG8_WAIT_V(n) asm volatile("s_waitcnt vmcnt(" #n ")" ::: "memory")
; #define PG8_WAIT_L(n) asm volatile("s_waitcnt lgkmcnt(" #n ")" ::: "memory")
; #define PG8_BAR __builtin_amdgcn_s_barrier()
; #define PG8_SCHED __builtin_amdgcn_sched_barrier(0)
; template <class Epi, class Sched, bool ALIGN_EPI = false, bool SP2 = false>
; __device__ __forceinline__ void gemm_phase(PG8_LAS unsigned char* lds, const Gemm g, const Sched& S, const Epi& E, const int tid) {
;     ...
;             PG8_WAIT_V(8); PG8_WAIT_L(0); PG8_BAR; PG8_MMA(1, 0, At, B0); PG8_MMA(1, 1, At, B1); PG8_BAR; PG8_SCHED;
;             PG8_LDB(B0, 1, 0); PG8_LDB(B1, 1, 1); PG8_SCHED; PG8_LDA(At, 1, 0); PG8_STAGE(PG8_SA(0, 1), a2 + hstep, voffA);
;             PG8_WAIT_V(8); PG8_WAIT_L(0); PG8_BAR; PG8_MMA(0, 0, At, B0); PG8_MMA(0, 1, At, B1); PG8_BAR; PG8_SCHED;
	s_setprio 1
	v_mfma_f32_16x16x32_bf16 v[94:97], v[144:147], v[178:181], v[94:97]
	v_mfma_f32_16x16x32_bf16 v[90:93], v[154:157], v[178:181], v[90:93]
	v_mfma_f32_16x16x32_bf16 v[86:89], v[144:147], v[186:189], v[86:89]
	v_mfma_f32_16x16x32_bf16 v[82:85], v[154:157], v[186:189], v[82:85]
	v_mfma_f32_16x16x32_bf16 v[78:81], v[144:147], v[194:197], v[78:81]
	v_mfma_f32_16x16x32_bf16 v[74:77], v[154:157], v[194:197], v[74:77]
	v_mfma_f32_16x16x32_bf16 v[70:73], v[144:147], v[214:217], v[70:73]
	v_mfma_f32_16x16x32_bf16 v[66:69], v[154:157], v[214:217], v[66:69]
	v_mfma_f32_16x16x32_bf16 v[94:97], v[150:153], v[182:185], v[94:97]
	v_mfma_f32_16x16x32_bf16 v[90:93], v[158:161], v[182:185], v[90:93]
	v_mfma_f32_16x16x32_bf16 v[86:89], v[150:153], v[190:193], v[86:89]
	v_mfma_f32_16x16x32_bf16 v[82:85], v[158:161], v[190:193], v[82:85]
	v_mfma_f32_16x16x32_bf16 v[78:81], v[150:153], v[198:201], v[78:81]
	v_mfma_f32_16x16x32_bf16 v[74:77], v[158:161], v[198:201], v[74:77]
	v_mfma_f32_16x16x32_bf16 v[70:73], v[150:153], v[218:221], v[70:73]
	v_mfma_f32_16x16x32_bf16 v[66:69], v[158:161], v[218:221], v[66:69]
	s_setprio 0
	s_setprio 1
	v_mfma_f32_16x16x32_bf16 v[28:31], v[162:165], v[178:181], v[28:31]
	v_mfma_f32_16x16x32_bf16 v[24:27], v[170:173], v[178:181], v[24:27]
	v_mfma_f32_16x16x32_bf16 v[20:23], v[162:165], v[186:189], v[20:23]
	v_mfma_f32_16x16x32_bf16 v[16:19], v[170:173], v[186:189], v[16:19]
	v_mfma_f32_16x16x32_bf16 v[12:15], v[162:165], v[194:197], v[12:15]
	v_mfma_f32_16x16x32_bf16 v[8:11], v[170:173], v[194:197], v[8:11]
	v_mfma_f32_16x16x32_bf16 v[4:7], v[162:165], v[214:217], v[4:7]
	v_mfma_f32_16x16x32_bf16 v[0:3], v[170:173], v[214:217], v[0:3]
	v_mfma_f32_16x16x32_bf16 v[28:31], v[166:169], v[182:185], v[28:31]
	v_mfma_f32_16x16x32_bf16 v[24:27], v[174:177], v[182:185], v[24:27]
	v_mfma_f32_16x16x32_bf16 v[20:23], v[166:169], v[190:193], v[20:23]
	v_mfma_f32_16x16x32_bf16 v[16:19], v[174:177], v[190:193], v[16:19]
	v_mfma_f32_16x16x32_bf16 v[12:15], v[166:169], v[198:201], v[12:15]
	v_mfma_f32_16x16x32_bf16 v[8:11], v[174:177], v[198:201], v[8:11]
	v_mfma_f32_16x16x32_bf16 v[4:7], v[166:169], v[218:221], v[4:7]
	v_mfma_f32_16x16x32_bf16 v[0:3], v[174:177], v[218:221], v[0:3]
	s_setprio 0
	s_barrier
	s_add_i32 s27, 0, 0x18000
	v_add_u32_e32 v149, s27, v142
	s_add_i32 s28, 0, 0x1c000
	ds_read_b128 v[144:147], v149
	ds_read_b128 v[150:153], v149 offset:1024
	ds_read_b128 v[154:157], v149 offset:2048
	ds_read_b128 v[158:161], v149 offset:3072
	v_add_u32_e32 v149, s28, v142
	ds_read_b128 v[162:165], v149
	ds_read_b128 v[166:169], v149 offset:1024
	ds_read_b128 v[170:173], v149 offset:2048
	ds_read_b128 v[174:177], v149 offset:3072
	s_add_u32 s8, s8, 0x40000
	s_addc_u32 s9, s9, 0
	s_mov_b32 m0, s17
	v_lshl_add_u64 v[224:225], s[8:9], 0, v[130:131]
	ds_read_b128 v[178:181], v143 offset:32768
	ds_read_b128 v[182:185], v143 offset:33792
	ds_read_b128 v[186:189], v143 offset:34816
	ds_read_b128 v[190:193], v143 offset:35840
	ds_read_b128 v[194:197], v143 offset:36864
	ds_read_b128 v[198:201], v143 offset:37888
	ds_read_b128 v[214:217], v143 offset:38912
	ds_read_b128 v[218:221], v143 offset:39936
	global_load_lds_dwordx4 v[224:225], off
	v_lshl_add_u64 v[224:225], s[8:9], 0, v[132:133]
	s_mov_b32 m0, s18
	s_nop 0
	global_load_lds_dwordx4 v[224:225], off
	s_waitcnt vmcnt(8)
	s_waitcnt lgkmcnt(0)
	s_barrier
	s_setprio 1
	v_mfma_f32_16x16x32_bf16 v[126:129], v[144:147], v[178:181], v[126:129]
	v_mfma_f32_16x16x32_bf16 v[122:125], v[154:157], v[178:181], v[122:125]
	v_mfma_f32_16x16x32_bf16 v[118:121], v[144:147], v[186:189], v[118:121]
	v_mfma_f32_16x16x32_bf16 v[114:117], v[154:157], v[186:189], v[114:117]
	v_mfma_f32_16x16x32_bf16 v[110:113], v[144:147], v[194:197], v[110:113]
	v_mfma_f32_16x16x32_bf16 v[106:109], v[154:157], v[194:197], v[106:109]
	v_mfma_f32_16x16x32_bf16 v[102:105], v[144:147], v[214:217], v[102:105]
	v_mfma_f32_16x16x32_bf16 v[98:101], v[154:157], v[214:217], v[98:101]
	v_mfma_f32_16x16x32_bf16 v[126:129], v[150:153], v[182:185], v[126:129]
	v_mfma_f32_16x16x32_bf16 v[122:125], v[158:161], v[182:185], v[122:125]
	v_mfma_f32_16x16x32_bf16 v[118:121], v[150:153], v[190:193], v[118:121]
	v_mfma_f32_16x16x32_bf16 v[114:117], v[158:161], v[190:193], v[114:117]
	v_mfma_f32_16x16x32_bf16 v[110:113], v[150:153], v[198:201], v[110:113]
	v_mfma_f32_16x16x32_bf16 v[106:109], v[158:161], v[198:201], v[106:109]
	v_mfma_f32_16x16x32_bf16 v[102:105], v[150:153], v[218:221], v[102:105]
	v_mfma_f32_16x16x32_bf16 v[98:101], v[158:161], v[218:221], v[98:101]
	s_setprio 0
	s_setprio 1
	v_mfma_f32_16x16x32_bf16 v[60:63], v[162:165], v[178:181], v[60:63]
	v_mfma_f32_16x16x32_bf16 v[56:59], v[170:173], v[178:181], v[56:59]
	v_mfma_f32_16x16x32_bf16 v[52:55], v[162:165], v[186:189], v[52:55]
	v_mfma_f32_16x16x32_bf16 v[48:51], v[170:173], v[186:189], v[48:51]
	v_mfma_f32_16x16x32_bf16 v[44:47], v[162:165], v[194:197], v[44:47]
	v_mfma_f32_16x16x32_bf16 v[40:43], v[170:173], v[194:197], v[40:43]
	v_mfma_f32_16x16x32_bf16 v[36:39], v[162:165], v[214:217], v[36:39]
	v_mfma_f32_16x16x32_bf16 v[32:35], v[170:173], v[214:217], v[32:35]
	v_mfma_f32_16x16x32_bf16 v[60:63], v[166:169], v[182:185], v[60:63]
	v_mfma_f32_16x16x32_bf16 v[56:59], v[174:177], v[182:185], v[56:59]
	v_mfma_f32_16x16x32_bf16 v[52:55], v[166:169], v[190:193], v[52:55]
	v_mfma_f32_16x16x32_bf16 v[48:51], v[174:177], v[190:193], v[48:51]
	v_mfma_f32_16x16x32_bf16 v[44:47], v[166:169], v[198:201], v[44:47]
	v_mfma_f32_16x16x32_bf16 v[40:43], v[174:177], v[198:201], v[40:43]
	v_mfma_f32_16x16x32_bf16 v[36:39], v[166:169], v[218:221], v[36:39]
	v_mfma_f32_16x16x32_bf16 v[32:35], v[174:177], v[218:221], v[32:35]
	s_setprio 0
	s_barrier
; #define PG8_STAGE(bufoff, gbase, voff) do { _Pragma("unroll") for (int _i = 0; _i < 2; ++_i) \
;         __builtin_amdgcn_global_load_lds((const unsigned*)((const char*)(gbase) + (voff)[_i]), (PG8_LAS unsigned*)(lds + (bufoff) + ldsw + _i * 8192), 16, 0, 0); } while (0)
; #define PG8_LDA(dst, b, h) do { _Pragma("unroll") for (int m = 0; m < 4; ++m) _Pragma("unroll") for (int k = 0; k < 2; ++k) dst[m][k] = *(const PG8_LAS bf16x8*)(lds + PG8_SA(b, h) + aoff + m * 2048 + k * 1024); } while (0)
; #define PG8_MMA(ai, bj, At, Bt) do { __builtin_amdgcn_s_setprio(1); _Pragma("unroll") for (int m = 0; m < 4; ++m) _Pragma("unroll") for (int n = 0; n < 2; ++n) _Pragma("unroll") for (int k = 0; k < 2; ++k) \
;         acc[ai][bj][m][n] = __builtin_amdgcn_mfma_f32_16x16x32_bf16(Bt[n][k], At[m][k], acc[ai][bj][m][n], 0, 0, 0); __builtin_amdgcn_s_setprio(0); } while (0)
; #define PG8_WAIT_V(n) asm volatile("s_waitcnt vmcnt(" #n ")" ::: "memory")
; #define PG8_WAIT_L(n) asm volatile("s_waitcnt lgkmcnt(" #n ")" ::: "memory")
; #define PG8_BAR __builtin_amdgcn_s_barrier()
; #define PG8_SCHED __builtin_amdgcn_sched_barrier(0)
; template <class Epi, class Sched, bool ALIGN_EPI = false, bool SP2 = false>
; __device__ __forceinline__ void gemm_phase(PG8_LAS unsigned char* lds, const Gemm g, const Sched& S, const Epi& E, const int tid) {
;     ...
;             PG8_LDA(At, 1, 1); PG8_STAGE(PG8_SB(1, 0), b3, voffB); PG8_STAGE(PG8_SB(1, 1), b3 + hstep, voffB); PG8_STAGE(PG8_SA(1, 0), a3, voffA);
;             PG8_WAIT_V(8); PG8_WAIT_L(0); PG8_BAR; PG8_MMA(1, 0, At, B0); PG8_MMA(1, 1, At, B1); PG8_BAR; PG8_SCHED;
;     __device__ __forceinline__ void operator()(const f32x4 (&acc)[2][2][4][2], const Unit& u, int wr, int wc, int fr, int fq) const {
;     ...
;                 const int gcol = col - LDQ;
;                 const f32x4 b0 = *(const f32x4*)(bgate + gcol), b1 = *(const f32x4*)(bgate + gcol + 4);
	s_add_i32 s8, s27, s12
	v_lshl_add_u64 v[202:203], v[202:203], 0, s[94:95]
	s_mov_b32 m0, s8
	ds_read_b128 v[178:181], v143 offset:49152
	ds_read_b128 v[182:185], v143 offset:50176
	ds_read_b128 v[186:189], v143 offset:51200
	ds_read_b128 v[190:193], v143 offset:52224
	ds_read_b128 v[194:197], v143 offset:53248
	ds_read_b128 v[198:201], v143 offset:54272
	ds_read_b128 v[214:217], v143 offset:55296
	ds_read_b128 v[218:221], v143 offset:56320
	global_load_lds_dwordx4 v[202:203], off
	s_add_i32 m0, s8, 0x2000
	s_add_u32 s6, s6, 0x40080
	v_lshl_add_u64 v[202:203], v[206:207], 0, s[94:95]
	s_addc_u32 s7, s7, 0
	s_add_i32 s8, s28, s12
	global_load_lds_dwordx4 v[202:203], off
	v_lshl_add_u64 v[202:203], s[6:7], 0, v[64:65]
	s_mov_b32 m0, s8
	s_nop 0
	global_load_lds_dwordx4 v[202:203], off
	v_lshl_add_u64 v[202:203], s[6:7], 0, v[134:135]
	s_add_i32 m0, s8, 0x2000
	s_nop 0
	global_load_lds_dwordx4 v[202:203], off
	v_lshl_add_u64 v[202:203], v[208:209], 0, s[94:95]
	s_mov_b32 m0, s20
	s_nop 0
	global_load_lds_dwordx4 v[202:203], off
	v_lshl_add_u64 v[202:203], v[222:223], 0, s[94:95]
	s_mov_b32 m0, s21
	s_nop 0
	global_load_lds_dwordx4 v[202:203], off
	s_waitcnt vmcnt(8)
	s_waitcnt lgkmcnt(0)
	s_barrier
	s_setprio 1
	v_mfma_f32_16x16x32_bf16 v[94:97], v[144:147], v[178:181], v[94:97]
	v_mfma_f32_16x16x32_bf16 v[90:93], v[154:157], v[178:181], v[90:93]
	v_mfma_f32_16x16x32_bf16 v[86:89], v[144:147], v[186:189], v[86:89]
	v_mfma_f32_16x16x32_bf16 v[82:85], v[154:157], v[186:189], v[82:85]
	v_mfma_f32_16x16x32_bf16 v[78:81], v[144:147], v[194:197], v[78:81]
	v_mfma_f32_16x16x32_bf16 v[74:77], v[154:157], v[194:197], v[74:77]
	v_mfma_f32_16x16x32_bf16 v[70:73], v[144:147], v[214:217], v[70:73]
	v_mfma_f32_16x16x32_bf16 v[66:69], v[154:157], v[214:217], v[66:69]
	v_mfma_f32_16x16x32_bf16 v[94:97], v[150:153], v[182:185], v[94:97]
	v_mfma_f32_16x16x32_bf16 v[90:93], v[158:161], v[182:185], v[90:93]
	v_mfma_f32_16x16x32_bf16 v[86:89], v[150:153], v[190:193], v[86:89]
	v_mfma_f32_16x16x32_bf16 v[82:85], v[158:161], v[190:193], v[82:85]
	v_mfma_f32_16x16x32_bf16 v[78:81], v[150:153], v[198:201], v[78:81]
	v_mfma_f32_16x16x32_bf16 v[74:77], v[158:161], v[198:201], v[74:77]
	v_mfma_f32_16x16x32_bf16 v[70:73], v[150:153], v[218:221], v[70:73]
	v_mfma_f32_16x16x32_bf16 v[66:69], v[158:161], v[218:221], v[66:69]
	s_setprio 0
	s_setprio 1
	v_mfma_f32_16x16x32_bf16 v[28:31], v[162:165], v[178:181], v[28:31]
	v_mfma_f32_16x16x32_bf16 v[24:27], v[170:173], v[178:181], v[24:27]
	v_mfma_f32_16x16x32_bf16 v[20:23], v[162:165], v[186:189], v[20:23]
	v_mfma_f32_16x16x32_bf16 v[16:19], v[170:173], v[186:189], v[16:19]
	v_mfma_f32_16x16x32_bf16 v[12:15], v[162:165], v[194:197], v[12:15]
	v_mfma_f32_16x16x32_bf16 v[8:11], v[170:173], v[194:197], v[8:11]
	v_mfma_f32_16x16x32_bf16 v[4:7], v[162:165], v[214:217], v[4:7]
	v_mfma_f32_16x16x32_bf16 v[0:3], v[170:173], v[214:217], v[0:3]
	v_mfma_f32_16x16x32_bf16 v[28:31], v[166:169], v[182:185], v[28:31]
	v_mfma_f32_16x16x32_bf16 v[24:27], v[174:177], v[182:185], v[24:27]
	v_mfma_f32_16x16x32_bf16 v[20:23], v[166:169], v[190:193], v[20:23]
	v_mfma_f32_16x16x32_bf16 v[16:19], v[174:177], v[190:193], v[16:19]
	v_mfma_f32_16x16x32_bf16 v[12:15], v[166:169], v[198:201], v[12:15]
	v_mfma_f32_16x16x32_bf16 v[8:11], v[174:177], v[198:201], v[8:11]
	v_mfma_f32_16x16x32_bf16 v[4:7], v[166:169], v[218:221], v[4:7]
	v_mfma_f32_16x16x32_bf16 v[0:3], v[174:177], v[218:221], v[0:3]
	s_setprio 0
	s_barrier
	s_add_i32 s26, s26, 2
	s_add_u32 s4, s4, 0x100
	s_addc_u32 s5, s5, 0
	s_cmp_gt_u32 s26, 13
	s_cbranch_scc0 .LBB0_511
	s_and_b32 s12, 0xffff, s11
	s_lshl_b32 s13, s19, 8
	s_lshl_b32 s11, s12, 8
	s_and_b32 s2, s13, 0xff00
	s_and_b32 s14, 0xffff, s14
	v_or_b32_e32 v64, s15, v148
	s_cmpk_gt_u32 s14, 0x8f
	v_or_b32_e32 v186, s2, v64
	s_cselect_b64 s[2:3], -1, 0
	v_cmp_eq_u32_e64 s[0:1], 0, v141
	v_add_u32_e32 v187, s11, v140
	s_mov_b64 s[4:5], -1
	s_and_b64 vcc, exec, s[2:3]
	s_cbranch_vccz .LBB0_514
	v_add_u32_e32 v138, 0xffffee00, v186
	v_ashrrev_i32_e32 v139, 31, v138
	v_lshl_add_u64 v[134:135], v[138:139], 2, s[52:53]
	global_load_dwordx4 v[130:133], v[134:135], off offset:16
	s_nop 0
	global_load_dwordx4 v[134:137], v[134:135], off
	s_waitcnt vmcnt(0)
; __device__ __forceinline__ unsigned pk2(float lo, float hi) { f32x2_t v = {lo, hi}; bf16x2_t b = __builtin_convertvector(v, bf16x2_t); return __builtin_bit_cast(unsigned, b); }
; __device__ __forceinline__ float sigmoidf_(float x) { return __builtin_amdgcn_rcpf(1.0f + __expf(-x)); }
;     __device__ __forceinline__ void operator()(const f32x4 (&acc)[2][2][4][2], const Unit& u, int wr, int wc, int fr, int fq) const {
;     ...
;                 const int gcol = col - LDQ;
;                 const f32x4 b0 = *(const f32x4*)(bgate + gcol), b1 = *(const f32x4*)(bgate + gcol + 4);
; #pragma unroll
;                 for (int ai = 0; ai < 2; ++ai)
; #pragma unroll
;                     for (int m = 0; m < 4; ++m) {
;                         const int row = row0 + ai * 128 + m * 16;
;                         const f32x4 v0 = acc[ai][bj][m][0] + b0, v1 = acc[ai][bj][m][1] + b1;
;                         u32x4 w; w.x = pk2(sigmoidf_(v0[0]), sigmoidf_(v0[1])); w.y = pk2(sigmoidf_(v0[2]), sigmoidf_(v0[3]));
;                         w.z = pk2(sigmoidf_(v1[0]), sigmoidf_(v1[1])); w.w = pk2(sigmoidf_(v1[2]), sigmoidf_(v1[3]));
;                         __builtin_nontemporal_store(w, (u32x4*)(gates + (unsigned)(row * NG + gcol)));
	v_pk_add_f32 v[146:147], v[122:123], v[130:131]
	v_pk_add_f32 v[140:141], v[126:127], v[134:135]
	v_pk_add_f32 v[142:143], v[128:129], v[136:137]
	v_mul_f32_e32 v64, 0xbfb8aa3b, v140
	v_mul_f32_e32 v139, 0xbfb8aa3b, v141
	v_exp_f32_e32 v64, v64
	v_exp_f32_e32 v139, v139
	v_pk_add_f32 v[144:145], v[124:125], v[132:133]
	v_add_f32_e32 v64, 1.0, v64
	v_add_f32_e32 v139, 1.0, v139
	v_rcp_f32_e32 v64, v64
	v_rcp_f32_e32 v139, v139
	s_nop 0
	v_cvt_pk_bf16_f32 v140, v64, v139
	v_mul_f32_e32 v64, 0xbfb8aa3b, v142
	v_mul_f32_e32 v139, 0xbfb8aa3b, v143
	v_exp_f32_e32 v64, v64
	v_exp_f32_e32 v139, v139
	v_add_f32_e32 v64, 1.0, v64
	v_add_f32_e32 v139, 1.0, v139
	v_rcp_f32_e32 v64, v64
	v_rcp_f32_e32 v139, v139
	s_nop 0
	v_cvt_pk_bf16_f32 v141, v64, v139
	v_mul_f32_e32 v64, 0xbfb8aa3b, v146
	v_mul_f32_e32 v139, 0xbfb8aa3b, v147
	v_exp_f32_e32 v64, v64
	v_exp_f32_e32 v139, v139
	v_pk_add_f32 v[146:147], v[114:115], v[130:131]
	v_add_f32_e32 v64, 1.0, v64
	v_add_f32_e32 v139, 1.0, v139
	v_rcp_f32_e32 v64, v64
	v_rcp_f32_e32 v139, v139
	s_nop 0
	v_cvt_pk_bf16_f32 v142, v64, v139
	v_mul_f32_e32 v64, 0xbfb8aa3b, v144
	v_mul_f32_e32 v139, 0xbfb8aa3b, v145
	v_exp_f32_e32 v64, v64
	v_exp_f32_e32 v139, v139
	v_add_f32_e32 v64, 1.0, v64
	v_add_f32_e32 v139, 1.0, v139
	v_rcp_f32_e32 v64, v64
	v_rcp_f32_e32 v139, v139
	s_nop 0
	v_cvt_pk_bf16_f32 v143, v64, v139
	v_mad_u64_u32 v[138:139], s[4:5], v187, s76, v[138:139]
	v_mov_b32_e32 v139, v65
	v_lshl_add_u64 v[144:145], v[138:139], 1, s[36:37]
	flat_store_dwordx4 v[144:145], v[140:143] nt
	v_pk_add_f32 v[144:145], v[116:117], v[132:133]
	s_mov_b64 s[4:5], 0
	v_pk_add_f32 v[140:141], v[118:119], v[134:135]
	v_pk_add_f32 v[142:143], v[120:121], v[136:137]
	v_mul_f32_e32 v64, 0xbfb8aa3b, v140
	v_mul_f32_e32 v139, 0xbfb8aa3b, v141
	v_exp_f32_e32 v64, v64
	v_exp_f32_e32 v139, v139
	v_add_f32_e32 v64, 1.0, v64
	v_add_f32_e32 v139, 1.0, v139
	v_rcp_f32_e32 v64, v64
	v_rcp_f32_e32 v139, v139
	s_nop 0
	v_cvt_pk_bf16_f32 v140, v64, v139
	v_mul_f32_e32 v64, 0xbfb8aa3b, v142
	v_mul_f32_e32 v139, 0xbfb8aa3b, v143
	v_exp_f32_e32 v64, v64
	v_exp_f32_e32 v139, v139
	v_add_f32_e32 v64, 1.0, v64
	v_add_f32_e32 v139, 1.0, v139
	v_rcp_f32_e32 v64, v64
	v_rcp_f32_e32 v139, v139
	s_nop 0
	v_cvt_pk_bf16_f32 v141, v64, v139
	v_mul_f32_e32 v64, 0xbfb8aa3b, v146
	v_mul_f32_e32 v139, 0xbfb8aa3b, v147
	v_exp_f32_e32 v64, v64
	v_exp_f32_e32 v139, v139
	v_pk_add_f32 v[146:147], v[110:111], v[134:135]
	v_add_f32_e32 v64, 1.0, v64
	v_add_f32_e32 v139, 1.0, v139
	v_rcp_f32_e32 v64, v64
	v_rcp_f32_e32 v139, v139
	s_nop 0
	v_cvt_pk_bf16_f32 v142, v64, v139
	v_mul_f32_e32 v64, 0xbfb8aa3b, v144
	v_mul_f32_e32 v139, 0xbfb8aa3b, v145
	v_exp_f32_e32 v64, v64
	v_exp_f32_e32 v139, v139
	v_add_f32_e32 v64, 1.0, v64
	v_add_f32_e32 v139, 1.0, v139
	v_rcp_f32_e32 v64, v64
	v_rcp_f32_e32 v139, v139
	s_nop 0
	v_cvt_pk_bf16_f32 v143, v64, v139
	v_add_u32_e32 v64, 0xc000, v138
	v_lshl_add_u64 v[144:145], v[64:65], 1, s[36:37]
	v_mul_f32_e32 v64, 0xbfb8aa3b, v146
	v_mul_f32_e32 v139, 0xbfb8aa3b, v147
	v_exp_f32_e32 v64, v64
	v_exp_f32_e32 v139, v139
	flat_store_dwordx4 v[144:145], v[140:143] nt
	v_pk_add_f32 v[144:145], v[112:113], v[136:137]
	v_add_f32_e32 v64, 1.0, v64
	v_add_f32_e32 v139, 1.0, v139
	v_rcp_f32_e32 v64, v64
	v_rcp_f32_e32 v139, v139
	v_pk_add_f32 v[142:143], v[106:107], v[130:131]
	v_pk_add_f32 v[140:141], v[108:109], v[132:133]
	v_pk_add_f32 v[146:147], v[98:99], v[130:131]
	v_cvt_pk_bf16_f32 v150, v64, v139
	v_mul_f32_e32 v64, 0xbfb8aa3b, v144
	v_mul_f32_e32 v139, 0xbfb8aa3b, v145
	v_exp_f32_e32 v64, v64
	v_exp_f32_e32 v139, v139
	v_pk_add_f32 v[144:145], v[100:101], v[132:133]
	v_add_f32_e32 v64, 1.0, v64
	v_add_f32_e32 v139, 1.0, v139
	v_rcp_f32_e32 v64, v64
	v_rcp_f32_e32 v139, v139
	s_nop 0
	v_cvt_pk_bf16_f32 v151, v64, v139
	v_mul_f32_e32 v64, 0xbfb8aa3b, v142
	v_mul_f32_e32 v139, 0xbfb8aa3b, v143
	v_exp_f32_e32 v64, v64
	v_exp_f32_e32 v139, v139
	v_pk_add_f32 v[142:143], v[104:105], v[136:137]
	v_add_f32_e32 v64, 1.0, v64
	v_add_f32_e32 v139, 1.0, v139
	v_rcp_f32_e32 v64, v64
	v_rcp_f32_e32 v139, v139
	s_nop 0
	v_cvt_pk_bf16_f32 v152, v64, v139
	v_mul_f32_e32 v64, 0xbfb8aa3b, v140
	v_mul_f32_e32 v139, 0xbfb8aa3b, v141
	v_exp_f32_e32 v64, v64
	v_exp_f32_e32 v139, v139
	v_add_f32_e32 v64, 1.0, v64
	v_add_f32_e32 v139, 1.0, v139
	v_rcp_f32_e32 v64, v64
	v_rcp_f32_e32 v139, v139
	s_nop 0
	v_cvt_pk_bf16_f32 v153, v64, v139
	v_add_u32_e32 v64, 0x18000, v138
	v_lshl_add_u64 v[140:141], v[64:65], 1, s[36:37]
	flat_store_dwordx4 v[140:141], v[150:153] nt
	v_pk_add_f32 v[140:141], v[102:103], v[134:135]
	s_nop 0
	v_mul_f32_e32 v64, 0xbfb8aa3b, v140
	v_mul_f32_e32 v139, 0xbfb8aa3b, v141
	v_exp_f32_e32 v64, v64
	v_exp_f32_e32 v139, v139
	v_add_f32_e32 v64, 1.0, v64
	v_add_f32_e32 v139, 1.0, v139
	v_rcp_f32_e32 v64, v64
	v_rcp_f32_e32 v139, v139
	s_nop 0
	v_cvt_pk_bf16_f32 v140, v64, v139
	v_mul_f32_e32 v64, 0xbfb8aa3b, v142
	v_mul_f32_e32 v139, 0xbfb8aa3b, v143
	v_exp_f32_e32 v64, v64
	v_exp_f32_e32 v139, v139
	v_add_f32_e32 v64, 1.0, v64
	v_add_f32_e32 v139, 1.0, v139
	v_rcp_f32_e32 v64, v64
	v_rcp_f32_e32 v139, v139
	s_nop 0
	v_cvt_pk_bf16_f32 v141, v64, v139
	v_mul_f32_e32 v64, 0xbfb8aa3b, v146
	v_mul_f32_e32 v139, 0xbfb8aa3b, v147
	v_exp_f32_e32 v64, v64
	v_exp_f32_e32 v139, v139
	v_pk_add_f32 v[146:147], v[90:91], v[130:131]
	v_add_f32_e32 v64, 1.0, v64
	v_add_f32_e32 v139, 1.0, v139
	v_rcp_f32_e32 v64, v64
	v_rcp_f32_e32 v139, v139
	s_nop 0
	v_cvt_pk_bf16_f32 v142, v64, v139
	v_mul_f32_e32 v64, 0xbfb8aa3b, v144
	v_mul_f32_e32 v139, 0xbfb8aa3b, v145
	v_exp_f32_e32 v64, v64
	v_exp_f32_e32 v139, v139
	v_add_f32_e32 v64, 1.0, v64
; __device__ __forceinline__ unsigned pk2(float lo, float hi) { f32x2_t v = {lo, hi}; bf16x2_t b = __builtin_convertvector(v, bf16x2_t); return __builtin_bit_cast(unsigned, b); }
; __device__ __forceinline__ float sigmoidf_(float x) { return __builtin_amdgcn_rcpf(1.0f + __expf(-x)); }
;     __device__ __forceinline__ void operator()(const f32x4 (&acc)[2][2][4][2], const Unit& u, int wr, int wc, int fr, int fq) const {
;     ...
; #pragma unroll
;                 for (int ai = 0; ai < 2; ++ai)
; #pragma unroll
;                     for (int m = 0; m < 4; ++m) {
;                         const int row = row0 + ai * 128 + m * 16;
;                         const f32x4 v0 = acc[ai][bj][m][0] + b0, v1 = acc[ai][bj][m][1] + b1;
;                         u32x4 w; w.x = pk2(sigmoidf_(v0[0]), sigmoidf_(v0[1])); w.y = pk2(sigmoidf_(v0[2]), sigmoidf_(v0[3]));
;                         w.z = pk2(sigmoidf_(v1[0]), sigmoidf_(v1[1])); w.w = pk2(sigmoidf_(v1[2]), sigmoidf_(v1[3]));
;                         __builtin_nontemporal_store(w, (u32x4*)(gates + (unsigned)(row * NG + gcol)));
	v_add_f32_e32 v139, 1.0, v139
	v_rcp_f32_e32 v64, v64
	v_rcp_f32_e32 v139, v139
	s_nop 0
	v_cvt_pk_bf16_f32 v143, v64, v139
	v_add_u32_e32 v64, 0x24000, v138
	v_lshl_add_u64 v[144:145], v[64:65], 1, s[36:37]
	flat_store_dwordx4 v[144:145], v[140:143] nt
	v_pk_add_f32 v[144:145], v[92:93], v[132:133]
	s_nop 0
	v_pk_add_f32 v[140:141], v[94:95], v[134:135]
	v_pk_add_f32 v[142:143], v[96:97], v[136:137]
	v_mul_f32_e32 v64, 0xbfb8aa3b, v140
	v_mul_f32_e32 v139, 0xbfb8aa3b, v141
	v_exp_f32_e32 v64, v64
	v_exp_f32_e32 v139, v139
	v_add_f32_e32 v64, 1.0, v64
	v_add_f32_e32 v139, 1.0, v139
	v_rcp_f32_e32 v64, v64
	v_rcp_f32_e32 v139, v139
	s_nop 0
	v_cvt_pk_bf16_f32 v140, v64, v139
	v_mul_f32_e32 v64, 0xbfb8aa3b, v142
	v_mul_f32_e32 v139, 0xbfb8aa3b, v143
	v_exp_f32_e32 v64, v64
	v_exp_f32_e32 v139, v139
	v_add_f32_e32 v64, 1.0, v64
	v_add_f32_e32 v139, 1.0, v139
	v_rcp_f32_e32 v64, v64
	v_rcp_f32_e32 v139, v139
	s_nop 0
	v_cvt_pk_bf16_f32 v141, v64, v139
	v_mul_f32_e32 v64, 0xbfb8aa3b, v146
	v_mul_f32_e32 v139, 0xbfb8aa3b, v147
	v_exp_f32_e32 v64, v64
	v_exp_f32_e32 v139, v139
	v_pk_add_f32 v[146:147], v[82:83], v[130:131]
	v_add_f32_e32 v64, 1.0, v64
	v_add_f32_e32 v139, 1.0, v139
	v_rcp_f32_e32 v64, v64
	v_rcp_f32_e32 v139, v139
	s_nop 0
	v_cvt_pk_bf16_f32 v142, v64, v139
	v_mul_f32_e32 v64, 0xbfb8aa3b, v144
	v_mul_f32_e32 v139, 0xbfb8aa3b, v145
	v_exp_f32_e32 v64, v64
	v_exp_f32_e32 v139, v139
	v_add_f32_e32 v64, 1.0, v64
	v_add_f32_e32 v139, 1.0, v139
	v_rcp_f32_e32 v64, v64
	v_rcp_f32_e32 v139, v139
	s_nop 0
	v_cvt_pk_bf16_f32 v143, v64, v139
	v_add_u32_e32 v64, 0x60000, v138
	v_lshl_add_u64 v[144:145], v[64:65], 1, s[36:37]
	flat_store_dwordx4 v[144:145], v[140:143] nt
	v_pk_add_f32 v[144:145], v[84:85], v[132:133]
	s_nop 0
	v_pk_add_f32 v[140:141], v[86:87], v[134:135]
	v_pk_add_f32 v[142:143], v[88:89], v[136:137]
	v_mul_f32_e32 v64, 0xbfb8aa3b, v140
	v_mul_f32_e32 v139, 0xbfb8aa3b, v141
	v_exp_f32_e32 v64, v64
	v_exp_f32_e32 v139, v139
	v_add_f32_e32 v64, 1.0, v64
	v_add_f32_e32 v139, 1.0, v139
	v_rcp_f32_e32 v64, v64
	v_rcp_f32_e32 v139, v139
	s_nop 0
	v_cvt_pk_bf16_f32 v140, v64, v139
	v_mul_f32_e32 v64, 0xbfb8aa3b, v142
	v_mul_f32_e32 v139, 0xbfb8aa3b, v143
	v_exp_f32_e32 v64, v64
	v_exp_f32_e32 v139, v139
	v_add_f32_e32 v64, 1.0, v64
	v_add_f32_e32 v139, 1.0, v139
	v_rcp_f32_e32 v64, v64
	v_rcp_f32_e32 v139, v139
	s_nop 0
	v_cvt_pk_bf16_f32 v141, v64, v139
	v_mul_f32_e32 v64, 0xbfb8aa3b, v146
	v_mul_f32_e32 v139, 0xbfb8aa3b, v147
	v_exp_f32_e32 v64, v64
	v_exp_f32_e32 v139, v139
	v_pk_add_f32 v[146:147], v[74:75], v[130:131]
	v_add_f32_e32 v64, 1.0, v64
	v_add_f32_e32 v139, 1.0, v139
	v_rcp_f32_e32 v64, v64
	v_rcp_f32_e32 v139, v139
	s_nop 0
	v_cvt_pk_bf16_f32 v142, v64, v139
	v_mul_f32_e32 v64, 0xbfb8aa3b, v144
	v_mul_f32_e32 v139, 0xbfb8aa3b, v145
	v_exp_f32_e32 v64, v64
	v_exp_f32_e32 v139, v139
	v_add_f32_e32 v64, 1.0, v64
	v_add_f32_e32 v139, 1.0, v139
	v_rcp_f32_e32 v64, v64
	v_rcp_f32_e32 v139, v139
	s_nop 0
	v_cvt_pk_bf16_f32 v143, v64, v139
	v_add_u32_e32 v64, 0x6c000, v138
	v_lshl_add_u64 v[144:145], v[64:65], 1, s[36:37]
	flat_store_dwordx4 v[144:145], v[140:143] nt
	v_pk_add_f32 v[144:145], v[76:77], v[132:133]
	s_nop 0
	v_pk_add_f32 v[140:141], v[78:79], v[134:135]
	v_pk_add_f32 v[142:143], v[80:81], v[136:137]
	v_mul_f32_e32 v64, 0xbfb8aa3b, v140
	v_mul_f32_e32 v139, 0xbfb8aa3b, v141
	v_exp_f32_e32 v64, v64
	v_exp_f32_e32 v139, v139
	v_pk_add_f32 v[134:135], v[70:71], v[134:135]
	v_pk_add_f32 v[136:137], v[72:73], v[136:137]
	v_add_f32_e32 v64, 1.0, v64
	v_add_f32_e32 v139, 1.0, v139
	v_rcp_f32_e32 v64, v64
	v_rcp_f32_e32 v139, v139
	s_nop 0
	v_cvt_pk_bf16_f32 v140, v64, v139
	v_mul_f32_e32 v64, 0xbfb8aa3b, v142
	v_mul_f32_e32 v139, 0xbfb8aa3b, v143
	v_exp_f32_e32 v64, v64
	v_exp_f32_e32 v139, v139
	v_add_f32_e32 v64, 1.0, v64
	v_add_f32_e32 v139, 1.0, v139
	v_rcp_f32_e32 v64, v64
	v_rcp_f32_e32 v139, v139
	s_nop 0
	v_cvt_pk_bf16_f32 v141, v64, v139
	v_mul_f32_e32 v64, 0xbfb8aa3b, v146
	v_mul_f32_e32 v139, 0xbfb8aa3b, v147
	v_exp_f32_e32 v64, v64
	v_exp_f32_e32 v139, v139
	v_add_f32_e32 v64, 1.0, v64
	v_add_f32_e32 v139, 1.0, v139
	v_rcp_f32_e32 v64, v64
	v_rcp_f32_e32 v139, v139
	s_nop 0
	v_cvt_pk_bf16_f32 v142, v64, v139
	v_mul_f32_e32 v64, 0xbfb8aa3b, v144
	v_mul_f32_e32 v139, 0xbfb8aa3b, v145
	v_exp_f32_e32 v64, v64
	v_exp_f32_e32 v139, v139
	v_add_f32_e32 v64, 1.0, v64
	v_add_f32_e32 v139, 1.0, v139
	v_rcp_f32_e32 v64, v64
	v_rcp_f32_e32 v139, v139
	s_nop 0
	v_cvt_pk_bf16_f32 v143, v64, v139
	v_add_u32_e32 v64, 0x78000, v138
	v_lshl_add_u64 v[144:145], v[64:65], 1, s[36:37]
	flat_store_dwordx4 v[144:145], v[140:143] nt
	v_mul_f32_e32 v64, 0xbfb8aa3b, v134
	v_exp_f32_e32 v64, v64
	v_pk_add_f32 v[140:141], v[68:69], v[132:133]
	v_pk_add_f32 v[132:133], v[66:67], v[130:131]
	v_mul_f32_e32 v130, 0xbfb8aa3b, v135
	v_exp_f32_e32 v130, v130
	v_add_f32_e32 v64, 1.0, v64
	v_rcp_f32_e32 v64, v64
	v_mul_f32_e32 v131, 0xbfb8aa3b, v137
	v_add_f32_e32 v130, 1.0, v130
	v_rcp_f32_e32 v130, v130
	v_exp_f32_e32 v131, v131
	v_cvt_pk_bf16_f32 v130, v64, v130
	v_mul_f32_e32 v64, 0xbfb8aa3b, v136
	v_exp_f32_e32 v64, v64
	v_add_f32_e32 v131, 1.0, v131
	v_rcp_f32_e32 v131, v131
	v_add_f32_e32 v64, 1.0, v64
	v_rcp_f32_e32 v64, v64
	s_nop 0
	v_cvt_pk_bf16_f32 v131, v64, v131
	v_mul_f32_e32 v64, 0xbfb8aa3b, v132
	v_mul_f32_e32 v132, 0xbfb8aa3b, v133
	v_exp_f32_e32 v64, v64
	v_exp_f32_e32 v132, v132
	v_mul_f32_e32 v133, 0xbfb8aa3b, v141
	v_exp_f32_e32 v133, v133
	v_add_f32_e32 v64, 1.0, v64
	v_add_f32_e32 v132, 1.0, v132
	v_rcp_f32_e32 v64, v64
	v_rcp_f32_e32 v132, v132
	v_add_f32_e32 v133, 1.0, v133
	v_rcp_f32_e32 v133, v133
	v_cvt_pk_bf16_f32 v132, v64, v132
	v_mul_f32_e32 v64, 0xbfb8aa3b, v140
	v_exp_f32_e32 v64, v64
	s_nop 0
	v_add_f32_e32 v64, 1.0, v64
	v_rcp_f32_e32 v64, v64
	s_nop 0
	v_cvt_pk_bf16_f32 v133, v64, v133
	v_add_u32_e32 v64, 0x84000, v138
	v_lshl_add_u64 v[134:135], v[64:65], 1, s[36:37]
	flat_store_dwordx4 v[134:135], v[130:133] nt

; #define PG8_STAGE(bufoff, gbase, voff) do { _Pragma("unroll") for (int _i = 0; _i < 2; ++_i) \
;         __builtin_amdgcn_global_load_lds((const unsigned*)((const char*)(gbase) + (voff)[_i]), (PG8_LAS unsigned*)(lds + (bufoff) + ldsw + _i * 8192), 16, 0, 0); } while (0)
; #define PG8_LDA(dst, b, h) do { _Pragma("unroll") for (int m = 0; m < 4; ++m) _Pragma("unroll") for (int k = 0; k < 2; ++k) dst[m][k] = *(const PG8_LAS bf16x8*)(lds + PG8_SA(b, h) + aoff + m * 2048 + k * 1024); } while (0)
; #define PG8_LDB(dst, b, h) do { _Pragma("unroll") for (int n = 0; n < 2; ++n) _Pragma("unroll") for (int k = 0; k < 2; ++k) dst[n][k] = *(const PG8_LAS bf16x8*)(lds + PG8_SB(b, h) + boff + n * 2048 + k * 1024); } while (0)
; #define PG8_MMA(ai, bj, At, Bt) do { __builtin_amdgcn_s_setprio(1); _Pragma("unroll") for (int m = 0; m < 4; ++m) _Pragma("unroll") for (int n = 0; n < 2; ++n) _Pragma("unroll") for (int k = 0; k < 2; ++k) \
;         acc[ai][bj][m][n] = __builtin_amdgcn_mfma_f32_16x16x32_bf16(Bt[n][k], At[m][k], acc[ai][bj][m][n], 0, 0, 0); __builtin_amdgcn_s_setprio(0); } while (0)
; #define PG8_WAIT_V(n) asm volatile("s_waitcnt vmcnt(" #n ")" ::: "memory")
; #define PG8_WAIT_L(n) asm volatile("s_waitcnt lgkmcnt(" #n ")" ::: "memory")
; template <class Epi, class Sched, bool ALIGN_EPI = false, bool SP2 = false>
; __device__ __forceinline__ void gemm_phase(PG8_LAS unsigned char* lds, const Gemm g, const Sched& S, const Epi& E, const int tid) {
;     ...
;             const bool last = (t == nt - 2);
;             const char* a1 = cA + (size_t)(t + 1) * kstep;
;             const char* a2 = last ? nA : cA + (size_t)(t + 2) * kstep; const char* b2 = last ? nB : cB + (size_t)(t + 2) * kstep;
;             const char* a3 = a2 + kstep; const char* b3 = b2 + kstep;
;             if (last && has_next) S.a_ready(nxt);
;             if constexpr (SP2) {
;             PG8_LDB(B0, 0, 0); PG8_LDB(B1, 0, 1); PG8_SCHED; PG8_LDA(At, 0, 0); PG8_STAGE(PG8_SA(1, 1), a1 + hstep, voffA);
;             PG8_WAIT_V(8); PG8_WAIT_L(0); PG8_BAR; PG8_MMA(0, 0, At, B0); PG8_MMA(0, 1, At, B1); PG8_BAR; PG8_SCHED;
;             PG8_LDA(At, 0, 1); PG8_STAGE(PG8_SB(0, 0), b2, voffB); PG8_STAGE(PG8_SB(0, 1), b2 + hstep, voffB); PG8_STAGE(PG8_SA(0, 0), a2, voffA);
;             PG8_WAIT_V(8); PG8_WAIT_L(0); PG8_BAR; PG8_MMA(1, 0, At, B0); PG8_MMA(1, 1, At, B1); PG8_BAR; PG8_SCHED;
.LBB0_704:
	s_add_u32 s24, s2, 0xfffc0080
	s_addc_u32 s25, s3, -1
	s_add_i32 s51, 0, 0x10000
	s_cmp_eq_u32 s50, 12
	s_cselect_b32 s27, s17, s25
	s_cselect_b32 s26, s29, s24
	v_add_u32_e32 v64, s51, v213
	s_cselect_b32 s25, s15, s49
	s_cselect_b32 s24, s47, s48
	s_add_i32 s54, 0, 0x14000
	ds_read_b128 v[130:133], v64
	ds_read_b128 v[134:137], v64 offset:1024
	ds_read_b128 v[138:141], v64 offset:2048
	ds_read_b128 v[142:145], v64 offset:3072
	v_add_u32_e32 v64, s54, v213
	ds_read_b128 v[146:149], v64
	ds_read_b128 v[150:153], v64 offset:1024
	ds_read_b128 v[154:157], v64 offset:2048
	ds_read_b128 v[158:161], v64 offset:3072
	v_lshl_add_u64 v[202:203], s[2:3], 0, v[198:199]
	s_add_i32 m0, s35, 0xc000
	ds_read_b128 v[162:165], v227
	ds_read_b128 v[166:169], v227 offset:1024
	ds_read_b128 v[170:173], v227 offset:2048
	ds_read_b128 v[174:177], v227 offset:3072
	ds_read_b128 v[178:181], v227 offset:4096
	ds_read_b128 v[182:185], v227 offset:5120
	ds_read_b128 v[218:221], v227 offset:6144
	ds_read_b128 v[222:225], v227 offset:7168
	global_load_lds_dwordx4 v[202:203], off
	v_lshl_add_u64 v[202:203], s[2:3], 0, v[196:197]
	s_add_i32 m0, s35, 0xe000
	s_nop 0
	global_load_lds_dwordx4 v[202:203], off
	s_waitcnt vmcnt(8)
	s_waitcnt lgkmcnt(0)
	s_barrier
	s_setprio 1
	v_mfma_f32_16x16x32_bf16 v[126:129], v[130:133], v[162:165], v[126:129]
	v_mfma_f32_16x16x32_bf16 v[122:125], v[138:141], v[162:165], v[122:125]
	v_mfma_f32_16x16x32_bf16 v[118:121], v[130:133], v[170:173], v[118:121]
	v_mfma_f32_16x16x32_bf16 v[114:117], v[138:141], v[170:173], v[114:117]
	v_mfma_f32_16x16x32_bf16 v[110:113], v[130:133], v[178:181], v[110:113]
	v_mfma_f32_16x16x32_bf16 v[106:109], v[138:141], v[178:181], v[106:109]
	v_mfma_f32_16x16x32_bf16 v[102:105], v[130:133], v[218:221], v[102:105]
	v_mfma_f32_16x16x32_bf16 v[98:101], v[138:141], v[218:221], v[98:101]
	v_mfma_f32_16x16x32_bf16 v[126:129], v[134:137], v[166:169], v[126:129]
	v_mfma_f32_16x16x32_bf16 v[122:125], v[142:145], v[166:169], v[122:125]
	v_mfma_f32_16x16x32_bf16 v[118:121], v[134:137], v[174:177], v[118:121]
	v_mfma_f32_16x16x32_bf16 v[114:117], v[142:145], v[174:177], v[114:117]
	v_mfma_f32_16x16x32_bf16 v[110:113], v[134:137], v[182:185], v[110:113]
	v_mfma_f32_16x16x32_bf16 v[106:109], v[142:145], v[182:185], v[106:109]
	v_mfma_f32_16x16x32_bf16 v[102:105], v[134:137], v[222:225], v[102:105]
	v_mfma_f32_16x16x32_bf16 v[98:101], v[142:145], v[222:225], v[98:101]
	s_setprio 0
	s_setprio 1
	v_mfma_f32_16x16x32_bf16 v[60:63], v[146:149], v[162:165], v[60:63]
	v_mfma_f32_16x16x32_bf16 v[56:59], v[154:157], v[162:165], v[56:59]
	v_mfma_f32_16x16x32_bf16 v[52:55], v[146:149], v[170:173], v[52:55]
	v_mfma_f32_16x16x32_bf16 v[48:51], v[154:157], v[170:173], v[48:51]
	v_mfma_f32_16x16x32_bf16 v[44:47], v[146:149], v[178:181], v[44:47]
	v_mfma_f32_16x16x32_bf16 v[40:43], v[154:157], v[178:181], v[40:43]
	v_mfma_f32_16x16x32_bf16 v[36:39], v[146:149], v[218:221], v[36:39]
	v_mfma_f32_16x16x32_bf16 v[32:35], v[154:157], v[218:221], v[32:35]
	v_mfma_f32_16x16x32_bf16 v[60:63], v[150:153], v[166:169], v[60:63]
	v_mfma_f32_16x16x32_bf16 v[56:59], v[158:161], v[166:169], v[56:59]
	v_mfma_f32_16x16x32_bf16 v[52:55], v[150:153], v[174:177], v[52:55]
	v_mfma_f32_16x16x32_bf16 v[48:51], v[158:161], v[174:177], v[48:51]
	v_mfma_f32_16x16x32_bf16 v[44:47], v[150:153], v[182:185], v[44:47]
	v_mfma_f32_16x16x32_bf16 v[40:43], v[158:161], v[182:185], v[40:43]
	v_mfma_f32_16x16x32_bf16 v[36:39], v[150:153], v[222:225], v[36:39]
	v_mfma_f32_16x16x32_bf16 v[32:35], v[158:161], v[222:225], v[32:35]
	s_setprio 0
	s_barrier
	s_add_i32 s51, s51, s34
	v_lshl_add_u64 v[202:203], s[24:25], 0, v[190:191]
	s_mov_b32 m0, s51
	ds_read_b128 v[162:165], v227 offset:16384
	ds_read_b128 v[166:169], v227 offset:17408
	ds_read_b128 v[170:173], v227 offset:18432
	ds_read_b128 v[174:177], v227 offset:19456
	ds_read_b128 v[178:181], v227 offset:20480
	ds_read_b128 v[182:185], v227 offset:21504
	ds_read_b128 v[218:221], v227 offset:22528
	ds_read_b128 v[222:225], v227 offset:23552
	global_load_lds_dwordx4 v[202:203], off
	s_add_i32 m0, s51, 0x2000
	s_add_u32 s52, s24, 0x40000
	v_lshl_add_u64 v[206:207], s[24:25], 0, v[186:187]
	s_addc_u32 s53, s25, 0
	s_add_i32 s51, s54, s34
	global_load_lds_dwordx4 v[206:207], off
	v_lshl_add_u64 v[208:209], s[52:53], 0, v[190:191]
	s_mov_b32 m0, s51
	v_lshl_add_u64 v[214:215], s[26:27], 0, v[188:189]
	global_load_lds_dwordx4 v[208:209], off
	v_lshl_add_u64 v[208:209], s[52:53], 0, v[186:187]
	s_add_i32 m0, s51, 0x2000
	s_nop 0
	global_load_lds_dwordx4 v[208:209], off
	v_lshl_add_u64 v[208:209], s[26:27], 0, v[192:193]
	s_mov_b32 m0, s35
	s_nop 0
	global_load_lds_dwordx4 v[208:209], off
	s_mov_b32 m0, s39
	s_nop 0
	global_load_lds_dwordx4 v[214:215], off
	s_waitcnt vmcnt(8)
	s_waitcnt lgkmcnt(0)
	s_barrier
; #define PG8_STAGE(bufoff, gbase, voff) do { _Pragma("unroll") for (int _i = 0; _i < 2; ++_i) \
;         __builtin_amdgcn_global_load_lds((const unsigned*)((const char*)(gbase) + (voff)[_i]), (PG8_LAS unsigned*)(lds + (bufoff) + ldsw + _i * 8192), 16, 0, 0); } while (0)
; #define PG8_LDA(dst, b, h) do { _Pragma("unroll") for (int m = 0; m < 4; ++m) _Pragma("unroll") for (int k = 0; k < 2; ++k) dst[m][k] = *(const PG8_LAS bf16x8*)(lds + PG8_SA(b, h) + aoff + m * 2048 + k * 1024); } while (0)
; #define PG8_LDB(dst, b, h) do { _Pragma("unroll") for (int n = 0; n < 2; ++n) _Pragma("unroll") for (int k = 0; k < 2; ++k) dst[n][k] = *(const PG8_LAS bf16x8*)(lds + PG8_SB(b, h) + boff + n * 2048 + k * 1024); } while (0)
; #define PG8_MMA(ai, bj, At, Bt) do { __builtin_amdgcn_s_setprio(1); _Pragma("unroll") for (int m = 0; m < 4; ++m) _Pragma("unroll") for (int n = 0; n < 2; ++n) _Pragma("unroll") for (int k = 0; k < 2; ++k) \
;         acc[ai][bj][m][n] = __builtin_amdgcn_mfma_f32_16x16x32_bf16(Bt[n][k], At[m][k], acc[ai][bj][m][n], 0, 0, 0); __builtin_amdgcn_s_setprio(0); } while (0)
; #define PG8_WAIT_V(n) asm volatile("s_waitcnt vmcnt(" #n ")" ::: "memory")
; #define PG8_WAIT_L(n) asm volatile("s_waitcnt lgkmcnt(" #n ")" ::: "memory")
; #define PG8_BAR __builtin_amdgcn_s_barrier()
; #define PG8_SCHED __builtin_amdgcn_sched_barrier(0)
; template <class Epi, class Sched, bool ALIGN_EPI = false, bool SP2 = false>
; __device__ __forceinline__ void gemm_phase(PG8_LAS unsigned char* lds, const Gemm g, const Sched& S, const Epi& E, const int tid) {
;     ...
;             PG8_WAIT_V(8); PG8_WAIT_L(0); PG8_BAR; PG8_MMA(1, 0, At, B0); PG8_MMA(1, 1, At, B1); PG8_BAR; PG8_SCHED;
;             PG8_LDB(B0, 1, 0); PG8_LDB(B1, 1, 1); PG8_SCHED; PG8_LDA(At, 1, 0); PG8_STAGE(PG8_SA(0, 1), a2 + hstep, voffA);
;             PG8_WAIT_V(8); PG8_WAIT_L(0); PG8_BAR; PG8_MMA(0, 0, At, B0); PG8_MMA(0, 1, At, B1); PG8_BAR; PG8_SCHED;
	s_setprio 1
	v_mfma_f32_16x16x32_bf16 v[94:97], v[130:133], v[162:165], v[94:97]
	v_mfma_f32_16x16x32_bf16 v[90:93], v[138:141], v[162:165], v[90:93]
	v_mfma_f32_16x16x32_bf16 v[86:89], v[130:133], v[170:173], v[86:89]
	v_mfma_f32_16x16x32_bf16 v[82:85], v[138:141], v[170:173], v[82:85]
	v_mfma_f32_16x16x32_bf16 v[78:81], v[130:133], v[178:181], v[78:81]
	v_mfma_f32_16x16x32_bf16 v[74:77], v[138:141], v[178:181], v[74:77]
	v_mfma_f32_16x16x32_bf16 v[70:73], v[130:133], v[218:221], v[70:73]
	v_mfma_f32_16x16x32_bf16 v[66:69], v[138:141], v[218:221], v[66:69]
	v_mfma_f32_16x16x32_bf16 v[94:97], v[134:137], v[166:169], v[94:97]
	v_mfma_f32_16x16x32_bf16 v[90:93], v[142:145], v[166:169], v[90:93]
	v_mfma_f32_16x16x32_bf16 v[86:89], v[134:137], v[174:177], v[86:89]
	v_mfma_f32_16x16x32_bf16 v[82:85], v[142:145], v[174:177], v[82:85]
	v_mfma_f32_16x16x32_bf16 v[78:81], v[134:137], v[182:185], v[78:81]
	v_mfma_f32_16x16x32_bf16 v[74:77], v[142:145], v[182:185], v[74:77]
	v_mfma_f32_16x16x32_bf16 v[70:73], v[134:137], v[222:225], v[70:73]
	v_mfma_f32_16x16x32_bf16 v[66:69], v[142:145], v[222:225], v[66:69]
	s_setprio 0
	s_setprio 1
	v_mfma_f32_16x16x32_bf16 v[28:31], v[146:149], v[162:165], v[28:31]
	v_mfma_f32_16x16x32_bf16 v[24:27], v[154:157], v[162:165], v[24:27]
	v_mfma_f32_16x16x32_bf16 v[20:23], v[146:149], v[170:173], v[20:23]
	v_mfma_f32_16x16x32_bf16 v[16:19], v[154:157], v[170:173], v[16:19]
	v_mfma_f32_16x16x32_bf16 v[12:15], v[146:149], v[178:181], v[12:15]
	v_mfma_f32_16x16x32_bf16 v[8:11], v[154:157], v[178:181], v[8:11]
	v_mfma_f32_16x16x32_bf16 v[4:7], v[146:149], v[218:221], v[4:7]
	v_mfma_f32_16x16x32_bf16 v[0:3], v[154:157], v[218:221], v[0:3]
	v_mfma_f32_16x16x32_bf16 v[28:31], v[150:153], v[166:169], v[28:31]
	v_mfma_f32_16x16x32_bf16 v[24:27], v[158:161], v[166:169], v[24:27]
	v_mfma_f32_16x16x32_bf16 v[20:23], v[150:153], v[174:177], v[20:23]
	v_mfma_f32_16x16x32_bf16 v[16:19], v[158:161], v[174:177], v[16:19]
	v_mfma_f32_16x16x32_bf16 v[12:15], v[150:153], v[182:185], v[12:15]
	v_mfma_f32_16x16x32_bf16 v[8:11], v[158:161], v[182:185], v[8:11]
	v_mfma_f32_16x16x32_bf16 v[4:7], v[150:153], v[222:225], v[4:7]
	v_mfma_f32_16x16x32_bf16 v[0:3], v[158:161], v[222:225], v[0:3]
	s_setprio 0
	s_barrier
	s_add_i32 s51, 0, 0x18000
	v_add_u32_e32 v64, s51, v213
	s_add_i32 s52, 0, 0x1c000
	ds_read_b128 v[130:133], v64
	ds_read_b128 v[134:137], v64 offset:1024
	ds_read_b128 v[138:141], v64 offset:2048
	ds_read_b128 v[142:145], v64 offset:3072
	v_add_u32_e32 v64, s52, v213
	ds_read_b128 v[146:149], v64
	ds_read_b128 v[150:153], v64 offset:1024
	ds_read_b128 v[154:157], v64 offset:2048
	ds_read_b128 v[158:161], v64 offset:3072
	s_add_u32 s26, s26, 0x40000
	s_addc_u32 s27, s27, 0
	s_mov_b32 m0, s42
	v_lshl_add_u64 v[228:229], s[26:27], 0, v[192:193]
	ds_read_b128 v[162:165], v227 offset:32768
	ds_read_b128 v[166:169], v227 offset:33792
	ds_read_b128 v[170:173], v227 offset:34816
	ds_read_b128 v[174:177], v227 offset:35840
	ds_read_b128 v[178:181], v227 offset:36864
	ds_read_b128 v[182:185], v227 offset:37888
	ds_read_b128 v[218:221], v227 offset:38912
	ds_read_b128 v[222:225], v227 offset:39936
	global_load_lds_dwordx4 v[228:229], off
	v_lshl_add_u64 v[228:229], s[26:27], 0, v[188:189]
	s_mov_b32 m0, s43
	s_nop 0
	global_load_lds_dwordx4 v[228:229], off
	s_waitcnt vmcnt(8)
	s_waitcnt lgkmcnt(0)
	s_barrier
	s_setprio 1
	v_mfma_f32_16x16x32_bf16 v[126:129], v[130:133], v[162:165], v[126:129]
	v_mfma_f32_16x16x32_bf16 v[122:125], v[138:141], v[162:165], v[122:125]
	v_mfma_f32_16x16x32_bf16 v[118:121], v[130:133], v[170:173], v[118:121]
	v_mfma_f32_16x16x32_bf16 v[114:117], v[138:141], v[170:173], v[114:117]
	v_mfma_f32_16x16x32_bf16 v[110:113], v[130:133], v[178:181], v[110:113]
	v_mfma_f32_16x16x32_bf16 v[106:109], v[138:141], v[178:181], v[106:109]
	v_mfma_f32_16x16x32_bf16 v[102:105], v[130:133], v[218:221], v[102:105]
	v_mfma_f32_16x16x32_bf16 v[98:101], v[138:141], v[218:221], v[98:101]
	v_mfma_f32_16x16x32_bf16 v[126:129], v[134:137], v[166:169], v[126:129]
	v_mfma_f32_16x16x32_bf16 v[122:125], v[142:145], v[166:169], v[122:125]
	v_mfma_f32_16x16x32_bf16 v[118:121], v[134:137], v[174:177], v[118:121]
	v_mfma_f32_16x16x32_bf16 v[114:117], v[142:145], v[174:177], v[114:117]
	v_mfma_f32_16x16x32_bf16 v[110:113], v[134:137], v[182:185], v[110:113]
	v_mfma_f32_16x16x32_bf16 v[106:109], v[142:145], v[182:185], v[106:109]
	v_mfma_f32_16x16x32_bf16 v[102:105], v[134:137], v[222:225], v[102:105]
	v_mfma_f32_16x16x32_bf16 v[98:101], v[142:145], v[222:225], v[98:101]
	s_setprio 0
	s_setprio 1
	v_mfma_f32_16x16x32_bf16 v[60:63], v[146:149], v[162:165], v[60:63]
	v_mfma_f32_16x16x32_bf16 v[56:59], v[154:157], v[162:165], v[56:59]
	v_mfma_f32_16x16x32_bf16 v[52:55], v[146:149], v[170:173], v[52:55]
	v_mfma_f32_16x16x32_bf16 v[48:51], v[154:157], v[170:173], v[48:51]
	v_mfma_f32_16x16x32_bf16 v[44:47], v[146:149], v[178:181], v[44:47]
	v_mfma_f32_16x16x32_bf16 v[40:43], v[154:157], v[178:181], v[40:43]
	v_mfma_f32_16x16x32_bf16 v[36:39], v[146:149], v[218:221], v[36:39]
	v_mfma_f32_16x16x32_bf16 v[32:35], v[154:157], v[218:221], v[32:35]
	v_mfma_f32_16x16x32_bf16 v[60:63], v[150:153], v[166:169], v[60:63]
	v_mfma_f32_16x16x32_bf16 v[56:59], v[158:161], v[166:169], v[56:59]
	v_mfma_f32_16x16x32_bf16 v[52:55], v[150:153], v[174:177], v[52:55]
	v_mfma_f32_16x16x32_bf16 v[48:51], v[158:161], v[174:177], v[48:51]
	v_mfma_f32_16x16x32_bf16 v[44:47], v[150:153], v[182:185], v[44:47]
	v_mfma_f32_16x16x32_bf16 v[40:43], v[158:161], v[182:185], v[40:43]
	v_mfma_f32_16x16x32_bf16 v[36:39], v[150:153], v[222:225], v[36:39]
	v_mfma_f32_16x16x32_bf16 v[32:35], v[158:161], v[222:225], v[32:35]
	s_setprio 0
	s_barrier
; #define PG8_STAGE(bufoff, gbase, voff) do { _Pragma("unroll") for (int _i = 0; _i < 2; ++_i) \
;         __builtin_amdgcn_global_load_lds((const unsigned*)((const char*)(gbase) + (voff)[_i]), (PG8_LAS unsigned*)(lds + (bufoff) + ldsw + _i * 8192), 16, 0, 0); } while (0)
; #define PG8_LDA(dst, b, h) do { _Pragma("unroll") for (int m = 0; m < 4; ++m) _Pragma("unroll") for (int k = 0; k < 2; ++k) dst[m][k] = *(const PG8_LAS bf16x8*)(lds + PG8_SA(b, h) + aoff + m * 2048 + k * 1024); } while (0)
; #define PG8_MMA(ai, bj, At, Bt) do { __builtin_amdgcn_s_setprio(1); _Pragma("unroll") for (int m = 0; m < 4; ++m) _Pragma("unroll") for (int n = 0; n < 2; ++n) _Pragma("unroll") for (int k = 0; k < 2; ++k) \
;         acc[ai][bj][m][n] = __builtin_amdgcn_mfma_f32_16x16x32_bf16(Bt[n][k], At[m][k], acc[ai][bj][m][n], 0, 0, 0); __builtin_amdgcn_s_setprio(0); } while (0)
; #define PG8_WAIT_V(n) asm volatile("s_waitcnt vmcnt(" #n ")" ::: "memory")
; #define PG8_WAIT_L(n) asm volatile("s_waitcnt lgkmcnt(" #n ")" ::: "memory")
; #define PG8_BAR __builtin_amdgcn_s_barrier()
; #define PG8_SCHED __builtin_amdgcn_sched_barrier(0)
; template <class Epi, class Sched, bool ALIGN_EPI = false, bool SP2 = false>
; __device__ __forceinline__ void gemm_phase(PG8_LAS unsigned char* lds, const Gemm g, const Sched& S, const Epi& E, const int tid) {
;     ...
;             PG8_LDA(At, 1, 1); PG8_STAGE(PG8_SB(1, 0), b3, voffB); PG8_STAGE(PG8_SB(1, 1), b3 + hstep, voffB); PG8_STAGE(PG8_SA(1, 0), a3, voffA);
;             PG8_WAIT_V(8); PG8_WAIT_L(0); PG8_BAR; PG8_MMA(1, 0, At, B0); PG8_MMA(1, 1, At, B1); PG8_BAR; PG8_SCHED;
;     ...
;         if constexpr (ALIGN_EPI) { if (wr == 0) PG8_BAR; }
	s_add_i32 s26, s51, s34
	v_lshl_add_u64 v[202:203], v[202:203], 0, s[94:95]
	s_mov_b32 m0, s26
	ds_read_b128 v[162:165], v227 offset:49152
	ds_read_b128 v[166:169], v227 offset:50176
	ds_read_b128 v[170:173], v227 offset:51200
	ds_read_b128 v[174:177], v227 offset:52224
	ds_read_b128 v[178:181], v227 offset:53248
	ds_read_b128 v[182:185], v227 offset:54272
	ds_read_b128 v[218:221], v227 offset:55296
	ds_read_b128 v[222:225], v227 offset:56320
	global_load_lds_dwordx4 v[202:203], off
	s_add_i32 m0, s26, 0x2000
	s_add_u32 s24, s24, 0x40080
	v_lshl_add_u64 v[202:203], v[206:207], 0, s[94:95]
	s_addc_u32 s25, s25, 0
	s_add_i32 s26, s52, s34
	global_load_lds_dwordx4 v[202:203], off
	v_lshl_add_u64 v[202:203], s[24:25], 0, v[190:191]
	s_mov_b32 m0, s26
	s_nop 0
	global_load_lds_dwordx4 v[202:203], off
	v_lshl_add_u64 v[202:203], s[24:25], 0, v[186:187]
	s_add_i32 m0, s26, 0x2000
	s_nop 0
	global_load_lds_dwordx4 v[202:203], off
	v_lshl_add_u64 v[202:203], v[208:209], 0, s[94:95]
	s_mov_b32 m0, s38
	s_nop 0
	global_load_lds_dwordx4 v[202:203], off
	v_lshl_add_u64 v[202:203], v[214:215], 0, s[94:95]
	s_mov_b32 m0, s44
	s_nop 0
	global_load_lds_dwordx4 v[202:203], off
	s_waitcnt vmcnt(8)
	s_waitcnt lgkmcnt(0)
	s_barrier
	s_setprio 1
	v_mfma_f32_16x16x32_bf16 v[94:97], v[130:133], v[162:165], v[94:97]
	v_mfma_f32_16x16x32_bf16 v[90:93], v[138:141], v[162:165], v[90:93]
	v_mfma_f32_16x16x32_bf16 v[86:89], v[130:133], v[170:173], v[86:89]
	v_mfma_f32_16x16x32_bf16 v[82:85], v[138:141], v[170:173], v[82:85]
	v_mfma_f32_16x16x32_bf16 v[78:81], v[130:133], v[178:181], v[78:81]
	v_mfma_f32_16x16x32_bf16 v[74:77], v[138:141], v[178:181], v[74:77]
	v_mfma_f32_16x16x32_bf16 v[70:73], v[130:133], v[218:221], v[70:73]
	v_mfma_f32_16x16x32_bf16 v[66:69], v[138:141], v[218:221], v[66:69]
	v_mfma_f32_16x16x32_bf16 v[94:97], v[134:137], v[166:169], v[94:97]
	v_mfma_f32_16x16x32_bf16 v[90:93], v[142:145], v[166:169], v[90:93]
	v_mfma_f32_16x16x32_bf16 v[86:89], v[134:137], v[174:177], v[86:89]
	v_mfma_f32_16x16x32_bf16 v[82:85], v[142:145], v[174:177], v[82:85]
	v_mfma_f32_16x16x32_bf16 v[78:81], v[134:137], v[182:185], v[78:81]
	v_mfma_f32_16x16x32_bf16 v[74:77], v[142:145], v[182:185], v[74:77]
	v_mfma_f32_16x16x32_bf16 v[70:73], v[134:137], v[222:225], v[70:73]
	v_mfma_f32_16x16x32_bf16 v[66:69], v[142:145], v[222:225], v[66:69]
	s_setprio 0
	s_setprio 1
	v_mfma_f32_16x16x32_bf16 v[28:31], v[146:149], v[162:165], v[28:31]
	v_mfma_f32_16x16x32_bf16 v[24:27], v[154:157], v[162:165], v[24:27]
	v_mfma_f32_16x16x32_bf16 v[20:23], v[146:149], v[170:173], v[20:23]
	v_mfma_f32_16x16x32_bf16 v[16:19], v[154:157], v[170:173], v[16:19]
	v_mfma_f32_16x16x32_bf16 v[12:15], v[146:149], v[178:181], v[12:15]
	v_mfma_f32_16x16x32_bf16 v[8:11], v[154:157], v[178:181], v[8:11]
	v_mfma_f32_16x16x32_bf16 v[4:7], v[146:149], v[218:221], v[4:7]
	v_mfma_f32_16x16x32_bf16 v[0:3], v[154:157], v[218:221], v[0:3]
	v_mfma_f32_16x16x32_bf16 v[28:31], v[150:153], v[166:169], v[28:31]
	v_mfma_f32_16x16x32_bf16 v[24:27], v[158:161], v[166:169], v[24:27]
	v_mfma_f32_16x16x32_bf16 v[20:23], v[150:153], v[174:177], v[20:23]
	v_mfma_f32_16x16x32_bf16 v[16:19], v[158:161], v[174:177], v[16:19]
	v_mfma_f32_16x16x32_bf16 v[12:15], v[150:153], v[182:185], v[12:15]
	v_mfma_f32_16x16x32_bf16 v[8:11], v[158:161], v[182:185], v[8:11]
	v_mfma_f32_16x16x32_bf16 v[4:7], v[150:153], v[222:225], v[4:7]
	v_mfma_f32_16x16x32_bf16 v[0:3], v[158:161], v[222:225], v[0:3]
	s_setprio 0
	s_barrier
	s_add_i32 s50, s50, 2
	s_add_u32 s48, s48, 0x100
	s_addc_u32 s49, s49, 0
	s_add_u32 s2, s2, 0x100
	s_addc_u32 s3, s3, 0
	s_cmp_gt_u32 s50, 13
	s_cbranch_scc0 .LBB0_704
	s_and_b64 vcc, exec, s[12:13]
	s_cbranch_vccz .LBB0_707
	s_barrier
